# peer_out LN3 epilogue: gamma/beta preloaded once before the token loop, removing 3 per-token load+store-ack round trips
# speedup vs baseline: 1.0083x; 1.0017x over previous
; DI int otid() { int t = __builtin_amdgcn_workitem_id_x(); asm volatile("" : "+v"(t)); return t; }
; DI void phase_peer_out(const Params& p, char* lds) {
;     ...
;   const int tid = otid(), lane = tid & 63, wave = tid >> 6, hb = lane >> 5, l5 = lane & 31;
;   int* sidx = (int*)lds + wave * 384; float* sw = (float*)(sidx + 128);
;   const u16* H = (const u16*)(ws + OFF_H); const unsigned* TV = (const unsigned*)(ws + OFF_TOPV);
;   const unsigned char* U6 = (const unsigned char*)(ws + OFF_U8) + 24 * l5; const unsigned char* V6 = (const unsigned char*)(ws + OFF_V8) + 24 * l5;
;   const float* USC = (const float*)(ws + OFF_USC); const float* VSC = (const float*)(ws + OFF_VSC);
;   const float* g3 = p.in[23]; const float* b3 = p.in[24];
;   int ci = 0, cj = 0; const bool cval = lane < 50;
;   if (cval) { int rem = lane, i = 0; while (true) { const int cnt = 16 / (i + 1); if (rem < cnt) break; rem -= cnt; ++i; } ci = i; cj = rem; }
;   const int flat = ci * 16 + cj;
;     ...
;     for (int grp = 0; grp < 2; ++grp) {
;       const float dt = sw[grp * 64 + lane] * USC[el[grp]];
;       const float ge = 0.5f * dt * (1.f + erff(dt * 0.7071067811865476f));
;       coefv[grp] = gl[grp] * ge * VSC[el[grp]];
;     }
;     f32x2 o2[16];
; #pragma unroll
;     for (int i = 0; i < 16; ++i) o2[i] = f32x2{0.f, 0.f};
; #pragma unroll
;     for (int kb = 0; kb < 8; ++kb) {
;       v6u qb[8];
; #pragma unroll
;       for (int k = 0; k < 8; ++k) {
;         const int e0 = __builtin_amdgcn_readlane(el[0], kb * 8 + k), e1 = __builtin_amdgcn_readlane(el[1], kb * 8 + k);
;         qb[k] = load6(V6 + (size_t)(hb ? e1 : e0) * 768);
.LBB0_1184:
	s_or_b64 exec, exec, s[2:3]
	v_ashrrev_i32_e32 v1, 6, v222
	v_readlane_b32 s0, v250, 27
	s_nop 1
	v_add_u32_e32 v60, s0, v1
	s_mov_b32 s0, 0x10000
	v_cmp_gt_i32_e64 s[0:1], s0, v60
	s_and_saveexec_b64 s[2:3], s[0:1]
	s_cbranch_execz .LBB0_1211
	s_movk_i32 s0, 0x600
	v_and_b32_e32 v5, 31, v222
	v_mul_lo_u32 v1, v1, s0
	v_readlane_b32 s0, v250, 52
	v_mul_u32_u24_e32 v2, 24, v5
	v_mov_b32_e32 v3, 0
	v_readlane_b32 s1, v250, 53
	v_add_u32_e32 v110, 0, v1
	v_lshl_add_u32 v1, v58, 4, v56
	v_lshl_add_u64 v[62:63], s[0:1], 0, v[2:3]
	v_readlane_b32 s0, v250, 54
	v_readlane_b32 s1, v250, 55
	v_sub_u32_e32 v111, 0xff, v1
	v_and_b32_e32 v1, 64, v223
	v_lshl_add_u64 v[64:65], s[0:1], 0, v[2:3]
	v_lshlrev_b32_e32 v2, 6, v5
	v_lshrrev_b32_e32 v4, 5, v0
	v_lshl_add_u64 v[66:67], s[24:25], 0, v[2:3]
	v_add_u32_e32 v7, 64, v1
	v_cmp_gt_u32_e64 s[0:1], 32, v0
	v_lshl_add_u32 v112, v0, 2, v110
	v_xor_b32_e32 v0, 32, v223
	v_readlane_b32 s16, v250, 30
	v_cmp_lt_i32_e64 s[2:3], v0, v7
	v_readlane_b32 s17, v250, 31
	v_readlane_b32 s18, v250, 32
	v_readlane_b32 s19, v250, 33
	v_cndmask_b32_e64 v0, v223, v0, s[2:3]
	v_lshlrev_b32_e32 v2, 7, v5
	v_readlane_b32 s30, v250, 44
	v_readlane_b32 s31, v250, 45
	v_readlane_b32 s16, v250, 56
	v_lshl_add_u32 v6, v5, 2, v110
	v_lshlrev_b32_e32 v8, 8, v4
	v_lshlrev_b32_e32 v113, 2, v0
	v_lshl_add_u64 v[0:1], s[30:31], 0, v[2:3]
	v_lshlrev_b32_e32 v4, 6, v4
	v_mov_b32_e32 v5, v3
	v_readlane_b32 s17, v250, 57
	v_lshl_add_u64 v[68:69], v[0:1], 0, v[4:5]
	v_readlane_b32 s18, v250, 58
	v_lshl_add_u64 v[0:1], s[16:17], 0, v[2:3]
	v_lshl_add_u64 v[70:71], v[0:1], 0, v[4:5]
	v_xor_b32_e32 v0, 8, v223
	v_cmp_lt_i32_e64 s[2:3], v0, v7
	v_readlane_b32 s19, v250, 59
	v_readlane_b32 s20, v250, 34
	v_cndmask_b32_e64 v0, v223, v0, s[2:3]
	v_lshlrev_b32_e32 v114, 2, v0
	v_xor_b32_e32 v0, 4, v223
	v_cmp_lt_i32_e64 s[2:3], v0, v7
	v_readlane_b32 s21, v250, 35
	v_readlane_b32 s22, v250, 36
	v_cndmask_b32_e64 v0, v223, v0, s[2:3]
	v_lshlrev_b32_e32 v115, 2, v0
	v_xor_b32_e32 v0, 2, v223
	v_cmp_lt_i32_e64 s[2:3], v0, v7
	v_readlane_b32 s23, v250, 37
	v_readlane_b32 s24, v250, 38
	v_cndmask_b32_e64 v0, v223, v0, s[2:3]
	v_lshlrev_b32_e32 v116, 2, v0
	v_xor_b32_e32 v0, 1, v223
	v_cmp_lt_i32_e64 s[2:3], v0, v7
	v_readlane_b32 s25, v250, 39
	v_readlane_b32 s26, v250, 40
	v_cndmask_b32_e64 v0, v223, v0, s[2:3]
	v_lshlrev_b32_e32 v117, 2, v0
	v_and_b32_e32 v0, 16, v222
	v_cmp_eq_u32_e64 s[2:3], 0, v0
	v_xor_b32_e32 v0, 16, v223
	v_cmp_lt_i32_e64 s[4:5], v0, v7
	v_readlane_b32 s27, v250, 41
	v_readlane_b32 s28, v250, 42
	v_cndmask_b32_e64 v0, v223, v0, s[4:5]
	v_lshlrev_b32_e32 v118, 2, v0
	v_and_b32_e32 v0, 8, v222
	v_cmp_eq_u32_e64 s[4:5], 0, v0
	v_and_b32_e32 v0, 4, v222
	v_cmp_eq_u32_e64 s[6:7], 0, v0
	v_and_b32_e32 v0, 2, v222
	v_cmp_eq_u32_e64 s[8:9], 0, v0
	v_and_b32_e32 v0, 1, v222
	v_readlane_b32 s29, v250, 43
	v_cmp_eq_u32_e64 s[10:11], 0, v0
	v_lshl_add_u64 v[0:1], s[18:19], 0, v[2:3]
	v_mov_b32_e32 v59, v3
	v_ashrrev_i32_e32 v57, 31, v56
	v_lshl_add_u64 v[72:73], v[0:1], 0, v[4:5]
	s_mov_b64 s[18:19], 0
	v_mov_b32_e32 v119, 0xff800000
	v_bfrev_b32_e32 v120, 1
	s_movk_i32 s21, 0xff00
	s_movk_i32 s22, 0x3fff
	s_movk_i32 s23, 0x300
	v_add_u32_e32 v121, v6, v8
	s_mov_b32 s24, 0x378e98ab
	s_mov_b32 s25, 0x3b7cd369
	s_mov_b32 s26, 0xbcc618b2
	s_mov_b32 s27, 0x3dda74e4
	s_mov_b32 s28, 0x3f228afd
	s_mov_b32 s29, 0x3e03c728
	s_mov_b32 s30, 0xbfb8aa3b
	s_mov_b32 s31, 0x42ce8ed0
	s_mov_b32 s33, 0xc2b17218
	v_mov_b32_e32 v122, 0x3ba10414
	s_brev_b32 s34, -2
	s_mov_b32 s20, 0x3f9837f0
	v_mov_b32_e32 v123, 0x3727c5ac
	s_mov_b32 s35, 0x800000
	s_mov_b32 s36, 0xffff
	v_mov_b32_e32 v124, 0xb9c68948
	v_mov_b32_e32 v125, 0x7f800000
	global_load_dwordx4 v[184:187], v[68:69], off
	global_load_dwordx4 v[188:191], v[68:69], off offset:16
	global_load_dwordx4 v[192:195], v[68:69], off offset:32
	global_load_dwordx4 v[196:199], v[68:69], off offset:48
	global_load_dwordx4 v[200:203], v[70:71], off
	global_load_dwordx4 v[204:207], v[70:71], off offset:16
	global_load_dwordx4 v[208:211], v[70:71], off offset:32
	global_load_dwordx4 v[212:215], v[70:71], off offset:48
	s_waitcnt vmcnt(0)
	s_branch .LBB0_1187
.LBB0_1186:
	s_or_b64 exec, exec, s[12:13]
	v_lshl_add_u64 v[0:1], v[0:1], 2, s[56:57]
	global_load_dword v12, v[0:1], off
	v_readlane_b32 s12, v108, 0
	v_readlane_b32 s13, v107, 0
	v_readlane_b32 s16, v108, 1
	v_mov_b32_e32 v1, s12
	v_mov_b32_e32 v0, s13
	v_cndmask_b32_e64 v0, v0, v1, s[0:1]
	v_mad_i64_i32 v[0:1], s[12:13], v0, s23, v[64:65]
	v_readlane_b32 s12, v107, 1
	v_add_f32_e32 v5, v128, v5
	global_load_dwordx2 v[132:133], v[0:1], off offset:16
	global_load_dwordx4 v[128:131], v[0:1], off
	v_mov_b32_e32 v0, s12
	v_mov_b32_e32 v1, s16
	v_cndmask_b32_e64 v0, v0, v1, s[0:1]
	v_readlane_b32 s17, v108, 2
	v_readlane_b32 s37, v107, 2
	v_mad_i64_i32 v[0:1], s[12:13], v0, s23, v[64:65]
	global_load_dwordx2 v[138:139], v[0:1], off offset:16
	global_load_dwordx4 v[134:137], v[0:1], off
	v_mov_b32_e32 v0, s37
	v_mov_b32_e32 v1, s17
	v_cndmask_b32_e64 v0, v0, v1, s[0:1]
	v_add_f32_e32 v3, v3, v4
	v_mad_i64_i32 v[0:1], s[12:13], v0, s23, v[64:65]
	v_bfi_b32 v7, s34, v8, v7
	v_mul_f32_e32 v8, 0.5, v10
	v_bfi_b32 v4, s34, v11, v9
	v_readlane_b32 s38, v108, 3
	v_readlane_b32 s39, v107, 3
	v_rcp_f32_e32 v10, v5
	v_rcp_f32_e32 v3, v3
	global_load_dwordx2 v[144:145], v[0:1], off offset:16
	global_load_dwordx4 v[140:143], v[0:1], off
	v_readlane_b32 s40, v108, 4
	v_readlane_b32 s41, v107, 4
	v_readlane_b32 s42, v108, 5
	v_readlane_b32 s43, v107, 5
	v_readlane_b32 s44, v108, 6
	v_readlane_b32 s45, v107, 6
	v_add_f32_e32 v5, 1.0, v7
	v_add_f32_e32 v4, 1.0, v4
	v_mov_b32_e32 v7, s39
	v_mov_b32_e32 v9, s38
	v_mul_f32_e32 v6, 0.5, v6
	v_mov_b32_e32 v11, s41
	v_mov_b32_e32 v13, s40
	v_mov_b32_e32 v14, s43
	v_mov_b32_e32 v15, s42
	v_mov_b32_e32 v16, s45
	v_mov_b32_e32 v17, s44
	v_mul_f32_e32 v19, v8, v4
	v_cndmask_b32_e64 v4, v7, v9, s[0:1]
	v_mul_f32_e32 v18, v6, v5
	v_cndmask_b32_e64 v5, v11, v13, s[0:1]
	v_cndmask_b32_e64 v6, v14, v15, s[0:1]
	v_cndmask_b32_e64 v8, v16, v17, s[0:1]
	v_mad_i64_i32 v[0:1], s[12:13], v4, s23, v[64:65]
	v_mad_i64_i32 v[4:5], s[12:13], v5, s23, v[64:65]
	v_mad_i64_i32 v[6:7], s[12:13], v6, s23, v[64:65]
	v_mad_i64_i32 v[8:9], s[12:13], v8, s23, v[64:65]
	global_load_dwordx4 v[146:149], v[0:1], off
	global_load_dwordx2 v[150:151], v[0:1], off offset:16
	global_load_dwordx4 v[50:53], v[4:5], off
	global_load_dwordx2 v[54:55], v[4:5], off offset:16
	global_load_dwordx4 v[44:47], v[6:7], off
	global_load_dwordx2 v[48:49], v[6:7], off offset:16
	global_load_dwordx4 v[38:41], v[8:9], off
	v_mul_f32_e32 v0, v126, v10
	v_mul_f32_e32 v1, v127, v3
	v_mul_f32_e32 v0, v0, v18
	v_mul_f32_e32 v1, v1, v19
	v_readlane_b32 s12, v108, 7
	v_readlane_b32 s13, v107, 7
	s_waitcnt vmcnt(14)
; DI void phase_peer_out(const Params& p, char* lds) {
;     ...
;       const float dt = sw[grp * 64 + lane] * USC[el[grp]];
;       const float ge = 0.5f * dt * (1.f + erff(dt * 0.7071067811865476f));
;       coefv[grp] = gl[grp] * ge * VSC[el[grp]];
;     }
;     f32x2 o2[16];
; #pragma unroll
;     for (int i = 0; i < 16; ++i) o2[i] = f32x2{0.f, 0.f};
; #pragma unroll
;     for (int kb = 0; kb < 8; ++kb) {
;       v6u qb[8];
; #pragma unroll
;       for (int k = 0; k < 8; ++k) {
;         const int e0 = __builtin_amdgcn_readlane(el[0], kb * 8 + k), e1 = __builtin_amdgcn_readlane(el[1], kb * 8 + k);
;         qb[k] = load6(V6 + (size_t)(hb ? e1 : e0) * 768);
;       }
; #pragma unroll
;       for (int k = 0; k < 8; ++k) {
;         const float c0 = __uint_as_float(__builtin_amdgcn_readlane(__float_as_uint(coefv[0]), kb * 8 + k)), c1 = __uint_as_float(__builtin_amdgcn_readlane(__float_as_uint(coefv[1]), kb * 8 + k));
;         const float cf = hb ? c1 : c0;
;         const f32x2 c2 = {cf, cf};
;         const v32f f = __builtin_amdgcn_cvt_scalef32_pk32_f32_fp6(qb[k], 1.0f);
; #pragma unroll
;         for (int i = 0; i < 16; ++i) o2[i] = f32x2{f[2 * i], f[2 * i + 1]} * c2 + o2[i];
	v_mul_f32_e32 v106, v2, v0
	s_waitcnt vmcnt(13)
	v_mul_f32_e32 v109, v12, v1
	v_mov_b32_e32 v0, s13
	v_mov_b32_e32 v1, s12
	v_cndmask_b32_e64 v0, v0, v1, s[0:1]
	v_mad_i64_i32 v[0:1], s[12:13], v0, s23, v[64:65]
	global_load_dwordx2 v[36:37], v[0:1], off offset:16
	global_load_dwordx2 v[42:43], v[8:9], off offset:16
	global_load_dwordx4 v[32:35], v[0:1], off
	v_readlane_b32 s12, v106, 0
	v_readlane_b32 s13, v109, 0
	s_nop 0
	v_mov_b32_e32 v1, s12
	v_mov_b32_e32 v0, s13
	v_cndmask_b32_e64 v126, v0, v1, s[0:1]
	s_waitcnt vmcnt(14)
	v_cvt_scalef32_pk32_f32_fp6 v[0:31], v[128:133], 1.0
	v_readlane_b32 s12, v106, 1
	v_readlane_b32 s13, v109, 1
	v_pk_fma_f32 v[128:129], v[0:1], v[126:127], 0 op_sel_hi:[1,0,0]
	v_mov_b32_e32 v1, s12
	v_mov_b32_e32 v0, s13
	v_pk_fma_f32 v[130:131], v[2:3], v[126:127], 0 op_sel_hi:[1,0,0]
	v_pk_fma_f32 v[132:133], v[4:5], v[126:127], 0 op_sel_hi:[1,0,0]
	v_pk_fma_f32 v[152:153], v[6:7], v[126:127], 0 op_sel_hi:[1,0,0]
	v_pk_fma_f32 v[154:155], v[8:9], v[126:127], 0 op_sel_hi:[1,0,0]
	v_pk_fma_f32 v[156:157], v[10:11], v[126:127], 0 op_sel_hi:[1,0,0]
	v_pk_fma_f32 v[158:159], v[12:13], v[126:127], 0 op_sel_hi:[1,0,0]
	v_pk_fma_f32 v[160:161], v[14:15], v[126:127], 0 op_sel_hi:[1,0,0]
	v_pk_fma_f32 v[162:163], v[16:17], v[126:127], 0 op_sel_hi:[1,0,0]
	v_pk_fma_f32 v[164:165], v[18:19], v[126:127], 0 op_sel_hi:[1,0,0]
	v_pk_fma_f32 v[166:167], v[20:21], v[126:127], 0 op_sel_hi:[1,0,0]
	v_pk_fma_f32 v[168:169], v[22:23], v[126:127], 0 op_sel_hi:[1,0,0]
	v_pk_fma_f32 v[170:171], v[24:25], v[126:127], 0 op_sel_hi:[1,0,0]
	v_pk_fma_f32 v[172:173], v[26:27], v[126:127], 0 op_sel_hi:[1,0,0]
	v_pk_fma_f32 v[174:175], v[28:29], v[126:127], 0 op_sel_hi:[1,0,0]
	v_pk_fma_f32 v[126:127], v[30:31], v[126:127], 0 op_sel_hi:[1,0,0]
	v_cndmask_b32_e64 v176, v0, v1, s[0:1]
	s_waitcnt vmcnt(12)
	v_cvt_scalef32_pk32_f32_fp6 v[0:31], v[134:139], 1.0
	v_readlane_b32 s12, v106, 2
	v_readlane_b32 s13, v109, 2
	v_pk_fma_f32 v[128:129], v[0:1], v[176:177], v[128:129] op_sel_hi:[1,0,1]
	v_mov_b32_e32 v1, s12
	v_mov_b32_e32 v0, s13
	v_pk_fma_f32 v[130:131], v[2:3], v[176:177], v[130:131] op_sel_hi:[1,0,1]
	v_pk_fma_f32 v[132:133], v[4:5], v[176:177], v[132:133] op_sel_hi:[1,0,1]
	v_pk_fma_f32 v[134:135], v[6:7], v[176:177], v[152:153] op_sel_hi:[1,0,1]
	v_pk_fma_f32 v[136:137], v[8:9], v[176:177], v[154:155] op_sel_hi:[1,0,1]
	v_pk_fma_f32 v[138:139], v[10:11], v[176:177], v[156:157] op_sel_hi:[1,0,1]
	v_pk_fma_f32 v[152:153], v[12:13], v[176:177], v[158:159] op_sel_hi:[1,0,1]
	v_pk_fma_f32 v[154:155], v[14:15], v[176:177], v[160:161] op_sel_hi:[1,0,1]
	v_pk_fma_f32 v[156:157], v[16:17], v[176:177], v[162:163] op_sel_hi:[1,0,1]
	v_pk_fma_f32 v[158:159], v[18:19], v[176:177], v[164:165] op_sel_hi:[1,0,1]
	v_pk_fma_f32 v[160:161], v[20:21], v[176:177], v[166:167] op_sel_hi:[1,0,1]
	v_pk_fma_f32 v[162:163], v[22:23], v[176:177], v[168:169] op_sel_hi:[1,0,1]
	v_pk_fma_f32 v[164:165], v[24:25], v[176:177], v[170:171] op_sel_hi:[1,0,1]
	v_pk_fma_f32 v[166:167], v[26:27], v[176:177], v[172:173] op_sel_hi:[1,0,1]
	v_pk_fma_f32 v[168:169], v[28:29], v[176:177], v[174:175] op_sel_hi:[1,0,1]
	v_pk_fma_f32 v[126:127], v[30:31], v[176:177], v[126:127] op_sel_hi:[1,0,1]
	v_cndmask_b32_e64 v170, v0, v1, s[0:1]
	s_waitcnt vmcnt(10)
	v_cvt_scalef32_pk32_f32_fp6 v[0:31], v[140:145], 1.0
	v_readlane_b32 s12, v106, 3
	v_readlane_b32 s13, v109, 3
	v_pk_fma_f32 v[128:129], v[0:1], v[170:171], v[128:129] op_sel_hi:[1,0,1]
	v_mov_b32_e32 v1, s12
	v_mov_b32_e32 v0, s13
	v_pk_fma_f32 v[130:131], v[2:3], v[170:171], v[130:131] op_sel_hi:[1,0,1]
	v_pk_fma_f32 v[132:133], v[4:5], v[170:171], v[132:133] op_sel_hi:[1,0,1]
	v_pk_fma_f32 v[134:135], v[6:7], v[170:171], v[134:135] op_sel_hi:[1,0,1]
	v_pk_fma_f32 v[136:137], v[8:9], v[170:171], v[136:137] op_sel_hi:[1,0,1]
	v_pk_fma_f32 v[138:139], v[10:11], v[170:171], v[138:139] op_sel_hi:[1,0,1]
	v_pk_fma_f32 v[140:141], v[12:13], v[170:171], v[152:153] op_sel_hi:[1,0,1]
	v_pk_fma_f32 v[142:143], v[14:15], v[170:171], v[154:155] op_sel_hi:[1,0,1]
	v_pk_fma_f32 v[144:145], v[16:17], v[170:171], v[156:157] op_sel_hi:[1,0,1]
	v_pk_fma_f32 v[152:153], v[18:19], v[170:171], v[158:159] op_sel_hi:[1,0,1]
	v_pk_fma_f32 v[154:155], v[20:21], v[170:171], v[160:161] op_sel_hi:[1,0,1]
	v_pk_fma_f32 v[156:157], v[22:23], v[170:171], v[162:163] op_sel_hi:[1,0,1]
	v_pk_fma_f32 v[158:159], v[24:25], v[170:171], v[164:165] op_sel_hi:[1,0,1]
	v_pk_fma_f32 v[160:161], v[26:27], v[170:171], v[166:167] op_sel_hi:[1,0,1]
	v_pk_fma_f32 v[162:163], v[28:29], v[170:171], v[168:169] op_sel_hi:[1,0,1]
	v_pk_fma_f32 v[126:127], v[30:31], v[170:171], v[126:127] op_sel_hi:[1,0,1]
	v_cndmask_b32_e64 v164, v0, v1, s[0:1]
	s_waitcnt vmcnt(8)
	v_cvt_scalef32_pk32_f32_fp6 v[0:31], v[146:151], 1.0
	v_readlane_b32 s12, v106, 4
	v_readlane_b32 s13, v109, 4
	v_pk_fma_f32 v[128:129], v[0:1], v[164:165], v[128:129] op_sel_hi:[1,0,1]
	v_mov_b32_e32 v1, s12
	v_mov_b32_e32 v0, s13
	v_pk_fma_f32 v[130:131], v[2:3], v[164:165], v[130:131] op_sel_hi:[1,0,1]
	v_pk_fma_f32 v[132:133], v[4:5], v[164:165], v[132:133] op_sel_hi:[1,0,1]
	v_pk_fma_f32 v[134:135], v[6:7], v[164:165], v[134:135] op_sel_hi:[1,0,1]
	v_pk_fma_f32 v[136:137], v[8:9], v[164:165], v[136:137] op_sel_hi:[1,0,1]
	v_pk_fma_f32 v[138:139], v[10:11], v[164:165], v[138:139] op_sel_hi:[1,0,1]
	v_pk_fma_f32 v[140:141], v[12:13], v[164:165], v[140:141] op_sel_hi:[1,0,1]
	v_pk_fma_f32 v[142:143], v[14:15], v[164:165], v[142:143] op_sel_hi:[1,0,1]
	v_pk_fma_f32 v[144:145], v[16:17], v[164:165], v[144:145] op_sel_hi:[1,0,1]
	v_pk_fma_f32 v[146:147], v[18:19], v[164:165], v[152:153] op_sel_hi:[1,0,1]
	v_pk_fma_f32 v[148:149], v[20:21], v[164:165], v[154:155] op_sel_hi:[1,0,1]
	v_pk_fma_f32 v[150:151], v[22:23], v[164:165], v[156:157] op_sel_hi:[1,0,1]
	v_pk_fma_f32 v[152:153], v[24:25], v[164:165], v[158:159] op_sel_hi:[1,0,1]
	v_pk_fma_f32 v[154:155], v[26:27], v[164:165], v[160:161] op_sel_hi:[1,0,1]
	v_pk_fma_f32 v[156:157], v[28:29], v[164:165], v[162:163] op_sel_hi:[1,0,1]
	v_pk_fma_f32 v[126:127], v[30:31], v[164:165], v[126:127] op_sel_hi:[1,0,1]
	v_cndmask_b32_e64 v158, v0, v1, s[0:1]
	s_waitcnt vmcnt(6)
; DI void phase_peer_out(const Params& p, char* lds) {
;     ...
;       for (int k = 0; k < 8; ++k) {
;         const int e0 = __builtin_amdgcn_readlane(el[0], kb * 8 + k), e1 = __builtin_amdgcn_readlane(el[1], kb * 8 + k);
;         qb[k] = load6(V6 + (size_t)(hb ? e1 : e0) * 768);
;       }
; #pragma unroll
;       for (int k = 0; k < 8; ++k) {
;         const float c0 = __uint_as_float(__builtin_amdgcn_readlane(__float_as_uint(coefv[0]), kb * 8 + k)), c1 = __uint_as_float(__builtin_amdgcn_readlane(__float_as_uint(coefv[1]), kb * 8 + k));
;         const float cf = hb ? c1 : c0;
;         const f32x2 c2 = {cf, cf};
;         const v32f f = __builtin_amdgcn_cvt_scalef32_pk32_f32_fp6(qb[k], 1.0f);
; #pragma unroll
;         for (int i = 0; i < 16; ++i) o2[i] = f32x2{f[2 * i], f[2 * i + 1]} * c2 + o2[i];
	v_cvt_scalef32_pk32_f32_fp6 v[0:31], v[50:55], 1.0
	v_readlane_b32 s12, v106, 5
	v_readlane_b32 s13, v109, 5
	v_pk_fma_f32 v[50:51], v[0:1], v[158:159], v[128:129] op_sel_hi:[1,0,1]
	v_mov_b32_e32 v1, s12
	v_mov_b32_e32 v0, s13
	v_pk_fma_f32 v[52:53], v[2:3], v[158:159], v[130:131] op_sel_hi:[1,0,1]
	v_pk_fma_f32 v[54:55], v[4:5], v[158:159], v[132:133] op_sel_hi:[1,0,1]
	v_pk_fma_f32 v[128:129], v[6:7], v[158:159], v[134:135] op_sel_hi:[1,0,1]
	v_pk_fma_f32 v[130:131], v[8:9], v[158:159], v[136:137] op_sel_hi:[1,0,1]
	v_pk_fma_f32 v[132:133], v[10:11], v[158:159], v[138:139] op_sel_hi:[1,0,1]
	v_pk_fma_f32 v[134:135], v[12:13], v[158:159], v[140:141] op_sel_hi:[1,0,1]
	v_pk_fma_f32 v[136:137], v[14:15], v[158:159], v[142:143] op_sel_hi:[1,0,1]
	v_pk_fma_f32 v[138:139], v[16:17], v[158:159], v[144:145] op_sel_hi:[1,0,1]
	v_pk_fma_f32 v[140:141], v[18:19], v[158:159], v[146:147] op_sel_hi:[1,0,1]
	v_pk_fma_f32 v[142:143], v[20:21], v[158:159], v[148:149] op_sel_hi:[1,0,1]
	v_pk_fma_f32 v[144:145], v[22:23], v[158:159], v[150:151] op_sel_hi:[1,0,1]
	v_pk_fma_f32 v[146:147], v[24:25], v[158:159], v[152:153] op_sel_hi:[1,0,1]
	v_pk_fma_f32 v[148:149], v[26:27], v[158:159], v[154:155] op_sel_hi:[1,0,1]
	v_pk_fma_f32 v[150:151], v[28:29], v[158:159], v[156:157] op_sel_hi:[1,0,1]
	v_pk_fma_f32 v[126:127], v[30:31], v[158:159], v[126:127] op_sel_hi:[1,0,1]
	v_cndmask_b32_e64 v152, v0, v1, s[0:1]
	s_waitcnt vmcnt(4)
	v_cvt_scalef32_pk32_f32_fp6 v[0:31], v[44:49], 1.0
	v_readlane_b32 s12, v106, 6
	v_readlane_b32 s13, v109, 6
	v_pk_fma_f32 v[44:45], v[0:1], v[152:153], v[50:51] op_sel_hi:[1,0,1]
	v_mov_b32_e32 v1, s12
	v_mov_b32_e32 v0, s13
	v_pk_fma_f32 v[46:47], v[2:3], v[152:153], v[52:53] op_sel_hi:[1,0,1]
	v_pk_fma_f32 v[48:49], v[4:5], v[152:153], v[54:55] op_sel_hi:[1,0,1]
	v_pk_fma_f32 v[50:51], v[6:7], v[152:153], v[128:129] op_sel_hi:[1,0,1]
	v_pk_fma_f32 v[52:53], v[8:9], v[152:153], v[130:131] op_sel_hi:[1,0,1]
	v_pk_fma_f32 v[54:55], v[10:11], v[152:153], v[132:133] op_sel_hi:[1,0,1]
	v_pk_fma_f32 v[128:129], v[12:13], v[152:153], v[134:135] op_sel_hi:[1,0,1]
	v_pk_fma_f32 v[130:131], v[14:15], v[152:153], v[136:137] op_sel_hi:[1,0,1]
	v_pk_fma_f32 v[132:133], v[16:17], v[152:153], v[138:139] op_sel_hi:[1,0,1]
	v_pk_fma_f32 v[134:135], v[18:19], v[152:153], v[140:141] op_sel_hi:[1,0,1]
	v_pk_fma_f32 v[136:137], v[20:21], v[152:153], v[142:143] op_sel_hi:[1,0,1]
	v_pk_fma_f32 v[138:139], v[22:23], v[152:153], v[144:145] op_sel_hi:[1,0,1]
	v_pk_fma_f32 v[140:141], v[24:25], v[152:153], v[146:147] op_sel_hi:[1,0,1]
	v_pk_fma_f32 v[142:143], v[26:27], v[152:153], v[148:149] op_sel_hi:[1,0,1]
	v_pk_fma_f32 v[144:145], v[28:29], v[152:153], v[150:151] op_sel_hi:[1,0,1]
	v_pk_fma_f32 v[126:127], v[30:31], v[152:153], v[126:127] op_sel_hi:[1,0,1]
	v_cndmask_b32_e64 v146, v0, v1, s[0:1]
	s_waitcnt vmcnt(1)
	v_cvt_scalef32_pk32_f32_fp6 v[0:31], v[38:43], 1.0
	v_readlane_b32 s12, v106, 7
	v_readlane_b32 s13, v109, 7
	v_pk_fma_f32 v[38:39], v[0:1], v[146:147], v[44:45] op_sel_hi:[1,0,1]
	v_mov_b32_e32 v1, s12
	v_mov_b32_e32 v0, s13
	v_readlane_b32 s12, v108, 8
	v_readlane_b32 s13, v107, 8
	v_pk_fma_f32 v[40:41], v[2:3], v[146:147], v[46:47] op_sel_hi:[1,0,1]
	v_pk_fma_f32 v[42:43], v[4:5], v[146:147], v[48:49] op_sel_hi:[1,0,1]
	v_pk_fma_f32 v[44:45], v[6:7], v[146:147], v[50:51] op_sel_hi:[1,0,1]
	v_pk_fma_f32 v[46:47], v[8:9], v[146:147], v[52:53] op_sel_hi:[1,0,1]
	v_pk_fma_f32 v[48:49], v[10:11], v[146:147], v[54:55] op_sel_hi:[1,0,1]
	v_pk_fma_f32 v[50:51], v[12:13], v[146:147], v[128:129] op_sel_hi:[1,0,1]
	v_pk_fma_f32 v[52:53], v[14:15], v[146:147], v[130:131] op_sel_hi:[1,0,1]
	v_pk_fma_f32 v[54:55], v[16:17], v[146:147], v[132:133] op_sel_hi:[1,0,1]
	v_pk_fma_f32 v[132:133], v[18:19], v[146:147], v[134:135] op_sel_hi:[1,0,1]
	v_pk_fma_f32 v[134:135], v[20:21], v[146:147], v[136:137] op_sel_hi:[1,0,1]
	v_pk_fma_f32 v[136:137], v[22:23], v[146:147], v[138:139] op_sel_hi:[1,0,1]
	v_pk_fma_f32 v[138:139], v[24:25], v[146:147], v[140:141] op_sel_hi:[1,0,1]
	v_pk_fma_f32 v[140:141], v[26:27], v[146:147], v[142:143] op_sel_hi:[1,0,1]
	v_pk_fma_f32 v[142:143], v[28:29], v[146:147], v[144:145] op_sel_hi:[1,0,1]
	v_pk_fma_f32 v[144:145], v[30:31], v[146:147], v[126:127] op_sel_hi:[1,0,1]
	v_cndmask_b32_e64 v146, v0, v1, s[0:1]
	v_mov_b32_e32 v0, s13
	v_mov_b32_e32 v1, s12
	v_cndmask_b32_e64 v0, v0, v1, s[0:1]
	v_mad_i64_i32 v[130:131], s[12:13], v0, s23, v[64:65]
	s_waitcnt vmcnt(0)
; DI void phase_peer_out(const Params& p, char* lds) {
;     ...
;     for (int kb = 0; kb < 8; ++kb) {
;       v6u qb[8];
; #pragma unroll
;       for (int k = 0; k < 8; ++k) {
;         const int e0 = __builtin_amdgcn_readlane(el[0], kb * 8 + k), e1 = __builtin_amdgcn_readlane(el[1], kb * 8 + k);
;         qb[k] = load6(V6 + (size_t)(hb ? e1 : e0) * 768);
;       }
; #pragma unroll
;       for (int k = 0; k < 8; ++k) {
;         const float c0 = __uint_as_float(__builtin_amdgcn_readlane(__float_as_uint(coefv[0]), kb * 8 + k)), c1 = __uint_as_float(__builtin_amdgcn_readlane(__float_as_uint(coefv[1]), kb * 8 + k));
;         const float cf = hb ? c1 : c0;
;         const f32x2 c2 = {cf, cf};
;         const v32f f = __builtin_amdgcn_cvt_scalef32_pk32_f32_fp6(qb[k], 1.0f);
; #pragma unroll
;         for (int i = 0; i < 16; ++i) o2[i] = f32x2{f[2 * i], f[2 * i + 1]} * c2 + o2[i];
	v_cvt_scalef32_pk32_f32_fp6 v[0:31], v[32:37], 1.0
	v_readlane_b32 s12, v108, 9
	v_readlane_b32 s13, v107, 9
	v_pk_fma_f32 v[150:151], v[0:1], v[146:147], v[38:39] op_sel_hi:[1,0,1]
	v_mov_b32_e32 v1, s12
	v_mov_b32_e32 v0, s13
	v_cndmask_b32_e64 v0, v0, v1, s[0:1]
	v_mad_i64_i32 v[0:1], s[12:13], v0, s23, v[64:65]
	v_readlane_b32 s12, v108, 10
	v_readlane_b32 s13, v107, 10
	global_load_dwordx4 v[126:129], v[130:131], off
	v_pk_fma_f32 v[168:169], v[18:19], v[146:147], v[132:133] op_sel_hi:[1,0,1]
	global_load_dwordx2 v[130:131], v[130:131], off offset:16
	v_pk_fma_f32 v[170:171], v[20:21], v[146:147], v[134:135] op_sel_hi:[1,0,1]
	v_pk_fma_f32 v[172:173], v[22:23], v[146:147], v[136:137] op_sel_hi:[1,0,1]
	global_load_dwordx2 v[136:137], v[0:1], off offset:16
	global_load_dwordx4 v[132:135], v[0:1], off
	v_mov_b32_e32 v0, s13
	v_mov_b32_e32 v1, s12
	v_cndmask_b32_e64 v0, v0, v1, s[0:1]
	v_mad_i64_i32 v[0:1], s[12:13], v0, s23, v[64:65]
	v_readlane_b32 s12, v108, 11
	v_readlane_b32 s13, v107, 11
	v_pk_fma_f32 v[152:153], v[2:3], v[146:147], v[40:41] op_sel_hi:[1,0,1]
	v_mov_b32_e32 v3, s12
	v_mov_b32_e32 v2, s13
	v_cndmask_b32_e64 v2, v2, v3, s[0:1]
	v_mad_i64_i32 v[2:3], s[12:13], v2, s23, v[64:65]
	v_readlane_b32 s12, v108, 12
	v_readlane_b32 s13, v107, 12
	v_pk_fma_f32 v[154:155], v[4:5], v[146:147], v[42:43] op_sel_hi:[1,0,1]
	v_pk_fma_f32 v[156:157], v[6:7], v[146:147], v[44:45] op_sel_hi:[1,0,1]
	v_pk_fma_f32 v[158:159], v[8:9], v[146:147], v[46:47] op_sel_hi:[1,0,1]
	v_pk_fma_f32 v[160:161], v[10:11], v[146:147], v[48:49] op_sel_hi:[1,0,1]
	v_pk_fma_f32 v[162:163], v[12:13], v[146:147], v[50:51] op_sel_hi:[1,0,1]
	v_pk_fma_f32 v[164:165], v[14:15], v[146:147], v[52:53] op_sel_hi:[1,0,1]
	v_pk_fma_f32 v[166:167], v[16:17], v[146:147], v[54:55] op_sel_hi:[1,0,1]
	v_pk_fma_f32 v[174:175], v[24:25], v[146:147], v[138:139] op_sel_hi:[1,0,1]
	v_pk_fma_f32 v[176:177], v[26:27], v[146:147], v[140:141] op_sel_hi:[1,0,1]
	v_pk_fma_f32 v[178:179], v[28:29], v[146:147], v[142:143] op_sel_hi:[1,0,1]
	v_pk_fma_f32 v[180:181], v[30:31], v[146:147], v[144:145] op_sel_hi:[1,0,1]
	global_load_dwordx4 v[138:141], v[0:1], off
	global_load_dwordx2 v[142:143], v[0:1], off offset:16
	global_load_dwordx4 v[144:147], v[2:3], off
	v_mov_b32_e32 v0, s13
	v_mov_b32_e32 v1, s12
	v_cndmask_b32_e64 v0, v0, v1, s[0:1]
	v_mad_i64_i32 v[0:1], s[12:13], v0, s23, v[64:65]
	v_readlane_b32 s12, v108, 13
	v_readlane_b32 s13, v107, 13
	global_load_dwordx2 v[148:149], v[2:3], off offset:16
	global_load_dwordx4 v[50:53], v[0:1], off
	v_mov_b32_e32 v2, s13
	v_mov_b32_e32 v3, s12
	v_cndmask_b32_e64 v2, v2, v3, s[0:1]
	v_mad_i64_i32 v[2:3], s[12:13], v2, s23, v[64:65]
	v_readlane_b32 s12, v108, 14
	v_readlane_b32 s13, v107, 14
	global_load_dwordx2 v[54:55], v[0:1], off offset:16
	global_load_dwordx4 v[44:47], v[2:3], off
	v_mov_b32_e32 v0, s13
	v_mov_b32_e32 v1, s12
	v_cndmask_b32_e64 v0, v0, v1, s[0:1]
	v_mad_i64_i32 v[0:1], s[12:13], v0, s23, v[64:65]
	v_readlane_b32 s12, v108, 15
	v_readlane_b32 s13, v107, 15
	global_load_dwordx2 v[48:49], v[2:3], off offset:16
	global_load_dwordx4 v[38:41], v[0:1], off
	v_mov_b32_e32 v2, s13
	v_mov_b32_e32 v3, s12
	v_cndmask_b32_e64 v2, v2, v3, s[0:1]
	v_mad_i64_i32 v[2:3], s[12:13], v2, s23, v[64:65]
	global_load_dwordx2 v[36:37], v[2:3], off offset:16
	global_load_dwordx2 v[42:43], v[0:1], off offset:16
	global_load_dwordx4 v[32:35], v[2:3], off
	v_readlane_b32 s12, v106, 8
	v_readlane_b32 s13, v109, 8
	s_nop 0
	v_mov_b32_e32 v1, s12
	v_mov_b32_e32 v0, s13
	v_cndmask_b32_e64 v182, v0, v1, s[0:1]
	v_readlane_b32 s12, v106, 9
	v_readlane_b32 s13, v109, 9
	s_waitcnt vmcnt(14)
	v_cvt_scalef32_pk32_f32_fp6 v[0:31], v[126:131], 1.0
	v_pk_fma_f32 v[126:127], v[0:1], v[182:183], v[150:151] op_sel_hi:[1,0,1]
	v_mov_b32_e32 v0, s13
	v_mov_b32_e32 v1, s12
	v_pk_fma_f32 v[128:129], v[2:3], v[182:183], v[152:153] op_sel_hi:[1,0,1]
	v_pk_fma_f32 v[130:131], v[4:5], v[182:183], v[154:155] op_sel_hi:[1,0,1]
	v_pk_fma_f32 v[150:151], v[6:7], v[182:183], v[156:157] op_sel_hi:[1,0,1]
	v_pk_fma_f32 v[152:153], v[8:9], v[182:183], v[158:159] op_sel_hi:[1,0,1]
	v_pk_fma_f32 v[154:155], v[10:11], v[182:183], v[160:161] op_sel_hi:[1,0,1]
	v_pk_fma_f32 v[156:157], v[12:13], v[182:183], v[162:163] op_sel_hi:[1,0,1]
	v_pk_fma_f32 v[158:159], v[14:15], v[182:183], v[164:165] op_sel_hi:[1,0,1]
	v_pk_fma_f32 v[160:161], v[16:17], v[182:183], v[166:167] op_sel_hi:[1,0,1]
	v_pk_fma_f32 v[162:163], v[18:19], v[182:183], v[168:169] op_sel_hi:[1,0,1]
	v_pk_fma_f32 v[164:165], v[20:21], v[182:183], v[170:171] op_sel_hi:[1,0,1]
	v_pk_fma_f32 v[166:167], v[22:23], v[182:183], v[172:173] op_sel_hi:[1,0,1]
	v_pk_fma_f32 v[168:169], v[24:25], v[182:183], v[174:175] op_sel_hi:[1,0,1]
	v_pk_fma_f32 v[170:171], v[26:27], v[182:183], v[176:177] op_sel_hi:[1,0,1]
	v_pk_fma_f32 v[172:173], v[28:29], v[182:183], v[178:179] op_sel_hi:[1,0,1]
	v_pk_fma_f32 v[174:175], v[30:31], v[182:183], v[180:181] op_sel_hi:[1,0,1]
	v_cndmask_b32_e64 v176, v0, v1, s[0:1]
	s_waitcnt vmcnt(12)
; DI void phase_peer_out(const Params& p, char* lds) {
;     ...
;       for (int k = 0; k < 8; ++k) {
;         const int e0 = __builtin_amdgcn_readlane(el[0], kb * 8 + k), e1 = __builtin_amdgcn_readlane(el[1], kb * 8 + k);
;         qb[k] = load6(V6 + (size_t)(hb ? e1 : e0) * 768);
;       }
; #pragma unroll
;       for (int k = 0; k < 8; ++k) {
;         const float c0 = __uint_as_float(__builtin_amdgcn_readlane(__float_as_uint(coefv[0]), kb * 8 + k)), c1 = __uint_as_float(__builtin_amdgcn_readlane(__float_as_uint(coefv[1]), kb * 8 + k));
;         const float cf = hb ? c1 : c0;
;         const f32x2 c2 = {cf, cf};
;         const v32f f = __builtin_amdgcn_cvt_scalef32_pk32_f32_fp6(qb[k], 1.0f);
; #pragma unroll
;         for (int i = 0; i < 16; ++i) o2[i] = f32x2{f[2 * i], f[2 * i + 1]} * c2 + o2[i];
	v_cvt_scalef32_pk32_f32_fp6 v[0:31], v[132:137], 1.0
	v_readlane_b32 s12, v106, 10
	v_readlane_b32 s13, v109, 10
	v_pk_fma_f32 v[126:127], v[0:1], v[176:177], v[126:127] op_sel_hi:[1,0,1]
	v_mov_b32_e32 v1, s12
	v_mov_b32_e32 v0, s13
	v_pk_fma_f32 v[128:129], v[2:3], v[176:177], v[128:129] op_sel_hi:[1,0,1]
	v_pk_fma_f32 v[130:131], v[4:5], v[176:177], v[130:131] op_sel_hi:[1,0,1]
	v_pk_fma_f32 v[132:133], v[6:7], v[176:177], v[150:151] op_sel_hi:[1,0,1]
	v_pk_fma_f32 v[134:135], v[8:9], v[176:177], v[152:153] op_sel_hi:[1,0,1]
	v_pk_fma_f32 v[136:137], v[10:11], v[176:177], v[154:155] op_sel_hi:[1,0,1]
	v_pk_fma_f32 v[150:151], v[12:13], v[176:177], v[156:157] op_sel_hi:[1,0,1]
	v_pk_fma_f32 v[152:153], v[14:15], v[176:177], v[158:159] op_sel_hi:[1,0,1]
	v_pk_fma_f32 v[154:155], v[16:17], v[176:177], v[160:161] op_sel_hi:[1,0,1]
	v_pk_fma_f32 v[156:157], v[18:19], v[176:177], v[162:163] op_sel_hi:[1,0,1]
	v_pk_fma_f32 v[158:159], v[20:21], v[176:177], v[164:165] op_sel_hi:[1,0,1]
	v_pk_fma_f32 v[160:161], v[22:23], v[176:177], v[166:167] op_sel_hi:[1,0,1]
	v_pk_fma_f32 v[162:163], v[24:25], v[176:177], v[168:169] op_sel_hi:[1,0,1]
	v_pk_fma_f32 v[164:165], v[26:27], v[176:177], v[170:171] op_sel_hi:[1,0,1]
	v_pk_fma_f32 v[166:167], v[28:29], v[176:177], v[172:173] op_sel_hi:[1,0,1]
	v_pk_fma_f32 v[168:169], v[30:31], v[176:177], v[174:175] op_sel_hi:[1,0,1]
	v_cndmask_b32_e64 v170, v0, v1, s[0:1]
	s_waitcnt vmcnt(10)
	v_cvt_scalef32_pk32_f32_fp6 v[0:31], v[138:143], 1.0
	v_readlane_b32 s12, v106, 11
	v_readlane_b32 s13, v109, 11
	v_pk_fma_f32 v[126:127], v[0:1], v[170:171], v[126:127] op_sel_hi:[1,0,1]
	v_mov_b32_e32 v1, s12
	v_mov_b32_e32 v0, s13
	v_pk_fma_f32 v[128:129], v[2:3], v[170:171], v[128:129] op_sel_hi:[1,0,1]
	v_pk_fma_f32 v[130:131], v[4:5], v[170:171], v[130:131] op_sel_hi:[1,0,1]
	v_pk_fma_f32 v[132:133], v[6:7], v[170:171], v[132:133] op_sel_hi:[1,0,1]
	v_pk_fma_f32 v[134:135], v[8:9], v[170:171], v[134:135] op_sel_hi:[1,0,1]
	v_pk_fma_f32 v[136:137], v[10:11], v[170:171], v[136:137] op_sel_hi:[1,0,1]
	v_pk_fma_f32 v[138:139], v[12:13], v[170:171], v[150:151] op_sel_hi:[1,0,1]
	v_pk_fma_f32 v[140:141], v[14:15], v[170:171], v[152:153] op_sel_hi:[1,0,1]
	v_pk_fma_f32 v[142:143], v[16:17], v[170:171], v[154:155] op_sel_hi:[1,0,1]
	v_pk_fma_f32 v[150:151], v[18:19], v[170:171], v[156:157] op_sel_hi:[1,0,1]
	v_pk_fma_f32 v[152:153], v[20:21], v[170:171], v[158:159] op_sel_hi:[1,0,1]
	v_pk_fma_f32 v[154:155], v[22:23], v[170:171], v[160:161] op_sel_hi:[1,0,1]
	v_pk_fma_f32 v[156:157], v[24:25], v[170:171], v[162:163] op_sel_hi:[1,0,1]
	v_pk_fma_f32 v[158:159], v[26:27], v[170:171], v[164:165] op_sel_hi:[1,0,1]
	v_pk_fma_f32 v[160:161], v[28:29], v[170:171], v[166:167] op_sel_hi:[1,0,1]
	v_pk_fma_f32 v[162:163], v[30:31], v[170:171], v[168:169] op_sel_hi:[1,0,1]
	v_cndmask_b32_e64 v164, v0, v1, s[0:1]
	s_waitcnt vmcnt(8)
	v_cvt_scalef32_pk32_f32_fp6 v[0:31], v[144:149], 1.0
	v_readlane_b32 s12, v106, 12
	v_readlane_b32 s13, v109, 12
	v_pk_fma_f32 v[126:127], v[0:1], v[164:165], v[126:127] op_sel_hi:[1,0,1]
	v_mov_b32_e32 v1, s12
	v_mov_b32_e32 v0, s13
	v_pk_fma_f32 v[128:129], v[2:3], v[164:165], v[128:129] op_sel_hi:[1,0,1]
	v_pk_fma_f32 v[130:131], v[4:5], v[164:165], v[130:131] op_sel_hi:[1,0,1]
	v_pk_fma_f32 v[132:133], v[6:7], v[164:165], v[132:133] op_sel_hi:[1,0,1]
	v_pk_fma_f32 v[134:135], v[8:9], v[164:165], v[134:135] op_sel_hi:[1,0,1]
	v_pk_fma_f32 v[136:137], v[10:11], v[164:165], v[136:137] op_sel_hi:[1,0,1]
	v_pk_fma_f32 v[138:139], v[12:13], v[164:165], v[138:139] op_sel_hi:[1,0,1]
	v_pk_fma_f32 v[140:141], v[14:15], v[164:165], v[140:141] op_sel_hi:[1,0,1]
	v_pk_fma_f32 v[142:143], v[16:17], v[164:165], v[142:143] op_sel_hi:[1,0,1]
	v_pk_fma_f32 v[144:145], v[18:19], v[164:165], v[150:151] op_sel_hi:[1,0,1]
	v_pk_fma_f32 v[146:147], v[20:21], v[164:165], v[152:153] op_sel_hi:[1,0,1]
	v_pk_fma_f32 v[148:149], v[22:23], v[164:165], v[154:155] op_sel_hi:[1,0,1]
	v_pk_fma_f32 v[150:151], v[24:25], v[164:165], v[156:157] op_sel_hi:[1,0,1]
	v_pk_fma_f32 v[152:153], v[26:27], v[164:165], v[158:159] op_sel_hi:[1,0,1]
	v_pk_fma_f32 v[154:155], v[28:29], v[164:165], v[160:161] op_sel_hi:[1,0,1]
	v_pk_fma_f32 v[156:157], v[30:31], v[164:165], v[162:163] op_sel_hi:[1,0,1]
	v_cndmask_b32_e64 v158, v0, v1, s[0:1]
	s_waitcnt vmcnt(6)
	v_cvt_scalef32_pk32_f32_fp6 v[0:31], v[50:55], 1.0
	v_readlane_b32 s12, v106, 13
	v_readlane_b32 s13, v109, 13
	v_pk_fma_f32 v[50:51], v[0:1], v[158:159], v[126:127] op_sel_hi:[1,0,1]
	v_mov_b32_e32 v1, s12
	v_mov_b32_e32 v0, s13
	v_pk_fma_f32 v[52:53], v[2:3], v[158:159], v[128:129] op_sel_hi:[1,0,1]
	v_pk_fma_f32 v[54:55], v[4:5], v[158:159], v[130:131] op_sel_hi:[1,0,1]
	v_pk_fma_f32 v[126:127], v[6:7], v[158:159], v[132:133] op_sel_hi:[1,0,1]
	v_pk_fma_f32 v[128:129], v[8:9], v[158:159], v[134:135] op_sel_hi:[1,0,1]
	v_pk_fma_f32 v[130:131], v[10:11], v[158:159], v[136:137] op_sel_hi:[1,0,1]
	v_pk_fma_f32 v[132:133], v[12:13], v[158:159], v[138:139] op_sel_hi:[1,0,1]
	v_pk_fma_f32 v[134:135], v[14:15], v[158:159], v[140:141] op_sel_hi:[1,0,1]
	v_pk_fma_f32 v[136:137], v[16:17], v[158:159], v[142:143] op_sel_hi:[1,0,1]
	v_pk_fma_f32 v[138:139], v[18:19], v[158:159], v[144:145] op_sel_hi:[1,0,1]
	v_pk_fma_f32 v[140:141], v[20:21], v[158:159], v[146:147] op_sel_hi:[1,0,1]
	v_pk_fma_f32 v[142:143], v[22:23], v[158:159], v[148:149] op_sel_hi:[1,0,1]
	v_pk_fma_f32 v[144:145], v[24:25], v[158:159], v[150:151] op_sel_hi:[1,0,1]
	v_pk_fma_f32 v[146:147], v[26:27], v[158:159], v[152:153] op_sel_hi:[1,0,1]
	v_pk_fma_f32 v[148:149], v[28:29], v[158:159], v[154:155] op_sel_hi:[1,0,1]
	v_pk_fma_f32 v[150:151], v[30:31], v[158:159], v[156:157] op_sel_hi:[1,0,1]
	v_cndmask_b32_e64 v152, v0, v1, s[0:1]
	s_waitcnt vmcnt(4)
; DI void phase_peer_out(const Params& p, char* lds) {
;     ...
;     for (int kb = 0; kb < 8; ++kb) {
;       v6u qb[8];
; #pragma unroll
;       for (int k = 0; k < 8; ++k) {
;         const int e0 = __builtin_amdgcn_readlane(el[0], kb * 8 + k), e1 = __builtin_amdgcn_readlane(el[1], kb * 8 + k);
;         qb[k] = load6(V6 + (size_t)(hb ? e1 : e0) * 768);
;       }
; #pragma unroll
;       for (int k = 0; k < 8; ++k) {
;         const float c0 = __uint_as_float(__builtin_amdgcn_readlane(__float_as_uint(coefv[0]), kb * 8 + k)), c1 = __uint_as_float(__builtin_amdgcn_readlane(__float_as_uint(coefv[1]), kb * 8 + k));
;         const float cf = hb ? c1 : c0;
;         const f32x2 c2 = {cf, cf};
;         const v32f f = __builtin_amdgcn_cvt_scalef32_pk32_f32_fp6(qb[k], 1.0f);
; #pragma unroll
;         for (int i = 0; i < 16; ++i) o2[i] = f32x2{f[2 * i], f[2 * i + 1]} * c2 + o2[i];
	v_cvt_scalef32_pk32_f32_fp6 v[0:31], v[44:49], 1.0
	v_readlane_b32 s12, v106, 14
	v_readlane_b32 s13, v109, 14
	v_pk_fma_f32 v[44:45], v[0:1], v[152:153], v[50:51] op_sel_hi:[1,0,1]
	v_mov_b32_e32 v1, s12
	v_mov_b32_e32 v0, s13
	v_pk_fma_f32 v[46:47], v[2:3], v[152:153], v[52:53] op_sel_hi:[1,0,1]
	v_pk_fma_f32 v[48:49], v[4:5], v[152:153], v[54:55] op_sel_hi:[1,0,1]
	v_pk_fma_f32 v[50:51], v[6:7], v[152:153], v[126:127] op_sel_hi:[1,0,1]
	v_pk_fma_f32 v[52:53], v[8:9], v[152:153], v[128:129] op_sel_hi:[1,0,1]
	v_pk_fma_f32 v[54:55], v[10:11], v[152:153], v[130:131] op_sel_hi:[1,0,1]
	v_pk_fma_f32 v[126:127], v[12:13], v[152:153], v[132:133] op_sel_hi:[1,0,1]
	v_pk_fma_f32 v[128:129], v[14:15], v[152:153], v[134:135] op_sel_hi:[1,0,1]
	v_pk_fma_f32 v[130:131], v[16:17], v[152:153], v[136:137] op_sel_hi:[1,0,1]
	v_pk_fma_f32 v[132:133], v[18:19], v[152:153], v[138:139] op_sel_hi:[1,0,1]
	v_pk_fma_f32 v[134:135], v[20:21], v[152:153], v[140:141] op_sel_hi:[1,0,1]
	v_pk_fma_f32 v[136:137], v[22:23], v[152:153], v[142:143] op_sel_hi:[1,0,1]
	v_pk_fma_f32 v[138:139], v[24:25], v[152:153], v[144:145] op_sel_hi:[1,0,1]
	v_pk_fma_f32 v[140:141], v[26:27], v[152:153], v[146:147] op_sel_hi:[1,0,1]
	v_pk_fma_f32 v[142:143], v[28:29], v[152:153], v[148:149] op_sel_hi:[1,0,1]
	v_pk_fma_f32 v[144:145], v[30:31], v[152:153], v[150:151] op_sel_hi:[1,0,1]
	v_cndmask_b32_e64 v146, v0, v1, s[0:1]
	s_waitcnt vmcnt(1)
	v_cvt_scalef32_pk32_f32_fp6 v[0:31], v[38:43], 1.0
	v_readlane_b32 s12, v106, 15
	v_readlane_b32 s13, v109, 15
	v_pk_fma_f32 v[38:39], v[0:1], v[146:147], v[44:45] op_sel_hi:[1,0,1]
	v_mov_b32_e32 v1, s12
	v_mov_b32_e32 v0, s13
	v_readlane_b32 s12, v108, 16
	v_readlane_b32 s13, v107, 16
	v_pk_fma_f32 v[40:41], v[2:3], v[146:147], v[46:47] op_sel_hi:[1,0,1]
	v_pk_fma_f32 v[42:43], v[4:5], v[146:147], v[48:49] op_sel_hi:[1,0,1]
	v_pk_fma_f32 v[44:45], v[6:7], v[146:147], v[50:51] op_sel_hi:[1,0,1]
	v_pk_fma_f32 v[46:47], v[8:9], v[146:147], v[52:53] op_sel_hi:[1,0,1]
	v_pk_fma_f32 v[48:49], v[10:11], v[146:147], v[54:55] op_sel_hi:[1,0,1]
	v_pk_fma_f32 v[50:51], v[12:13], v[146:147], v[126:127] op_sel_hi:[1,0,1]
	v_pk_fma_f32 v[52:53], v[14:15], v[146:147], v[128:129] op_sel_hi:[1,0,1]
	v_pk_fma_f32 v[54:55], v[16:17], v[146:147], v[130:131] op_sel_hi:[1,0,1]
	v_pk_fma_f32 v[132:133], v[18:19], v[146:147], v[132:133] op_sel_hi:[1,0,1]
	v_pk_fma_f32 v[134:135], v[20:21], v[146:147], v[134:135] op_sel_hi:[1,0,1]
	v_pk_fma_f32 v[136:137], v[22:23], v[146:147], v[136:137] op_sel_hi:[1,0,1]
	v_pk_fma_f32 v[138:139], v[24:25], v[146:147], v[138:139] op_sel_hi:[1,0,1]
	v_pk_fma_f32 v[140:141], v[26:27], v[146:147], v[140:141] op_sel_hi:[1,0,1]
	v_pk_fma_f32 v[142:143], v[28:29], v[146:147], v[142:143] op_sel_hi:[1,0,1]
	v_pk_fma_f32 v[144:145], v[30:31], v[146:147], v[144:145] op_sel_hi:[1,0,1]
	v_cndmask_b32_e64 v146, v0, v1, s[0:1]
	v_mov_b32_e32 v0, s13
	v_mov_b32_e32 v1, s12
	v_cndmask_b32_e64 v0, v0, v1, s[0:1]
	v_mad_i64_i32 v[130:131], s[12:13], v0, s23, v[64:65]
	s_waitcnt vmcnt(0)
	v_cvt_scalef32_pk32_f32_fp6 v[0:31], v[32:37], 1.0
	v_readlane_b32 s12, v108, 17
	v_readlane_b32 s13, v107, 17
	v_pk_fma_f32 v[150:151], v[0:1], v[146:147], v[38:39] op_sel_hi:[1,0,1]
	v_mov_b32_e32 v1, s12
	v_mov_b32_e32 v0, s13
	v_cndmask_b32_e64 v0, v0, v1, s[0:1]
	v_mad_i64_i32 v[0:1], s[12:13], v0, s23, v[64:65]
	v_readlane_b32 s12, v108, 18
	v_readlane_b32 s13, v107, 18
	global_load_dwordx4 v[126:129], v[130:131], off
	v_pk_fma_f32 v[168:169], v[18:19], v[146:147], v[132:133] op_sel_hi:[1,0,1]
	global_load_dwordx2 v[130:131], v[130:131], off offset:16
	v_pk_fma_f32 v[170:171], v[20:21], v[146:147], v[134:135] op_sel_hi:[1,0,1]
	v_pk_fma_f32 v[172:173], v[22:23], v[146:147], v[136:137] op_sel_hi:[1,0,1]
	global_load_dwordx2 v[136:137], v[0:1], off offset:16
	global_load_dwordx4 v[132:135], v[0:1], off
	v_mov_b32_e32 v0, s13
	v_mov_b32_e32 v1, s12
	v_cndmask_b32_e64 v0, v0, v1, s[0:1]
	v_mad_i64_i32 v[0:1], s[12:13], v0, s23, v[64:65]
	v_readlane_b32 s12, v108, 19
	v_readlane_b32 s13, v107, 19
	v_pk_fma_f32 v[152:153], v[2:3], v[146:147], v[40:41] op_sel_hi:[1,0,1]
	v_mov_b32_e32 v3, s12
	v_mov_b32_e32 v2, s13
	v_cndmask_b32_e64 v2, v2, v3, s[0:1]
	v_mad_i64_i32 v[2:3], s[12:13], v2, s23, v[64:65]
	v_readlane_b32 s12, v108, 20
	v_readlane_b32 s13, v107, 20
	v_pk_fma_f32 v[154:155], v[4:5], v[146:147], v[42:43] op_sel_hi:[1,0,1]
	v_pk_fma_f32 v[156:157], v[6:7], v[146:147], v[44:45] op_sel_hi:[1,0,1]
	v_pk_fma_f32 v[158:159], v[8:9], v[146:147], v[46:47] op_sel_hi:[1,0,1]
	v_pk_fma_f32 v[160:161], v[10:11], v[146:147], v[48:49] op_sel_hi:[1,0,1]
	v_pk_fma_f32 v[162:163], v[12:13], v[146:147], v[50:51] op_sel_hi:[1,0,1]
	v_pk_fma_f32 v[164:165], v[14:15], v[146:147], v[52:53] op_sel_hi:[1,0,1]
	v_pk_fma_f32 v[166:167], v[16:17], v[146:147], v[54:55] op_sel_hi:[1,0,1]
	v_pk_fma_f32 v[174:175], v[24:25], v[146:147], v[138:139] op_sel_hi:[1,0,1]
	v_pk_fma_f32 v[176:177], v[26:27], v[146:147], v[140:141] op_sel_hi:[1,0,1]
	v_pk_fma_f32 v[178:179], v[28:29], v[146:147], v[142:143] op_sel_hi:[1,0,1]
	v_pk_fma_f32 v[180:181], v[30:31], v[146:147], v[144:145] op_sel_hi:[1,0,1]
	global_load_dwordx4 v[138:141], v[0:1], off
	global_load_dwordx2 v[142:143], v[0:1], off offset:16
	global_load_dwordx4 v[144:147], v[2:3], off
	v_mov_b32_e32 v0, s13
	v_mov_b32_e32 v1, s12
	v_cndmask_b32_e64 v0, v0, v1, s[0:1]
	v_mad_i64_i32 v[0:1], s[12:13], v0, s23, v[64:65]
	v_readlane_b32 s12, v108, 21
	v_readlane_b32 s13, v107, 21
	global_load_dwordx2 v[148:149], v[2:3], off offset:16
	global_load_dwordx4 v[50:53], v[0:1], off
	v_mov_b32_e32 v2, s13
	v_mov_b32_e32 v3, s12
	v_cndmask_b32_e64 v2, v2, v3, s[0:1]
	v_mad_i64_i32 v[2:3], s[12:13], v2, s23, v[64:65]
	v_readlane_b32 s12, v108, 22
	v_readlane_b32 s13, v107, 22
	global_load_dwordx2 v[54:55], v[0:1], off offset:16
	global_load_dwordx4 v[44:47], v[2:3], off
	v_mov_b32_e32 v0, s13
	v_mov_b32_e32 v1, s12
	v_cndmask_b32_e64 v0, v0, v1, s[0:1]
	v_mad_i64_i32 v[0:1], s[12:13], v0, s23, v[64:65]
	v_readlane_b32 s12, v108, 23
	v_readlane_b32 s13, v107, 23
	global_load_dwordx2 v[48:49], v[2:3], off offset:16
	global_load_dwordx4 v[38:41], v[0:1], off
	v_mov_b32_e32 v2, s13
	v_mov_b32_e32 v3, s12
	v_cndmask_b32_e64 v2, v2, v3, s[0:1]
	v_mad_i64_i32 v[2:3], s[12:13], v2, s23, v[64:65]
	global_load_dwordx2 v[36:37], v[2:3], off offset:16
	global_load_dwordx2 v[42:43], v[0:1], off offset:16
	global_load_dwordx4 v[32:35], v[2:3], off
	v_readlane_b32 s12, v106, 16
	v_readlane_b32 s13, v109, 16
	s_nop 0
	v_mov_b32_e32 v1, s12
	v_mov_b32_e32 v0, s13
	v_cndmask_b32_e64 v182, v0, v1, s[0:1]
	v_readlane_b32 s12, v106, 17
	v_readlane_b32 s13, v109, 17
	s_waitcnt vmcnt(14)
; DI void phase_peer_out(const Params& p, char* lds) {
;     ...
;       for (int k = 0; k < 8; ++k) {
;         const int e0 = __builtin_amdgcn_readlane(el[0], kb * 8 + k), e1 = __builtin_amdgcn_readlane(el[1], kb * 8 + k);
;         qb[k] = load6(V6 + (size_t)(hb ? e1 : e0) * 768);
;       }
; #pragma unroll
;       for (int k = 0; k < 8; ++k) {
;         const float c0 = __uint_as_float(__builtin_amdgcn_readlane(__float_as_uint(coefv[0]), kb * 8 + k)), c1 = __uint_as_float(__builtin_amdgcn_readlane(__float_as_uint(coefv[1]), kb * 8 + k));
;         const float cf = hb ? c1 : c0;
;         const f32x2 c2 = {cf, cf};
;         const v32f f = __builtin_amdgcn_cvt_scalef32_pk32_f32_fp6(qb[k], 1.0f);
; #pragma unroll
;         for (int i = 0; i < 16; ++i) o2[i] = f32x2{f[2 * i], f[2 * i + 1]} * c2 + o2[i];
	v_cvt_scalef32_pk32_f32_fp6 v[0:31], v[126:131], 1.0
	v_pk_fma_f32 v[126:127], v[0:1], v[182:183], v[150:151] op_sel_hi:[1,0,1]
	v_mov_b32_e32 v0, s13
	v_mov_b32_e32 v1, s12
	v_pk_fma_f32 v[128:129], v[2:3], v[182:183], v[152:153] op_sel_hi:[1,0,1]
	v_pk_fma_f32 v[130:131], v[4:5], v[182:183], v[154:155] op_sel_hi:[1,0,1]
	v_pk_fma_f32 v[150:151], v[6:7], v[182:183], v[156:157] op_sel_hi:[1,0,1]
	v_pk_fma_f32 v[152:153], v[8:9], v[182:183], v[158:159] op_sel_hi:[1,0,1]
	v_pk_fma_f32 v[154:155], v[10:11], v[182:183], v[160:161] op_sel_hi:[1,0,1]
	v_pk_fma_f32 v[156:157], v[12:13], v[182:183], v[162:163] op_sel_hi:[1,0,1]
	v_pk_fma_f32 v[158:159], v[14:15], v[182:183], v[164:165] op_sel_hi:[1,0,1]
	v_pk_fma_f32 v[160:161], v[16:17], v[182:183], v[166:167] op_sel_hi:[1,0,1]
	v_pk_fma_f32 v[162:163], v[18:19], v[182:183], v[168:169] op_sel_hi:[1,0,1]
	v_pk_fma_f32 v[164:165], v[20:21], v[182:183], v[170:171] op_sel_hi:[1,0,1]
	v_pk_fma_f32 v[166:167], v[22:23], v[182:183], v[172:173] op_sel_hi:[1,0,1]
	v_pk_fma_f32 v[168:169], v[24:25], v[182:183], v[174:175] op_sel_hi:[1,0,1]
	v_pk_fma_f32 v[170:171], v[26:27], v[182:183], v[176:177] op_sel_hi:[1,0,1]
	v_pk_fma_f32 v[172:173], v[28:29], v[182:183], v[178:179] op_sel_hi:[1,0,1]
	v_pk_fma_f32 v[174:175], v[30:31], v[182:183], v[180:181] op_sel_hi:[1,0,1]
	v_cndmask_b32_e64 v176, v0, v1, s[0:1]
	s_waitcnt vmcnt(12)
	v_cvt_scalef32_pk32_f32_fp6 v[0:31], v[132:137], 1.0
	v_readlane_b32 s12, v106, 18
	v_readlane_b32 s13, v109, 18
	v_pk_fma_f32 v[126:127], v[0:1], v[176:177], v[126:127] op_sel_hi:[1,0,1]
	v_mov_b32_e32 v1, s12
	v_mov_b32_e32 v0, s13
	v_pk_fma_f32 v[128:129], v[2:3], v[176:177], v[128:129] op_sel_hi:[1,0,1]
	v_pk_fma_f32 v[130:131], v[4:5], v[176:177], v[130:131] op_sel_hi:[1,0,1]
	v_pk_fma_f32 v[132:133], v[6:7], v[176:177], v[150:151] op_sel_hi:[1,0,1]
	v_pk_fma_f32 v[134:135], v[8:9], v[176:177], v[152:153] op_sel_hi:[1,0,1]
	v_pk_fma_f32 v[136:137], v[10:11], v[176:177], v[154:155] op_sel_hi:[1,0,1]
	v_pk_fma_f32 v[150:151], v[12:13], v[176:177], v[156:157] op_sel_hi:[1,0,1]
	v_pk_fma_f32 v[152:153], v[14:15], v[176:177], v[158:159] op_sel_hi:[1,0,1]
	v_pk_fma_f32 v[154:155], v[16:17], v[176:177], v[160:161] op_sel_hi:[1,0,1]
	v_pk_fma_f32 v[156:157], v[18:19], v[176:177], v[162:163] op_sel_hi:[1,0,1]
	v_pk_fma_f32 v[158:159], v[20:21], v[176:177], v[164:165] op_sel_hi:[1,0,1]
	v_pk_fma_f32 v[160:161], v[22:23], v[176:177], v[166:167] op_sel_hi:[1,0,1]
	v_pk_fma_f32 v[162:163], v[24:25], v[176:177], v[168:169] op_sel_hi:[1,0,1]
	v_pk_fma_f32 v[164:165], v[26:27], v[176:177], v[170:171] op_sel_hi:[1,0,1]
	v_pk_fma_f32 v[166:167], v[28:29], v[176:177], v[172:173] op_sel_hi:[1,0,1]
	v_pk_fma_f32 v[168:169], v[30:31], v[176:177], v[174:175] op_sel_hi:[1,0,1]
	v_cndmask_b32_e64 v170, v0, v1, s[0:1]
	s_waitcnt vmcnt(10)
	v_cvt_scalef32_pk32_f32_fp6 v[0:31], v[138:143], 1.0
	v_readlane_b32 s12, v106, 19
	v_readlane_b32 s13, v109, 19
	v_pk_fma_f32 v[126:127], v[0:1], v[170:171], v[126:127] op_sel_hi:[1,0,1]
	v_mov_b32_e32 v1, s12
	v_mov_b32_e32 v0, s13
	v_pk_fma_f32 v[128:129], v[2:3], v[170:171], v[128:129] op_sel_hi:[1,0,1]
	v_pk_fma_f32 v[130:131], v[4:5], v[170:171], v[130:131] op_sel_hi:[1,0,1]
	v_pk_fma_f32 v[132:133], v[6:7], v[170:171], v[132:133] op_sel_hi:[1,0,1]
	v_pk_fma_f32 v[134:135], v[8:9], v[170:171], v[134:135] op_sel_hi:[1,0,1]
	v_pk_fma_f32 v[136:137], v[10:11], v[170:171], v[136:137] op_sel_hi:[1,0,1]
	v_pk_fma_f32 v[138:139], v[12:13], v[170:171], v[150:151] op_sel_hi:[1,0,1]
	v_pk_fma_f32 v[140:141], v[14:15], v[170:171], v[152:153] op_sel_hi:[1,0,1]
	v_pk_fma_f32 v[142:143], v[16:17], v[170:171], v[154:155] op_sel_hi:[1,0,1]
	v_pk_fma_f32 v[150:151], v[18:19], v[170:171], v[156:157] op_sel_hi:[1,0,1]
	v_pk_fma_f32 v[152:153], v[20:21], v[170:171], v[158:159] op_sel_hi:[1,0,1]
	v_pk_fma_f32 v[154:155], v[22:23], v[170:171], v[160:161] op_sel_hi:[1,0,1]
	v_pk_fma_f32 v[156:157], v[24:25], v[170:171], v[162:163] op_sel_hi:[1,0,1]
	v_pk_fma_f32 v[158:159], v[26:27], v[170:171], v[164:165] op_sel_hi:[1,0,1]
	v_pk_fma_f32 v[160:161], v[28:29], v[170:171], v[166:167] op_sel_hi:[1,0,1]
	v_pk_fma_f32 v[162:163], v[30:31], v[170:171], v[168:169] op_sel_hi:[1,0,1]
	v_cndmask_b32_e64 v164, v0, v1, s[0:1]
	s_waitcnt vmcnt(8)
	v_cvt_scalef32_pk32_f32_fp6 v[0:31], v[144:149], 1.0
	v_readlane_b32 s12, v106, 20
	v_readlane_b32 s13, v109, 20
	v_pk_fma_f32 v[126:127], v[0:1], v[164:165], v[126:127] op_sel_hi:[1,0,1]
	v_mov_b32_e32 v1, s12
	v_mov_b32_e32 v0, s13
	v_pk_fma_f32 v[128:129], v[2:3], v[164:165], v[128:129] op_sel_hi:[1,0,1]
	v_pk_fma_f32 v[130:131], v[4:5], v[164:165], v[130:131] op_sel_hi:[1,0,1]
	v_pk_fma_f32 v[132:133], v[6:7], v[164:165], v[132:133] op_sel_hi:[1,0,1]
	v_pk_fma_f32 v[134:135], v[8:9], v[164:165], v[134:135] op_sel_hi:[1,0,1]
	v_pk_fma_f32 v[136:137], v[10:11], v[164:165], v[136:137] op_sel_hi:[1,0,1]
	v_pk_fma_f32 v[138:139], v[12:13], v[164:165], v[138:139] op_sel_hi:[1,0,1]
	v_pk_fma_f32 v[140:141], v[14:15], v[164:165], v[140:141] op_sel_hi:[1,0,1]
	v_pk_fma_f32 v[142:143], v[16:17], v[164:165], v[142:143] op_sel_hi:[1,0,1]
	v_pk_fma_f32 v[144:145], v[18:19], v[164:165], v[150:151] op_sel_hi:[1,0,1]
	v_pk_fma_f32 v[146:147], v[20:21], v[164:165], v[152:153] op_sel_hi:[1,0,1]
	v_pk_fma_f32 v[148:149], v[22:23], v[164:165], v[154:155] op_sel_hi:[1,0,1]
	v_pk_fma_f32 v[150:151], v[24:25], v[164:165], v[156:157] op_sel_hi:[1,0,1]
	v_pk_fma_f32 v[152:153], v[26:27], v[164:165], v[158:159] op_sel_hi:[1,0,1]
	v_pk_fma_f32 v[154:155], v[28:29], v[164:165], v[160:161] op_sel_hi:[1,0,1]
	v_pk_fma_f32 v[156:157], v[30:31], v[164:165], v[162:163] op_sel_hi:[1,0,1]
	v_cndmask_b32_e64 v158, v0, v1, s[0:1]
	s_waitcnt vmcnt(6)
; DI void phase_peer_out(const Params& p, char* lds) {
;     ...
;       for (int k = 0; k < 8; ++k) {
;         const int e0 = __builtin_amdgcn_readlane(el[0], kb * 8 + k), e1 = __builtin_amdgcn_readlane(el[1], kb * 8 + k);
;         qb[k] = load6(V6 + (size_t)(hb ? e1 : e0) * 768);
;       }
; #pragma unroll
;       for (int k = 0; k < 8; ++k) {
;         const float c0 = __uint_as_float(__builtin_amdgcn_readlane(__float_as_uint(coefv[0]), kb * 8 + k)), c1 = __uint_as_float(__builtin_amdgcn_readlane(__float_as_uint(coefv[1]), kb * 8 + k));
;         const float cf = hb ? c1 : c0;
;         const f32x2 c2 = {cf, cf};
;         const v32f f = __builtin_amdgcn_cvt_scalef32_pk32_f32_fp6(qb[k], 1.0f);
; #pragma unroll
;         for (int i = 0; i < 16; ++i) o2[i] = f32x2{f[2 * i], f[2 * i + 1]} * c2 + o2[i];
	v_cvt_scalef32_pk32_f32_fp6 v[0:31], v[50:55], 1.0
	v_readlane_b32 s12, v106, 21
	v_readlane_b32 s13, v109, 21
	v_pk_fma_f32 v[50:51], v[0:1], v[158:159], v[126:127] op_sel_hi:[1,0,1]
	v_mov_b32_e32 v1, s12
	v_mov_b32_e32 v0, s13
	v_pk_fma_f32 v[52:53], v[2:3], v[158:159], v[128:129] op_sel_hi:[1,0,1]
	v_pk_fma_f32 v[54:55], v[4:5], v[158:159], v[130:131] op_sel_hi:[1,0,1]
	v_pk_fma_f32 v[126:127], v[6:7], v[158:159], v[132:133] op_sel_hi:[1,0,1]
	v_pk_fma_f32 v[128:129], v[8:9], v[158:159], v[134:135] op_sel_hi:[1,0,1]
	v_pk_fma_f32 v[130:131], v[10:11], v[158:159], v[136:137] op_sel_hi:[1,0,1]
	v_pk_fma_f32 v[132:133], v[12:13], v[158:159], v[138:139] op_sel_hi:[1,0,1]
	v_pk_fma_f32 v[134:135], v[14:15], v[158:159], v[140:141] op_sel_hi:[1,0,1]
	v_pk_fma_f32 v[136:137], v[16:17], v[158:159], v[142:143] op_sel_hi:[1,0,1]
	v_pk_fma_f32 v[138:139], v[18:19], v[158:159], v[144:145] op_sel_hi:[1,0,1]
	v_pk_fma_f32 v[140:141], v[20:21], v[158:159], v[146:147] op_sel_hi:[1,0,1]
	v_pk_fma_f32 v[142:143], v[22:23], v[158:159], v[148:149] op_sel_hi:[1,0,1]
	v_pk_fma_f32 v[144:145], v[24:25], v[158:159], v[150:151] op_sel_hi:[1,0,1]
	v_pk_fma_f32 v[146:147], v[26:27], v[158:159], v[152:153] op_sel_hi:[1,0,1]
	v_pk_fma_f32 v[148:149], v[28:29], v[158:159], v[154:155] op_sel_hi:[1,0,1]
	v_pk_fma_f32 v[150:151], v[30:31], v[158:159], v[156:157] op_sel_hi:[1,0,1]
	v_cndmask_b32_e64 v152, v0, v1, s[0:1]
	s_waitcnt vmcnt(4)
	v_cvt_scalef32_pk32_f32_fp6 v[0:31], v[44:49], 1.0
	v_readlane_b32 s12, v106, 22
	v_readlane_b32 s13, v109, 22
	v_pk_fma_f32 v[44:45], v[0:1], v[152:153], v[50:51] op_sel_hi:[1,0,1]
	v_mov_b32_e32 v1, s12
	v_mov_b32_e32 v0, s13
	v_pk_fma_f32 v[46:47], v[2:3], v[152:153], v[52:53] op_sel_hi:[1,0,1]
	v_pk_fma_f32 v[48:49], v[4:5], v[152:153], v[54:55] op_sel_hi:[1,0,1]
	v_pk_fma_f32 v[50:51], v[6:7], v[152:153], v[126:127] op_sel_hi:[1,0,1]
	v_pk_fma_f32 v[52:53], v[8:9], v[152:153], v[128:129] op_sel_hi:[1,0,1]
	v_pk_fma_f32 v[54:55], v[10:11], v[152:153], v[130:131] op_sel_hi:[1,0,1]
	v_pk_fma_f32 v[126:127], v[12:13], v[152:153], v[132:133] op_sel_hi:[1,0,1]
	v_pk_fma_f32 v[128:129], v[14:15], v[152:153], v[134:135] op_sel_hi:[1,0,1]
	v_pk_fma_f32 v[130:131], v[16:17], v[152:153], v[136:137] op_sel_hi:[1,0,1]
	v_pk_fma_f32 v[132:133], v[18:19], v[152:153], v[138:139] op_sel_hi:[1,0,1]
	v_pk_fma_f32 v[134:135], v[20:21], v[152:153], v[140:141] op_sel_hi:[1,0,1]
	v_pk_fma_f32 v[136:137], v[22:23], v[152:153], v[142:143] op_sel_hi:[1,0,1]
	v_pk_fma_f32 v[138:139], v[24:25], v[152:153], v[144:145] op_sel_hi:[1,0,1]
	v_pk_fma_f32 v[140:141], v[26:27], v[152:153], v[146:147] op_sel_hi:[1,0,1]
	v_pk_fma_f32 v[142:143], v[28:29], v[152:153], v[148:149] op_sel_hi:[1,0,1]
	v_pk_fma_f32 v[144:145], v[30:31], v[152:153], v[150:151] op_sel_hi:[1,0,1]
	v_cndmask_b32_e64 v146, v0, v1, s[0:1]
	s_waitcnt vmcnt(1)
	v_cvt_scalef32_pk32_f32_fp6 v[0:31], v[38:43], 1.0
	v_readlane_b32 s12, v106, 23
	v_readlane_b32 s13, v109, 23
	v_pk_fma_f32 v[38:39], v[0:1], v[146:147], v[44:45] op_sel_hi:[1,0,1]
	v_mov_b32_e32 v1, s12
	v_mov_b32_e32 v0, s13
	v_readlane_b32 s12, v108, 24
	v_readlane_b32 s13, v107, 24
	v_pk_fma_f32 v[40:41], v[2:3], v[146:147], v[46:47] op_sel_hi:[1,0,1]
	v_pk_fma_f32 v[42:43], v[4:5], v[146:147], v[48:49] op_sel_hi:[1,0,1]
	v_pk_fma_f32 v[44:45], v[6:7], v[146:147], v[50:51] op_sel_hi:[1,0,1]
	v_pk_fma_f32 v[46:47], v[8:9], v[146:147], v[52:53] op_sel_hi:[1,0,1]
	v_pk_fma_f32 v[48:49], v[10:11], v[146:147], v[54:55] op_sel_hi:[1,0,1]
	v_pk_fma_f32 v[50:51], v[12:13], v[146:147], v[126:127] op_sel_hi:[1,0,1]
	v_pk_fma_f32 v[52:53], v[14:15], v[146:147], v[128:129] op_sel_hi:[1,0,1]
	v_pk_fma_f32 v[54:55], v[16:17], v[146:147], v[130:131] op_sel_hi:[1,0,1]
	v_pk_fma_f32 v[132:133], v[18:19], v[146:147], v[132:133] op_sel_hi:[1,0,1]
	v_pk_fma_f32 v[134:135], v[20:21], v[146:147], v[134:135] op_sel_hi:[1,0,1]
	v_pk_fma_f32 v[136:137], v[22:23], v[146:147], v[136:137] op_sel_hi:[1,0,1]
	v_pk_fma_f32 v[138:139], v[24:25], v[146:147], v[138:139] op_sel_hi:[1,0,1]
	v_pk_fma_f32 v[140:141], v[26:27], v[146:147], v[140:141] op_sel_hi:[1,0,1]
	v_pk_fma_f32 v[142:143], v[28:29], v[146:147], v[142:143] op_sel_hi:[1,0,1]
	v_pk_fma_f32 v[144:145], v[30:31], v[146:147], v[144:145] op_sel_hi:[1,0,1]
	v_cndmask_b32_e64 v146, v0, v1, s[0:1]
	v_mov_b32_e32 v0, s13
	v_mov_b32_e32 v1, s12
	v_cndmask_b32_e64 v0, v0, v1, s[0:1]
	v_mad_i64_i32 v[130:131], s[12:13], v0, s23, v[64:65]
	s_waitcnt vmcnt(0)
; DI void phase_peer_out(const Params& p, char* lds) {
;     ...
;     for (int kb = 0; kb < 8; ++kb) {
;       v6u qb[8];
; #pragma unroll
;       for (int k = 0; k < 8; ++k) {
;         const int e0 = __builtin_amdgcn_readlane(el[0], kb * 8 + k), e1 = __builtin_amdgcn_readlane(el[1], kb * 8 + k);
;         qb[k] = load6(V6 + (size_t)(hb ? e1 : e0) * 768);
;       }
; #pragma unroll
;       for (int k = 0; k < 8; ++k) {
;         const float c0 = __uint_as_float(__builtin_amdgcn_readlane(__float_as_uint(coefv[0]), kb * 8 + k)), c1 = __uint_as_float(__builtin_amdgcn_readlane(__float_as_uint(coefv[1]), kb * 8 + k));
;         const float cf = hb ? c1 : c0;
;         const f32x2 c2 = {cf, cf};
;         const v32f f = __builtin_amdgcn_cvt_scalef32_pk32_f32_fp6(qb[k], 1.0f);
; #pragma unroll
;         for (int i = 0; i < 16; ++i) o2[i] = f32x2{f[2 * i], f[2 * i + 1]} * c2 + o2[i];
	v_cvt_scalef32_pk32_f32_fp6 v[0:31], v[32:37], 1.0
	v_readlane_b32 s12, v108, 25
	v_readlane_b32 s13, v107, 25
	v_pk_fma_f32 v[150:151], v[0:1], v[146:147], v[38:39] op_sel_hi:[1,0,1]
	v_mov_b32_e32 v1, s12
	v_mov_b32_e32 v0, s13
	v_cndmask_b32_e64 v0, v0, v1, s[0:1]
	v_mad_i64_i32 v[0:1], s[12:13], v0, s23, v[64:65]
	v_readlane_b32 s12, v108, 26
	v_readlane_b32 s13, v107, 26
	global_load_dwordx4 v[126:129], v[130:131], off
	v_pk_fma_f32 v[168:169], v[18:19], v[146:147], v[132:133] op_sel_hi:[1,0,1]
	global_load_dwordx2 v[130:131], v[130:131], off offset:16
	v_pk_fma_f32 v[170:171], v[20:21], v[146:147], v[134:135] op_sel_hi:[1,0,1]
	v_pk_fma_f32 v[172:173], v[22:23], v[146:147], v[136:137] op_sel_hi:[1,0,1]
	global_load_dwordx2 v[136:137], v[0:1], off offset:16
	global_load_dwordx4 v[132:135], v[0:1], off
	v_mov_b32_e32 v0, s13
	v_mov_b32_e32 v1, s12
	v_cndmask_b32_e64 v0, v0, v1, s[0:1]
	v_mad_i64_i32 v[0:1], s[12:13], v0, s23, v[64:65]
	v_readlane_b32 s12, v108, 27
	v_readlane_b32 s13, v107, 27
	v_pk_fma_f32 v[152:153], v[2:3], v[146:147], v[40:41] op_sel_hi:[1,0,1]
	v_mov_b32_e32 v3, s12
	v_mov_b32_e32 v2, s13
	v_cndmask_b32_e64 v2, v2, v3, s[0:1]
	v_mad_i64_i32 v[2:3], s[12:13], v2, s23, v[64:65]
	v_readlane_b32 s12, v108, 28
	v_readlane_b32 s13, v107, 28
	v_pk_fma_f32 v[154:155], v[4:5], v[146:147], v[42:43] op_sel_hi:[1,0,1]
	v_pk_fma_f32 v[156:157], v[6:7], v[146:147], v[44:45] op_sel_hi:[1,0,1]
	v_pk_fma_f32 v[158:159], v[8:9], v[146:147], v[46:47] op_sel_hi:[1,0,1]
	v_pk_fma_f32 v[160:161], v[10:11], v[146:147], v[48:49] op_sel_hi:[1,0,1]
	v_pk_fma_f32 v[162:163], v[12:13], v[146:147], v[50:51] op_sel_hi:[1,0,1]
	v_pk_fma_f32 v[164:165], v[14:15], v[146:147], v[52:53] op_sel_hi:[1,0,1]
	v_pk_fma_f32 v[166:167], v[16:17], v[146:147], v[54:55] op_sel_hi:[1,0,1]
	v_pk_fma_f32 v[174:175], v[24:25], v[146:147], v[138:139] op_sel_hi:[1,0,1]
	v_pk_fma_f32 v[176:177], v[26:27], v[146:147], v[140:141] op_sel_hi:[1,0,1]
	v_pk_fma_f32 v[178:179], v[28:29], v[146:147], v[142:143] op_sel_hi:[1,0,1]
	v_pk_fma_f32 v[180:181], v[30:31], v[146:147], v[144:145] op_sel_hi:[1,0,1]
	global_load_dwordx4 v[138:141], v[0:1], off
	global_load_dwordx2 v[142:143], v[0:1], off offset:16
	global_load_dwordx4 v[144:147], v[2:3], off
	v_mov_b32_e32 v0, s13
	v_mov_b32_e32 v1, s12
	v_cndmask_b32_e64 v0, v0, v1, s[0:1]
	v_mad_i64_i32 v[0:1], s[12:13], v0, s23, v[64:65]
	v_readlane_b32 s12, v108, 29
	v_readlane_b32 s13, v107, 29
	global_load_dwordx2 v[148:149], v[2:3], off offset:16
	global_load_dwordx4 v[50:53], v[0:1], off
	v_mov_b32_e32 v2, s13
	v_mov_b32_e32 v3, s12
	v_cndmask_b32_e64 v2, v2, v3, s[0:1]
	v_mad_i64_i32 v[2:3], s[12:13], v2, s23, v[64:65]
	v_readlane_b32 s12, v108, 30
	v_readlane_b32 s13, v107, 30
	global_load_dwordx2 v[54:55], v[0:1], off offset:16
	global_load_dwordx4 v[44:47], v[2:3], off
	v_mov_b32_e32 v0, s13
	v_mov_b32_e32 v1, s12
	v_cndmask_b32_e64 v0, v0, v1, s[0:1]
	v_mad_i64_i32 v[0:1], s[12:13], v0, s23, v[64:65]
	v_readlane_b32 s12, v108, 31
	v_readlane_b32 s13, v107, 31
	global_load_dwordx2 v[48:49], v[2:3], off offset:16
	global_load_dwordx4 v[38:41], v[0:1], off
	v_mov_b32_e32 v2, s13
	v_mov_b32_e32 v3, s12
	v_cndmask_b32_e64 v2, v2, v3, s[0:1]
	v_mad_i64_i32 v[2:3], s[12:13], v2, s23, v[64:65]
	global_load_dwordx2 v[36:37], v[2:3], off offset:16
	global_load_dwordx2 v[42:43], v[0:1], off offset:16
	global_load_dwordx4 v[32:35], v[2:3], off
	v_readlane_b32 s12, v106, 24
	v_readlane_b32 s13, v109, 24
	s_nop 0
	v_mov_b32_e32 v1, s12
	v_mov_b32_e32 v0, s13
	v_cndmask_b32_e64 v182, v0, v1, s[0:1]
	v_readlane_b32 s12, v106, 25
	v_readlane_b32 s13, v109, 25
	s_waitcnt vmcnt(14)
	v_cvt_scalef32_pk32_f32_fp6 v[0:31], v[126:131], 1.0
	v_pk_fma_f32 v[126:127], v[0:1], v[182:183], v[150:151] op_sel_hi:[1,0,1]
	v_mov_b32_e32 v0, s13
	v_mov_b32_e32 v1, s12
	v_pk_fma_f32 v[128:129], v[2:3], v[182:183], v[152:153] op_sel_hi:[1,0,1]
	v_pk_fma_f32 v[130:131], v[4:5], v[182:183], v[154:155] op_sel_hi:[1,0,1]
	v_pk_fma_f32 v[150:151], v[6:7], v[182:183], v[156:157] op_sel_hi:[1,0,1]
	v_pk_fma_f32 v[152:153], v[8:9], v[182:183], v[158:159] op_sel_hi:[1,0,1]
	v_pk_fma_f32 v[154:155], v[10:11], v[182:183], v[160:161] op_sel_hi:[1,0,1]
	v_pk_fma_f32 v[156:157], v[12:13], v[182:183], v[162:163] op_sel_hi:[1,0,1]
	v_pk_fma_f32 v[158:159], v[14:15], v[182:183], v[164:165] op_sel_hi:[1,0,1]
	v_pk_fma_f32 v[160:161], v[16:17], v[182:183], v[166:167] op_sel_hi:[1,0,1]
	v_pk_fma_f32 v[162:163], v[18:19], v[182:183], v[168:169] op_sel_hi:[1,0,1]
	v_pk_fma_f32 v[164:165], v[20:21], v[182:183], v[170:171] op_sel_hi:[1,0,1]
	v_pk_fma_f32 v[166:167], v[22:23], v[182:183], v[172:173] op_sel_hi:[1,0,1]
	v_pk_fma_f32 v[168:169], v[24:25], v[182:183], v[174:175] op_sel_hi:[1,0,1]
	v_pk_fma_f32 v[170:171], v[26:27], v[182:183], v[176:177] op_sel_hi:[1,0,1]
	v_pk_fma_f32 v[172:173], v[28:29], v[182:183], v[178:179] op_sel_hi:[1,0,1]
	v_pk_fma_f32 v[174:175], v[30:31], v[182:183], v[180:181] op_sel_hi:[1,0,1]
	v_cndmask_b32_e64 v176, v0, v1, s[0:1]
	s_waitcnt vmcnt(12)
; DI void phase_peer_out(const Params& p, char* lds) {
;     ...
;       for (int k = 0; k < 8; ++k) {
;         const int e0 = __builtin_amdgcn_readlane(el[0], kb * 8 + k), e1 = __builtin_amdgcn_readlane(el[1], kb * 8 + k);
;         qb[k] = load6(V6 + (size_t)(hb ? e1 : e0) * 768);
;       }
; #pragma unroll
;       for (int k = 0; k < 8; ++k) {
;         const float c0 = __uint_as_float(__builtin_amdgcn_readlane(__float_as_uint(coefv[0]), kb * 8 + k)), c1 = __uint_as_float(__builtin_amdgcn_readlane(__float_as_uint(coefv[1]), kb * 8 + k));
;         const float cf = hb ? c1 : c0;
;         const f32x2 c2 = {cf, cf};
;         const v32f f = __builtin_amdgcn_cvt_scalef32_pk32_f32_fp6(qb[k], 1.0f);
; #pragma unroll
;         for (int i = 0; i < 16; ++i) o2[i] = f32x2{f[2 * i], f[2 * i + 1]} * c2 + o2[i];
	v_cvt_scalef32_pk32_f32_fp6 v[0:31], v[132:137], 1.0
	v_readlane_b32 s12, v106, 26
	v_readlane_b32 s13, v109, 26
	v_pk_fma_f32 v[126:127], v[0:1], v[176:177], v[126:127] op_sel_hi:[1,0,1]
	v_mov_b32_e32 v1, s12
	v_mov_b32_e32 v0, s13
	v_pk_fma_f32 v[128:129], v[2:3], v[176:177], v[128:129] op_sel_hi:[1,0,1]
	v_pk_fma_f32 v[130:131], v[4:5], v[176:177], v[130:131] op_sel_hi:[1,0,1]
	v_pk_fma_f32 v[132:133], v[6:7], v[176:177], v[150:151] op_sel_hi:[1,0,1]
	v_pk_fma_f32 v[134:135], v[8:9], v[176:177], v[152:153] op_sel_hi:[1,0,1]
	v_pk_fma_f32 v[136:137], v[10:11], v[176:177], v[154:155] op_sel_hi:[1,0,1]
	v_pk_fma_f32 v[150:151], v[12:13], v[176:177], v[156:157] op_sel_hi:[1,0,1]
	v_pk_fma_f32 v[152:153], v[14:15], v[176:177], v[158:159] op_sel_hi:[1,0,1]
	v_pk_fma_f32 v[154:155], v[16:17], v[176:177], v[160:161] op_sel_hi:[1,0,1]
	v_pk_fma_f32 v[156:157], v[18:19], v[176:177], v[162:163] op_sel_hi:[1,0,1]
	v_pk_fma_f32 v[158:159], v[20:21], v[176:177], v[164:165] op_sel_hi:[1,0,1]
	v_pk_fma_f32 v[160:161], v[22:23], v[176:177], v[166:167] op_sel_hi:[1,0,1]
	v_pk_fma_f32 v[162:163], v[24:25], v[176:177], v[168:169] op_sel_hi:[1,0,1]
	v_pk_fma_f32 v[164:165], v[26:27], v[176:177], v[170:171] op_sel_hi:[1,0,1]
	v_pk_fma_f32 v[166:167], v[28:29], v[176:177], v[172:173] op_sel_hi:[1,0,1]
	v_pk_fma_f32 v[168:169], v[30:31], v[176:177], v[174:175] op_sel_hi:[1,0,1]
	v_cndmask_b32_e64 v170, v0, v1, s[0:1]
	s_waitcnt vmcnt(10)
	v_cvt_scalef32_pk32_f32_fp6 v[0:31], v[138:143], 1.0
	v_readlane_b32 s12, v106, 27
	v_readlane_b32 s13, v109, 27
	v_pk_fma_f32 v[126:127], v[0:1], v[170:171], v[126:127] op_sel_hi:[1,0,1]
	v_mov_b32_e32 v1, s12
	v_mov_b32_e32 v0, s13
	v_pk_fma_f32 v[128:129], v[2:3], v[170:171], v[128:129] op_sel_hi:[1,0,1]
	v_pk_fma_f32 v[130:131], v[4:5], v[170:171], v[130:131] op_sel_hi:[1,0,1]
	v_pk_fma_f32 v[132:133], v[6:7], v[170:171], v[132:133] op_sel_hi:[1,0,1]
	v_pk_fma_f32 v[134:135], v[8:9], v[170:171], v[134:135] op_sel_hi:[1,0,1]
	v_pk_fma_f32 v[136:137], v[10:11], v[170:171], v[136:137] op_sel_hi:[1,0,1]
	v_pk_fma_f32 v[138:139], v[12:13], v[170:171], v[150:151] op_sel_hi:[1,0,1]
	v_pk_fma_f32 v[140:141], v[14:15], v[170:171], v[152:153] op_sel_hi:[1,0,1]
	v_pk_fma_f32 v[142:143], v[16:17], v[170:171], v[154:155] op_sel_hi:[1,0,1]
	v_pk_fma_f32 v[150:151], v[18:19], v[170:171], v[156:157] op_sel_hi:[1,0,1]
	v_pk_fma_f32 v[152:153], v[20:21], v[170:171], v[158:159] op_sel_hi:[1,0,1]
	v_pk_fma_f32 v[154:155], v[22:23], v[170:171], v[160:161] op_sel_hi:[1,0,1]
	v_pk_fma_f32 v[156:157], v[24:25], v[170:171], v[162:163] op_sel_hi:[1,0,1]
	v_pk_fma_f32 v[158:159], v[26:27], v[170:171], v[164:165] op_sel_hi:[1,0,1]
	v_pk_fma_f32 v[160:161], v[28:29], v[170:171], v[166:167] op_sel_hi:[1,0,1]
	v_pk_fma_f32 v[162:163], v[30:31], v[170:171], v[168:169] op_sel_hi:[1,0,1]
	v_cndmask_b32_e64 v164, v0, v1, s[0:1]
	s_waitcnt vmcnt(8)
	v_cvt_scalef32_pk32_f32_fp6 v[0:31], v[144:149], 1.0
	v_readlane_b32 s12, v106, 28
	v_readlane_b32 s13, v109, 28
	v_pk_fma_f32 v[126:127], v[0:1], v[164:165], v[126:127] op_sel_hi:[1,0,1]
	v_mov_b32_e32 v1, s12
	v_mov_b32_e32 v0, s13
	v_pk_fma_f32 v[128:129], v[2:3], v[164:165], v[128:129] op_sel_hi:[1,0,1]
	v_pk_fma_f32 v[130:131], v[4:5], v[164:165], v[130:131] op_sel_hi:[1,0,1]
	v_pk_fma_f32 v[132:133], v[6:7], v[164:165], v[132:133] op_sel_hi:[1,0,1]
	v_pk_fma_f32 v[134:135], v[8:9], v[164:165], v[134:135] op_sel_hi:[1,0,1]
	v_pk_fma_f32 v[136:137], v[10:11], v[164:165], v[136:137] op_sel_hi:[1,0,1]
	v_pk_fma_f32 v[138:139], v[12:13], v[164:165], v[138:139] op_sel_hi:[1,0,1]
	v_pk_fma_f32 v[140:141], v[14:15], v[164:165], v[140:141] op_sel_hi:[1,0,1]
	v_pk_fma_f32 v[142:143], v[16:17], v[164:165], v[142:143] op_sel_hi:[1,0,1]
	v_pk_fma_f32 v[144:145], v[18:19], v[164:165], v[150:151] op_sel_hi:[1,0,1]
	v_pk_fma_f32 v[146:147], v[20:21], v[164:165], v[152:153] op_sel_hi:[1,0,1]
	v_pk_fma_f32 v[148:149], v[22:23], v[164:165], v[154:155] op_sel_hi:[1,0,1]
	v_pk_fma_f32 v[150:151], v[24:25], v[164:165], v[156:157] op_sel_hi:[1,0,1]
	v_pk_fma_f32 v[152:153], v[26:27], v[164:165], v[158:159] op_sel_hi:[1,0,1]
	v_pk_fma_f32 v[154:155], v[28:29], v[164:165], v[160:161] op_sel_hi:[1,0,1]
	v_pk_fma_f32 v[156:157], v[30:31], v[164:165], v[162:163] op_sel_hi:[1,0,1]
	v_cndmask_b32_e64 v158, v0, v1, s[0:1]
	s_waitcnt vmcnt(6)
	v_cvt_scalef32_pk32_f32_fp6 v[0:31], v[50:55], 1.0
	v_readlane_b32 s12, v106, 29
	v_readlane_b32 s13, v109, 29
	v_pk_fma_f32 v[50:51], v[0:1], v[158:159], v[126:127] op_sel_hi:[1,0,1]
	v_mov_b32_e32 v1, s12
	v_mov_b32_e32 v0, s13
	v_pk_fma_f32 v[52:53], v[2:3], v[158:159], v[128:129] op_sel_hi:[1,0,1]
	v_pk_fma_f32 v[54:55], v[4:5], v[158:159], v[130:131] op_sel_hi:[1,0,1]
	v_pk_fma_f32 v[126:127], v[6:7], v[158:159], v[132:133] op_sel_hi:[1,0,1]
	v_pk_fma_f32 v[128:129], v[8:9], v[158:159], v[134:135] op_sel_hi:[1,0,1]
	v_pk_fma_f32 v[130:131], v[10:11], v[158:159], v[136:137] op_sel_hi:[1,0,1]
	v_pk_fma_f32 v[132:133], v[12:13], v[158:159], v[138:139] op_sel_hi:[1,0,1]
	v_pk_fma_f32 v[134:135], v[14:15], v[158:159], v[140:141] op_sel_hi:[1,0,1]
	v_pk_fma_f32 v[136:137], v[16:17], v[158:159], v[142:143] op_sel_hi:[1,0,1]
	v_pk_fma_f32 v[138:139], v[18:19], v[158:159], v[144:145] op_sel_hi:[1,0,1]
	v_pk_fma_f32 v[140:141], v[20:21], v[158:159], v[146:147] op_sel_hi:[1,0,1]
	v_pk_fma_f32 v[142:143], v[22:23], v[158:159], v[148:149] op_sel_hi:[1,0,1]
	v_pk_fma_f32 v[144:145], v[24:25], v[158:159], v[150:151] op_sel_hi:[1,0,1]
	v_pk_fma_f32 v[146:147], v[26:27], v[158:159], v[152:153] op_sel_hi:[1,0,1]
	v_pk_fma_f32 v[148:149], v[28:29], v[158:159], v[154:155] op_sel_hi:[1,0,1]
	v_pk_fma_f32 v[150:151], v[30:31], v[158:159], v[156:157] op_sel_hi:[1,0,1]
	v_cndmask_b32_e64 v152, v0, v1, s[0:1]
	s_waitcnt vmcnt(4)
; DI void phase_peer_out(const Params& p, char* lds) {
;     ...
;     for (int kb = 0; kb < 8; ++kb) {
;       v6u qb[8];
; #pragma unroll
;       for (int k = 0; k < 8; ++k) {
;         const int e0 = __builtin_amdgcn_readlane(el[0], kb * 8 + k), e1 = __builtin_amdgcn_readlane(el[1], kb * 8 + k);
;         qb[k] = load6(V6 + (size_t)(hb ? e1 : e0) * 768);
;       }
; #pragma unroll
;       for (int k = 0; k < 8; ++k) {
;         const float c0 = __uint_as_float(__builtin_amdgcn_readlane(__float_as_uint(coefv[0]), kb * 8 + k)), c1 = __uint_as_float(__builtin_amdgcn_readlane(__float_as_uint(coefv[1]), kb * 8 + k));
;         const float cf = hb ? c1 : c0;
;         const f32x2 c2 = {cf, cf};
;         const v32f f = __builtin_amdgcn_cvt_scalef32_pk32_f32_fp6(qb[k], 1.0f);
; #pragma unroll
;         for (int i = 0; i < 16; ++i) o2[i] = f32x2{f[2 * i], f[2 * i + 1]} * c2 + o2[i];
	v_cvt_scalef32_pk32_f32_fp6 v[0:31], v[44:49], 1.0
	v_readlane_b32 s12, v106, 30
	v_readlane_b32 s13, v109, 30
	v_pk_fma_f32 v[44:45], v[0:1], v[152:153], v[50:51] op_sel_hi:[1,0,1]
	v_mov_b32_e32 v1, s12
	v_mov_b32_e32 v0, s13
	v_pk_fma_f32 v[46:47], v[2:3], v[152:153], v[52:53] op_sel_hi:[1,0,1]
	v_pk_fma_f32 v[48:49], v[4:5], v[152:153], v[54:55] op_sel_hi:[1,0,1]
	v_pk_fma_f32 v[50:51], v[6:7], v[152:153], v[126:127] op_sel_hi:[1,0,1]
	v_pk_fma_f32 v[52:53], v[8:9], v[152:153], v[128:129] op_sel_hi:[1,0,1]
	v_pk_fma_f32 v[54:55], v[10:11], v[152:153], v[130:131] op_sel_hi:[1,0,1]
	v_pk_fma_f32 v[126:127], v[12:13], v[152:153], v[132:133] op_sel_hi:[1,0,1]
	v_pk_fma_f32 v[128:129], v[14:15], v[152:153], v[134:135] op_sel_hi:[1,0,1]
	v_pk_fma_f32 v[130:131], v[16:17], v[152:153], v[136:137] op_sel_hi:[1,0,1]
	v_pk_fma_f32 v[132:133], v[18:19], v[152:153], v[138:139] op_sel_hi:[1,0,1]
	v_pk_fma_f32 v[134:135], v[20:21], v[152:153], v[140:141] op_sel_hi:[1,0,1]
	v_pk_fma_f32 v[136:137], v[22:23], v[152:153], v[142:143] op_sel_hi:[1,0,1]
	v_pk_fma_f32 v[138:139], v[24:25], v[152:153], v[144:145] op_sel_hi:[1,0,1]
	v_pk_fma_f32 v[140:141], v[26:27], v[152:153], v[146:147] op_sel_hi:[1,0,1]
	v_pk_fma_f32 v[142:143], v[28:29], v[152:153], v[148:149] op_sel_hi:[1,0,1]
	v_pk_fma_f32 v[144:145], v[30:31], v[152:153], v[150:151] op_sel_hi:[1,0,1]
	v_cndmask_b32_e64 v146, v0, v1, s[0:1]
	s_waitcnt vmcnt(1)
	v_cvt_scalef32_pk32_f32_fp6 v[0:31], v[38:43], 1.0
	v_readlane_b32 s12, v106, 31
	v_readlane_b32 s13, v109, 31
	v_pk_fma_f32 v[38:39], v[0:1], v[146:147], v[44:45] op_sel_hi:[1,0,1]
	v_mov_b32_e32 v1, s12
	v_mov_b32_e32 v0, s13
	v_readlane_b32 s12, v108, 32
	v_readlane_b32 s13, v107, 32
	v_pk_fma_f32 v[40:41], v[2:3], v[146:147], v[46:47] op_sel_hi:[1,0,1]
	v_pk_fma_f32 v[42:43], v[4:5], v[146:147], v[48:49] op_sel_hi:[1,0,1]
	v_pk_fma_f32 v[44:45], v[6:7], v[146:147], v[50:51] op_sel_hi:[1,0,1]
	v_pk_fma_f32 v[46:47], v[8:9], v[146:147], v[52:53] op_sel_hi:[1,0,1]
	v_pk_fma_f32 v[48:49], v[10:11], v[146:147], v[54:55] op_sel_hi:[1,0,1]
	v_pk_fma_f32 v[50:51], v[12:13], v[146:147], v[126:127] op_sel_hi:[1,0,1]
	v_pk_fma_f32 v[52:53], v[14:15], v[146:147], v[128:129] op_sel_hi:[1,0,1]
	v_pk_fma_f32 v[54:55], v[16:17], v[146:147], v[130:131] op_sel_hi:[1,0,1]
	v_pk_fma_f32 v[132:133], v[18:19], v[146:147], v[132:133] op_sel_hi:[1,0,1]
	v_pk_fma_f32 v[134:135], v[20:21], v[146:147], v[134:135] op_sel_hi:[1,0,1]
	v_pk_fma_f32 v[136:137], v[22:23], v[146:147], v[136:137] op_sel_hi:[1,0,1]
	v_pk_fma_f32 v[138:139], v[24:25], v[146:147], v[138:139] op_sel_hi:[1,0,1]
	v_pk_fma_f32 v[140:141], v[26:27], v[146:147], v[140:141] op_sel_hi:[1,0,1]
	v_pk_fma_f32 v[142:143], v[28:29], v[146:147], v[142:143] op_sel_hi:[1,0,1]
	v_pk_fma_f32 v[144:145], v[30:31], v[146:147], v[144:145] op_sel_hi:[1,0,1]
	v_cndmask_b32_e64 v146, v0, v1, s[0:1]
	v_mov_b32_e32 v0, s13
	v_mov_b32_e32 v1, s12
	v_cndmask_b32_e64 v0, v0, v1, s[0:1]
	v_mad_i64_i32 v[130:131], s[12:13], v0, s23, v[64:65]
	s_waitcnt vmcnt(0)
	v_cvt_scalef32_pk32_f32_fp6 v[0:31], v[32:37], 1.0
	v_readlane_b32 s12, v108, 33
	v_readlane_b32 s13, v107, 33
	v_pk_fma_f32 v[150:151], v[0:1], v[146:147], v[38:39] op_sel_hi:[1,0,1]
	v_mov_b32_e32 v1, s12
	v_mov_b32_e32 v0, s13
	v_cndmask_b32_e64 v0, v0, v1, s[0:1]
	v_mad_i64_i32 v[0:1], s[12:13], v0, s23, v[64:65]
	v_readlane_b32 s12, v108, 34
	v_readlane_b32 s13, v107, 34
	global_load_dwordx4 v[126:129], v[130:131], off
	v_pk_fma_f32 v[168:169], v[18:19], v[146:147], v[132:133] op_sel_hi:[1,0,1]
	global_load_dwordx2 v[130:131], v[130:131], off offset:16
	v_pk_fma_f32 v[170:171], v[20:21], v[146:147], v[134:135] op_sel_hi:[1,0,1]
	v_pk_fma_f32 v[172:173], v[22:23], v[146:147], v[136:137] op_sel_hi:[1,0,1]
	global_load_dwordx2 v[136:137], v[0:1], off offset:16
	global_load_dwordx4 v[132:135], v[0:1], off
	v_mov_b32_e32 v0, s13
	v_mov_b32_e32 v1, s12
	v_cndmask_b32_e64 v0, v0, v1, s[0:1]
	v_mad_i64_i32 v[0:1], s[12:13], v0, s23, v[64:65]
	v_readlane_b32 s12, v108, 35
	v_readlane_b32 s13, v107, 35
	v_pk_fma_f32 v[152:153], v[2:3], v[146:147], v[40:41] op_sel_hi:[1,0,1]
	v_mov_b32_e32 v3, s12
	v_mov_b32_e32 v2, s13
	v_cndmask_b32_e64 v2, v2, v3, s[0:1]
	v_mad_i64_i32 v[2:3], s[12:13], v2, s23, v[64:65]
	v_readlane_b32 s12, v108, 36
	v_readlane_b32 s13, v107, 36
	v_pk_fma_f32 v[154:155], v[4:5], v[146:147], v[42:43] op_sel_hi:[1,0,1]
	v_pk_fma_f32 v[156:157], v[6:7], v[146:147], v[44:45] op_sel_hi:[1,0,1]
	v_pk_fma_f32 v[158:159], v[8:9], v[146:147], v[46:47] op_sel_hi:[1,0,1]
	v_pk_fma_f32 v[160:161], v[10:11], v[146:147], v[48:49] op_sel_hi:[1,0,1]
	v_pk_fma_f32 v[162:163], v[12:13], v[146:147], v[50:51] op_sel_hi:[1,0,1]
	v_pk_fma_f32 v[164:165], v[14:15], v[146:147], v[52:53] op_sel_hi:[1,0,1]
	v_pk_fma_f32 v[166:167], v[16:17], v[146:147], v[54:55] op_sel_hi:[1,0,1]
	v_pk_fma_f32 v[174:175], v[24:25], v[146:147], v[138:139] op_sel_hi:[1,0,1]
	v_pk_fma_f32 v[176:177], v[26:27], v[146:147], v[140:141] op_sel_hi:[1,0,1]
	v_pk_fma_f32 v[178:179], v[28:29], v[146:147], v[142:143] op_sel_hi:[1,0,1]
	v_pk_fma_f32 v[180:181], v[30:31], v[146:147], v[144:145] op_sel_hi:[1,0,1]
	global_load_dwordx4 v[138:141], v[0:1], off
	global_load_dwordx2 v[142:143], v[0:1], off offset:16
	global_load_dwordx4 v[144:147], v[2:3], off
	v_mov_b32_e32 v0, s13
	v_mov_b32_e32 v1, s12
	v_cndmask_b32_e64 v0, v0, v1, s[0:1]
	v_mad_i64_i32 v[0:1], s[12:13], v0, s23, v[64:65]
	v_readlane_b32 s12, v108, 37
	v_readlane_b32 s13, v107, 37
	global_load_dwordx2 v[148:149], v[2:3], off offset:16
	global_load_dwordx4 v[50:53], v[0:1], off
	v_mov_b32_e32 v2, s13
	v_mov_b32_e32 v3, s12
	v_cndmask_b32_e64 v2, v2, v3, s[0:1]
	v_mad_i64_i32 v[2:3], s[12:13], v2, s23, v[64:65]
	v_readlane_b32 s12, v108, 38
	v_readlane_b32 s13, v107, 38
	global_load_dwordx2 v[54:55], v[0:1], off offset:16
	global_load_dwordx4 v[44:47], v[2:3], off
	v_mov_b32_e32 v0, s13
	v_mov_b32_e32 v1, s12
	v_cndmask_b32_e64 v0, v0, v1, s[0:1]
	v_mad_i64_i32 v[0:1], s[12:13], v0, s23, v[64:65]
	v_readlane_b32 s12, v108, 39
	v_readlane_b32 s13, v107, 39
	global_load_dwordx2 v[48:49], v[2:3], off offset:16
	global_load_dwordx4 v[38:41], v[0:1], off
	v_mov_b32_e32 v2, s13
	v_mov_b32_e32 v3, s12
	v_cndmask_b32_e64 v2, v2, v3, s[0:1]
	v_mad_i64_i32 v[2:3], s[12:13], v2, s23, v[64:65]
	global_load_dwordx2 v[36:37], v[2:3], off offset:16
	global_load_dwordx2 v[42:43], v[0:1], off offset:16
	global_load_dwordx4 v[32:35], v[2:3], off
	v_readlane_b32 s12, v106, 32
	v_readlane_b32 s13, v109, 32
	s_nop 0
	v_mov_b32_e32 v1, s12
	v_mov_b32_e32 v0, s13
	v_cndmask_b32_e64 v182, v0, v1, s[0:1]
	v_readlane_b32 s12, v106, 33
	v_readlane_b32 s13, v109, 33
	s_waitcnt vmcnt(14)
; DI void phase_peer_out(const Params& p, char* lds) {
;     ...
;       for (int k = 0; k < 8; ++k) {
;         const int e0 = __builtin_amdgcn_readlane(el[0], kb * 8 + k), e1 = __builtin_amdgcn_readlane(el[1], kb * 8 + k);
;         qb[k] = load6(V6 + (size_t)(hb ? e1 : e0) * 768);
;       }
; #pragma unroll
;       for (int k = 0; k < 8; ++k) {
;         const float c0 = __uint_as_float(__builtin_amdgcn_readlane(__float_as_uint(coefv[0]), kb * 8 + k)), c1 = __uint_as_float(__builtin_amdgcn_readlane(__float_as_uint(coefv[1]), kb * 8 + k));
;         const float cf = hb ? c1 : c0;
;         const f32x2 c2 = {cf, cf};
;         const v32f f = __builtin_amdgcn_cvt_scalef32_pk32_f32_fp6(qb[k], 1.0f);
; #pragma unroll
;         for (int i = 0; i < 16; ++i) o2[i] = f32x2{f[2 * i], f[2 * i + 1]} * c2 + o2[i];
	v_cvt_scalef32_pk32_f32_fp6 v[0:31], v[126:131], 1.0
	v_pk_fma_f32 v[126:127], v[0:1], v[182:183], v[150:151] op_sel_hi:[1,0,1]
	v_mov_b32_e32 v0, s13
	v_mov_b32_e32 v1, s12
	v_pk_fma_f32 v[128:129], v[2:3], v[182:183], v[152:153] op_sel_hi:[1,0,1]
	v_pk_fma_f32 v[130:131], v[4:5], v[182:183], v[154:155] op_sel_hi:[1,0,1]
	v_pk_fma_f32 v[150:151], v[6:7], v[182:183], v[156:157] op_sel_hi:[1,0,1]
	v_pk_fma_f32 v[152:153], v[8:9], v[182:183], v[158:159] op_sel_hi:[1,0,1]
	v_pk_fma_f32 v[154:155], v[10:11], v[182:183], v[160:161] op_sel_hi:[1,0,1]
	v_pk_fma_f32 v[156:157], v[12:13], v[182:183], v[162:163] op_sel_hi:[1,0,1]
	v_pk_fma_f32 v[158:159], v[14:15], v[182:183], v[164:165] op_sel_hi:[1,0,1]
	v_pk_fma_f32 v[160:161], v[16:17], v[182:183], v[166:167] op_sel_hi:[1,0,1]
	v_pk_fma_f32 v[162:163], v[18:19], v[182:183], v[168:169] op_sel_hi:[1,0,1]
	v_pk_fma_f32 v[164:165], v[20:21], v[182:183], v[170:171] op_sel_hi:[1,0,1]
	v_pk_fma_f32 v[166:167], v[22:23], v[182:183], v[172:173] op_sel_hi:[1,0,1]
	v_pk_fma_f32 v[168:169], v[24:25], v[182:183], v[174:175] op_sel_hi:[1,0,1]
	v_pk_fma_f32 v[170:171], v[26:27], v[182:183], v[176:177] op_sel_hi:[1,0,1]
	v_pk_fma_f32 v[172:173], v[28:29], v[182:183], v[178:179] op_sel_hi:[1,0,1]
	v_pk_fma_f32 v[174:175], v[30:31], v[182:183], v[180:181] op_sel_hi:[1,0,1]
	v_cndmask_b32_e64 v176, v0, v1, s[0:1]
	s_waitcnt vmcnt(12)
	v_cvt_scalef32_pk32_f32_fp6 v[0:31], v[132:137], 1.0
	v_readlane_b32 s12, v106, 34
	v_readlane_b32 s13, v109, 34
	v_pk_fma_f32 v[126:127], v[0:1], v[176:177], v[126:127] op_sel_hi:[1,0,1]
	v_mov_b32_e32 v1, s12
	v_mov_b32_e32 v0, s13
	v_pk_fma_f32 v[128:129], v[2:3], v[176:177], v[128:129] op_sel_hi:[1,0,1]
	v_pk_fma_f32 v[130:131], v[4:5], v[176:177], v[130:131] op_sel_hi:[1,0,1]
	v_pk_fma_f32 v[132:133], v[6:7], v[176:177], v[150:151] op_sel_hi:[1,0,1]
	v_pk_fma_f32 v[134:135], v[8:9], v[176:177], v[152:153] op_sel_hi:[1,0,1]
	v_pk_fma_f32 v[136:137], v[10:11], v[176:177], v[154:155] op_sel_hi:[1,0,1]
	v_pk_fma_f32 v[150:151], v[12:13], v[176:177], v[156:157] op_sel_hi:[1,0,1]
	v_pk_fma_f32 v[152:153], v[14:15], v[176:177], v[158:159] op_sel_hi:[1,0,1]
	v_pk_fma_f32 v[154:155], v[16:17], v[176:177], v[160:161] op_sel_hi:[1,0,1]
	v_pk_fma_f32 v[156:157], v[18:19], v[176:177], v[162:163] op_sel_hi:[1,0,1]
	v_pk_fma_f32 v[158:159], v[20:21], v[176:177], v[164:165] op_sel_hi:[1,0,1]
	v_pk_fma_f32 v[160:161], v[22:23], v[176:177], v[166:167] op_sel_hi:[1,0,1]
	v_pk_fma_f32 v[162:163], v[24:25], v[176:177], v[168:169] op_sel_hi:[1,0,1]
	v_pk_fma_f32 v[164:165], v[26:27], v[176:177], v[170:171] op_sel_hi:[1,0,1]
	v_pk_fma_f32 v[166:167], v[28:29], v[176:177], v[172:173] op_sel_hi:[1,0,1]
	v_pk_fma_f32 v[168:169], v[30:31], v[176:177], v[174:175] op_sel_hi:[1,0,1]
	v_cndmask_b32_e64 v170, v0, v1, s[0:1]
	s_waitcnt vmcnt(10)
	v_cvt_scalef32_pk32_f32_fp6 v[0:31], v[138:143], 1.0
	v_readlane_b32 s12, v106, 35
	v_readlane_b32 s13, v109, 35
	v_pk_fma_f32 v[126:127], v[0:1], v[170:171], v[126:127] op_sel_hi:[1,0,1]
	v_mov_b32_e32 v1, s12
	v_mov_b32_e32 v0, s13
	v_pk_fma_f32 v[128:129], v[2:3], v[170:171], v[128:129] op_sel_hi:[1,0,1]
	v_pk_fma_f32 v[130:131], v[4:5], v[170:171], v[130:131] op_sel_hi:[1,0,1]
	v_pk_fma_f32 v[132:133], v[6:7], v[170:171], v[132:133] op_sel_hi:[1,0,1]
	v_pk_fma_f32 v[134:135], v[8:9], v[170:171], v[134:135] op_sel_hi:[1,0,1]
	v_pk_fma_f32 v[136:137], v[10:11], v[170:171], v[136:137] op_sel_hi:[1,0,1]
	v_pk_fma_f32 v[138:139], v[12:13], v[170:171], v[150:151] op_sel_hi:[1,0,1]
	v_pk_fma_f32 v[140:141], v[14:15], v[170:171], v[152:153] op_sel_hi:[1,0,1]
	v_pk_fma_f32 v[142:143], v[16:17], v[170:171], v[154:155] op_sel_hi:[1,0,1]
	v_pk_fma_f32 v[150:151], v[18:19], v[170:171], v[156:157] op_sel_hi:[1,0,1]
	v_pk_fma_f32 v[152:153], v[20:21], v[170:171], v[158:159] op_sel_hi:[1,0,1]
	v_pk_fma_f32 v[154:155], v[22:23], v[170:171], v[160:161] op_sel_hi:[1,0,1]
	v_pk_fma_f32 v[156:157], v[24:25], v[170:171], v[162:163] op_sel_hi:[1,0,1]
	v_pk_fma_f32 v[158:159], v[26:27], v[170:171], v[164:165] op_sel_hi:[1,0,1]
	v_pk_fma_f32 v[160:161], v[28:29], v[170:171], v[166:167] op_sel_hi:[1,0,1]
	v_pk_fma_f32 v[162:163], v[30:31], v[170:171], v[168:169] op_sel_hi:[1,0,1]
	v_cndmask_b32_e64 v164, v0, v1, s[0:1]
	s_waitcnt vmcnt(8)
	v_cvt_scalef32_pk32_f32_fp6 v[0:31], v[144:149], 1.0
	v_readlane_b32 s12, v106, 36
	v_readlane_b32 s13, v109, 36
	v_pk_fma_f32 v[126:127], v[0:1], v[164:165], v[126:127] op_sel_hi:[1,0,1]
	v_mov_b32_e32 v1, s12
	v_mov_b32_e32 v0, s13
	v_pk_fma_f32 v[128:129], v[2:3], v[164:165], v[128:129] op_sel_hi:[1,0,1]
	v_pk_fma_f32 v[130:131], v[4:5], v[164:165], v[130:131] op_sel_hi:[1,0,1]
	v_pk_fma_f32 v[132:133], v[6:7], v[164:165], v[132:133] op_sel_hi:[1,0,1]
	v_pk_fma_f32 v[134:135], v[8:9], v[164:165], v[134:135] op_sel_hi:[1,0,1]
	v_pk_fma_f32 v[136:137], v[10:11], v[164:165], v[136:137] op_sel_hi:[1,0,1]
	v_pk_fma_f32 v[138:139], v[12:13], v[164:165], v[138:139] op_sel_hi:[1,0,1]
	v_pk_fma_f32 v[140:141], v[14:15], v[164:165], v[140:141] op_sel_hi:[1,0,1]
	v_pk_fma_f32 v[142:143], v[16:17], v[164:165], v[142:143] op_sel_hi:[1,0,1]
	v_pk_fma_f32 v[144:145], v[18:19], v[164:165], v[150:151] op_sel_hi:[1,0,1]
	v_pk_fma_f32 v[146:147], v[20:21], v[164:165], v[152:153] op_sel_hi:[1,0,1]
	v_pk_fma_f32 v[148:149], v[22:23], v[164:165], v[154:155] op_sel_hi:[1,0,1]
	v_pk_fma_f32 v[150:151], v[24:25], v[164:165], v[156:157] op_sel_hi:[1,0,1]
	v_pk_fma_f32 v[152:153], v[26:27], v[164:165], v[158:159] op_sel_hi:[1,0,1]
	v_pk_fma_f32 v[154:155], v[28:29], v[164:165], v[160:161] op_sel_hi:[1,0,1]
	v_pk_fma_f32 v[156:157], v[30:31], v[164:165], v[162:163] op_sel_hi:[1,0,1]
	v_cndmask_b32_e64 v158, v0, v1, s[0:1]
	s_waitcnt vmcnt(6)
; DI void phase_peer_out(const Params& p, char* lds) {
;     ...
;       for (int k = 0; k < 8; ++k) {
;         const int e0 = __builtin_amdgcn_readlane(el[0], kb * 8 + k), e1 = __builtin_amdgcn_readlane(el[1], kb * 8 + k);
;         qb[k] = load6(V6 + (size_t)(hb ? e1 : e0) * 768);
;       }
; #pragma unroll
;       for (int k = 0; k < 8; ++k) {
;         const float c0 = __uint_as_float(__builtin_amdgcn_readlane(__float_as_uint(coefv[0]), kb * 8 + k)), c1 = __uint_as_float(__builtin_amdgcn_readlane(__float_as_uint(coefv[1]), kb * 8 + k));
;         const float cf = hb ? c1 : c0;
;         const f32x2 c2 = {cf, cf};
;         const v32f f = __builtin_amdgcn_cvt_scalef32_pk32_f32_fp6(qb[k], 1.0f);
; #pragma unroll
;         for (int i = 0; i < 16; ++i) o2[i] = f32x2{f[2 * i], f[2 * i + 1]} * c2 + o2[i];
	v_cvt_scalef32_pk32_f32_fp6 v[0:31], v[50:55], 1.0
	v_readlane_b32 s12, v106, 37
	v_readlane_b32 s13, v109, 37
	v_pk_fma_f32 v[50:51], v[0:1], v[158:159], v[126:127] op_sel_hi:[1,0,1]
	v_mov_b32_e32 v1, s12
	v_mov_b32_e32 v0, s13
	v_pk_fma_f32 v[52:53], v[2:3], v[158:159], v[128:129] op_sel_hi:[1,0,1]
	v_pk_fma_f32 v[54:55], v[4:5], v[158:159], v[130:131] op_sel_hi:[1,0,1]
	v_pk_fma_f32 v[126:127], v[6:7], v[158:159], v[132:133] op_sel_hi:[1,0,1]
	v_pk_fma_f32 v[128:129], v[8:9], v[158:159], v[134:135] op_sel_hi:[1,0,1]
	v_pk_fma_f32 v[130:131], v[10:11], v[158:159], v[136:137] op_sel_hi:[1,0,1]
	v_pk_fma_f32 v[132:133], v[12:13], v[158:159], v[138:139] op_sel_hi:[1,0,1]
	v_pk_fma_f32 v[134:135], v[14:15], v[158:159], v[140:141] op_sel_hi:[1,0,1]
	v_pk_fma_f32 v[136:137], v[16:17], v[158:159], v[142:143] op_sel_hi:[1,0,1]
	v_pk_fma_f32 v[138:139], v[18:19], v[158:159], v[144:145] op_sel_hi:[1,0,1]
	v_pk_fma_f32 v[140:141], v[20:21], v[158:159], v[146:147] op_sel_hi:[1,0,1]
	v_pk_fma_f32 v[142:143], v[22:23], v[158:159], v[148:149] op_sel_hi:[1,0,1]
	v_pk_fma_f32 v[144:145], v[24:25], v[158:159], v[150:151] op_sel_hi:[1,0,1]
	v_pk_fma_f32 v[146:147], v[26:27], v[158:159], v[152:153] op_sel_hi:[1,0,1]
	v_pk_fma_f32 v[148:149], v[28:29], v[158:159], v[154:155] op_sel_hi:[1,0,1]
	v_pk_fma_f32 v[150:151], v[30:31], v[158:159], v[156:157] op_sel_hi:[1,0,1]
	v_cndmask_b32_e64 v152, v0, v1, s[0:1]
	s_waitcnt vmcnt(4)
	v_cvt_scalef32_pk32_f32_fp6 v[0:31], v[44:49], 1.0
	v_readlane_b32 s12, v106, 38
	v_readlane_b32 s13, v109, 38
	v_pk_fma_f32 v[44:45], v[0:1], v[152:153], v[50:51] op_sel_hi:[1,0,1]
	v_mov_b32_e32 v1, s12
	v_mov_b32_e32 v0, s13
	v_pk_fma_f32 v[46:47], v[2:3], v[152:153], v[52:53] op_sel_hi:[1,0,1]
	v_pk_fma_f32 v[48:49], v[4:5], v[152:153], v[54:55] op_sel_hi:[1,0,1]
	v_pk_fma_f32 v[50:51], v[6:7], v[152:153], v[126:127] op_sel_hi:[1,0,1]
	v_pk_fma_f32 v[52:53], v[8:9], v[152:153], v[128:129] op_sel_hi:[1,0,1]
	v_pk_fma_f32 v[54:55], v[10:11], v[152:153], v[130:131] op_sel_hi:[1,0,1]
	v_pk_fma_f32 v[126:127], v[12:13], v[152:153], v[132:133] op_sel_hi:[1,0,1]
	v_pk_fma_f32 v[128:129], v[14:15], v[152:153], v[134:135] op_sel_hi:[1,0,1]
	v_pk_fma_f32 v[130:131], v[16:17], v[152:153], v[136:137] op_sel_hi:[1,0,1]
	v_pk_fma_f32 v[132:133], v[18:19], v[152:153], v[138:139] op_sel_hi:[1,0,1]
	v_pk_fma_f32 v[134:135], v[20:21], v[152:153], v[140:141] op_sel_hi:[1,0,1]
	v_pk_fma_f32 v[136:137], v[22:23], v[152:153], v[142:143] op_sel_hi:[1,0,1]
	v_pk_fma_f32 v[138:139], v[24:25], v[152:153], v[144:145] op_sel_hi:[1,0,1]
	v_pk_fma_f32 v[140:141], v[26:27], v[152:153], v[146:147] op_sel_hi:[1,0,1]
	v_pk_fma_f32 v[142:143], v[28:29], v[152:153], v[148:149] op_sel_hi:[1,0,1]
	v_pk_fma_f32 v[144:145], v[30:31], v[152:153], v[150:151] op_sel_hi:[1,0,1]
	v_cndmask_b32_e64 v146, v0, v1, s[0:1]
	s_waitcnt vmcnt(1)
	v_cvt_scalef32_pk32_f32_fp6 v[0:31], v[38:43], 1.0
	v_readlane_b32 s12, v106, 39
	v_readlane_b32 s13, v109, 39
	v_pk_fma_f32 v[38:39], v[0:1], v[146:147], v[44:45] op_sel_hi:[1,0,1]
	v_mov_b32_e32 v1, s12
	v_mov_b32_e32 v0, s13
	v_readlane_b32 s12, v108, 40
	v_readlane_b32 s13, v107, 40
	v_pk_fma_f32 v[40:41], v[2:3], v[146:147], v[46:47] op_sel_hi:[1,0,1]
	v_pk_fma_f32 v[42:43], v[4:5], v[146:147], v[48:49] op_sel_hi:[1,0,1]
	v_pk_fma_f32 v[44:45], v[6:7], v[146:147], v[50:51] op_sel_hi:[1,0,1]
	v_pk_fma_f32 v[46:47], v[8:9], v[146:147], v[52:53] op_sel_hi:[1,0,1]
	v_pk_fma_f32 v[48:49], v[10:11], v[146:147], v[54:55] op_sel_hi:[1,0,1]
	v_pk_fma_f32 v[50:51], v[12:13], v[146:147], v[126:127] op_sel_hi:[1,0,1]
	v_pk_fma_f32 v[52:53], v[14:15], v[146:147], v[128:129] op_sel_hi:[1,0,1]
	v_pk_fma_f32 v[54:55], v[16:17], v[146:147], v[130:131] op_sel_hi:[1,0,1]
	v_pk_fma_f32 v[132:133], v[18:19], v[146:147], v[132:133] op_sel_hi:[1,0,1]
	v_pk_fma_f32 v[134:135], v[20:21], v[146:147], v[134:135] op_sel_hi:[1,0,1]
	v_pk_fma_f32 v[136:137], v[22:23], v[146:147], v[136:137] op_sel_hi:[1,0,1]
	v_pk_fma_f32 v[138:139], v[24:25], v[146:147], v[138:139] op_sel_hi:[1,0,1]
	v_pk_fma_f32 v[140:141], v[26:27], v[146:147], v[140:141] op_sel_hi:[1,0,1]
	v_pk_fma_f32 v[142:143], v[28:29], v[146:147], v[142:143] op_sel_hi:[1,0,1]
	v_pk_fma_f32 v[144:145], v[30:31], v[146:147], v[144:145] op_sel_hi:[1,0,1]
	v_cndmask_b32_e64 v146, v0, v1, s[0:1]
	v_mov_b32_e32 v0, s13
	v_mov_b32_e32 v1, s12
	v_cndmask_b32_e64 v0, v0, v1, s[0:1]
	v_mad_i64_i32 v[130:131], s[12:13], v0, s23, v[64:65]
	s_waitcnt vmcnt(0)
; DI void phase_peer_out(const Params& p, char* lds) {
;     ...
;     for (int kb = 0; kb < 8; ++kb) {
;       v6u qb[8];
; #pragma unroll
;       for (int k = 0; k < 8; ++k) {
;         const int e0 = __builtin_amdgcn_readlane(el[0], kb * 8 + k), e1 = __builtin_amdgcn_readlane(el[1], kb * 8 + k);
;         qb[k] = load6(V6 + (size_t)(hb ? e1 : e0) * 768);
;       }
; #pragma unroll
;       for (int k = 0; k < 8; ++k) {
;         const float c0 = __uint_as_float(__builtin_amdgcn_readlane(__float_as_uint(coefv[0]), kb * 8 + k)), c1 = __uint_as_float(__builtin_amdgcn_readlane(__float_as_uint(coefv[1]), kb * 8 + k));
;         const float cf = hb ? c1 : c0;
;         const f32x2 c2 = {cf, cf};
;         const v32f f = __builtin_amdgcn_cvt_scalef32_pk32_f32_fp6(qb[k], 1.0f);
; #pragma unroll
;         for (int i = 0; i < 16; ++i) o2[i] = f32x2{f[2 * i], f[2 * i + 1]} * c2 + o2[i];
	v_cvt_scalef32_pk32_f32_fp6 v[0:31], v[32:37], 1.0
	v_readlane_b32 s12, v108, 41
	v_readlane_b32 s13, v107, 41
	v_pk_fma_f32 v[150:151], v[0:1], v[146:147], v[38:39] op_sel_hi:[1,0,1]
	v_mov_b32_e32 v1, s12
	v_mov_b32_e32 v0, s13
	v_cndmask_b32_e64 v0, v0, v1, s[0:1]
	v_mad_i64_i32 v[0:1], s[12:13], v0, s23, v[64:65]
	v_readlane_b32 s12, v108, 42
	v_readlane_b32 s13, v107, 42
	global_load_dwordx4 v[126:129], v[130:131], off
	v_pk_fma_f32 v[168:169], v[18:19], v[146:147], v[132:133] op_sel_hi:[1,0,1]
	global_load_dwordx2 v[130:131], v[130:131], off offset:16
	v_pk_fma_f32 v[170:171], v[20:21], v[146:147], v[134:135] op_sel_hi:[1,0,1]
	v_pk_fma_f32 v[172:173], v[22:23], v[146:147], v[136:137] op_sel_hi:[1,0,1]
	global_load_dwordx2 v[136:137], v[0:1], off offset:16
	global_load_dwordx4 v[132:135], v[0:1], off
	v_mov_b32_e32 v0, s13
	v_mov_b32_e32 v1, s12
	v_cndmask_b32_e64 v0, v0, v1, s[0:1]
	v_mad_i64_i32 v[0:1], s[12:13], v0, s23, v[64:65]
	v_readlane_b32 s12, v108, 43
	v_readlane_b32 s13, v107, 43
	v_pk_fma_f32 v[152:153], v[2:3], v[146:147], v[40:41] op_sel_hi:[1,0,1]
	v_mov_b32_e32 v3, s12
	v_mov_b32_e32 v2, s13
	v_cndmask_b32_e64 v2, v2, v3, s[0:1]
	v_mad_i64_i32 v[2:3], s[12:13], v2, s23, v[64:65]
	v_readlane_b32 s12, v108, 44
	v_readlane_b32 s13, v107, 44
	v_pk_fma_f32 v[154:155], v[4:5], v[146:147], v[42:43] op_sel_hi:[1,0,1]
	v_pk_fma_f32 v[156:157], v[6:7], v[146:147], v[44:45] op_sel_hi:[1,0,1]
	v_pk_fma_f32 v[158:159], v[8:9], v[146:147], v[46:47] op_sel_hi:[1,0,1]
	v_pk_fma_f32 v[160:161], v[10:11], v[146:147], v[48:49] op_sel_hi:[1,0,1]
	v_pk_fma_f32 v[162:163], v[12:13], v[146:147], v[50:51] op_sel_hi:[1,0,1]
	v_pk_fma_f32 v[164:165], v[14:15], v[146:147], v[52:53] op_sel_hi:[1,0,1]
	v_pk_fma_f32 v[166:167], v[16:17], v[146:147], v[54:55] op_sel_hi:[1,0,1]
	v_pk_fma_f32 v[174:175], v[24:25], v[146:147], v[138:139] op_sel_hi:[1,0,1]
	v_pk_fma_f32 v[176:177], v[26:27], v[146:147], v[140:141] op_sel_hi:[1,0,1]
	v_pk_fma_f32 v[178:179], v[28:29], v[146:147], v[142:143] op_sel_hi:[1,0,1]
	v_pk_fma_f32 v[180:181], v[30:31], v[146:147], v[144:145] op_sel_hi:[1,0,1]
	global_load_dwordx4 v[138:141], v[0:1], off
	global_load_dwordx2 v[142:143], v[0:1], off offset:16
	global_load_dwordx4 v[144:147], v[2:3], off
	v_mov_b32_e32 v0, s13
	v_mov_b32_e32 v1, s12
	v_cndmask_b32_e64 v0, v0, v1, s[0:1]
	v_mad_i64_i32 v[0:1], s[12:13], v0, s23, v[64:65]
	v_readlane_b32 s12, v108, 45
	v_readlane_b32 s13, v107, 45
	global_load_dwordx2 v[148:149], v[2:3], off offset:16
	global_load_dwordx4 v[50:53], v[0:1], off
	v_mov_b32_e32 v2, s13
	v_mov_b32_e32 v3, s12
	v_cndmask_b32_e64 v2, v2, v3, s[0:1]
	v_mad_i64_i32 v[2:3], s[12:13], v2, s23, v[64:65]
	v_readlane_b32 s12, v108, 46
	v_readlane_b32 s13, v107, 46
	global_load_dwordx2 v[54:55], v[0:1], off offset:16
	global_load_dwordx4 v[44:47], v[2:3], off
	v_mov_b32_e32 v0, s13
	v_mov_b32_e32 v1, s12
	v_cndmask_b32_e64 v0, v0, v1, s[0:1]
	v_mad_i64_i32 v[0:1], s[12:13], v0, s23, v[64:65]
	v_readlane_b32 s12, v108, 47
	v_readlane_b32 s13, v107, 47
	global_load_dwordx2 v[48:49], v[2:3], off offset:16
	global_load_dwordx4 v[38:41], v[0:1], off
	v_mov_b32_e32 v2, s13
	v_mov_b32_e32 v3, s12
	v_cndmask_b32_e64 v2, v2, v3, s[0:1]
	v_mad_i64_i32 v[2:3], s[12:13], v2, s23, v[64:65]
	global_load_dwordx2 v[36:37], v[2:3], off offset:16
	global_load_dwordx2 v[42:43], v[0:1], off offset:16
	global_load_dwordx4 v[32:35], v[2:3], off
	v_readlane_b32 s12, v106, 40
	v_readlane_b32 s13, v109, 40
	s_nop 0
	v_mov_b32_e32 v1, s12
	v_mov_b32_e32 v0, s13
	v_cndmask_b32_e64 v182, v0, v1, s[0:1]
	v_readlane_b32 s12, v106, 41
	v_readlane_b32 s13, v109, 41
	s_waitcnt vmcnt(14)
	v_cvt_scalef32_pk32_f32_fp6 v[0:31], v[126:131], 1.0
	v_pk_fma_f32 v[126:127], v[0:1], v[182:183], v[150:151] op_sel_hi:[1,0,1]
	v_mov_b32_e32 v0, s13
	v_mov_b32_e32 v1, s12
	v_pk_fma_f32 v[128:129], v[2:3], v[182:183], v[152:153] op_sel_hi:[1,0,1]
	v_pk_fma_f32 v[130:131], v[4:5], v[182:183], v[154:155] op_sel_hi:[1,0,1]
	v_pk_fma_f32 v[150:151], v[6:7], v[182:183], v[156:157] op_sel_hi:[1,0,1]
	v_pk_fma_f32 v[152:153], v[8:9], v[182:183], v[158:159] op_sel_hi:[1,0,1]
	v_pk_fma_f32 v[154:155], v[10:11], v[182:183], v[160:161] op_sel_hi:[1,0,1]
	v_pk_fma_f32 v[156:157], v[12:13], v[182:183], v[162:163] op_sel_hi:[1,0,1]
	v_pk_fma_f32 v[158:159], v[14:15], v[182:183], v[164:165] op_sel_hi:[1,0,1]
	v_pk_fma_f32 v[160:161], v[16:17], v[182:183], v[166:167] op_sel_hi:[1,0,1]
	v_pk_fma_f32 v[162:163], v[18:19], v[182:183], v[168:169] op_sel_hi:[1,0,1]
	v_pk_fma_f32 v[164:165], v[20:21], v[182:183], v[170:171] op_sel_hi:[1,0,1]
	v_pk_fma_f32 v[166:167], v[22:23], v[182:183], v[172:173] op_sel_hi:[1,0,1]
	v_pk_fma_f32 v[168:169], v[24:25], v[182:183], v[174:175] op_sel_hi:[1,0,1]
	v_pk_fma_f32 v[170:171], v[26:27], v[182:183], v[176:177] op_sel_hi:[1,0,1]
	v_pk_fma_f32 v[172:173], v[28:29], v[182:183], v[178:179] op_sel_hi:[1,0,1]
	v_pk_fma_f32 v[174:175], v[30:31], v[182:183], v[180:181] op_sel_hi:[1,0,1]
	v_cndmask_b32_e64 v176, v0, v1, s[0:1]
	s_waitcnt vmcnt(12)
; DI void phase_peer_out(const Params& p, char* lds) {
;     ...
;       for (int k = 0; k < 8; ++k) {
;         const int e0 = __builtin_amdgcn_readlane(el[0], kb * 8 + k), e1 = __builtin_amdgcn_readlane(el[1], kb * 8 + k);
;         qb[k] = load6(V6 + (size_t)(hb ? e1 : e0) * 768);
;       }
; #pragma unroll
;       for (int k = 0; k < 8; ++k) {
;         const float c0 = __uint_as_float(__builtin_amdgcn_readlane(__float_as_uint(coefv[0]), kb * 8 + k)), c1 = __uint_as_float(__builtin_amdgcn_readlane(__float_as_uint(coefv[1]), kb * 8 + k));
;         const float cf = hb ? c1 : c0;
;         const f32x2 c2 = {cf, cf};
;         const v32f f = __builtin_amdgcn_cvt_scalef32_pk32_f32_fp6(qb[k], 1.0f);
; #pragma unroll
;         for (int i = 0; i < 16; ++i) o2[i] = f32x2{f[2 * i], f[2 * i + 1]} * c2 + o2[i];
	v_cvt_scalef32_pk32_f32_fp6 v[0:31], v[132:137], 1.0
	v_readlane_b32 s12, v106, 42
	v_readlane_b32 s13, v109, 42
	v_pk_fma_f32 v[126:127], v[0:1], v[176:177], v[126:127] op_sel_hi:[1,0,1]
	v_mov_b32_e32 v1, s12
	v_mov_b32_e32 v0, s13
	v_pk_fma_f32 v[128:129], v[2:3], v[176:177], v[128:129] op_sel_hi:[1,0,1]
	v_pk_fma_f32 v[130:131], v[4:5], v[176:177], v[130:131] op_sel_hi:[1,0,1]
	v_pk_fma_f32 v[132:133], v[6:7], v[176:177], v[150:151] op_sel_hi:[1,0,1]
	v_pk_fma_f32 v[134:135], v[8:9], v[176:177], v[152:153] op_sel_hi:[1,0,1]
	v_pk_fma_f32 v[136:137], v[10:11], v[176:177], v[154:155] op_sel_hi:[1,0,1]
	v_pk_fma_f32 v[150:151], v[12:13], v[176:177], v[156:157] op_sel_hi:[1,0,1]
	v_pk_fma_f32 v[152:153], v[14:15], v[176:177], v[158:159] op_sel_hi:[1,0,1]
	v_pk_fma_f32 v[154:155], v[16:17], v[176:177], v[160:161] op_sel_hi:[1,0,1]
	v_pk_fma_f32 v[156:157], v[18:19], v[176:177], v[162:163] op_sel_hi:[1,0,1]
	v_pk_fma_f32 v[158:159], v[20:21], v[176:177], v[164:165] op_sel_hi:[1,0,1]
	v_pk_fma_f32 v[160:161], v[22:23], v[176:177], v[166:167] op_sel_hi:[1,0,1]
	v_pk_fma_f32 v[162:163], v[24:25], v[176:177], v[168:169] op_sel_hi:[1,0,1]
	v_pk_fma_f32 v[164:165], v[26:27], v[176:177], v[170:171] op_sel_hi:[1,0,1]
	v_pk_fma_f32 v[166:167], v[28:29], v[176:177], v[172:173] op_sel_hi:[1,0,1]
	v_pk_fma_f32 v[168:169], v[30:31], v[176:177], v[174:175] op_sel_hi:[1,0,1]
	v_cndmask_b32_e64 v170, v0, v1, s[0:1]
	s_waitcnt vmcnt(10)
	v_cvt_scalef32_pk32_f32_fp6 v[0:31], v[138:143], 1.0
	v_readlane_b32 s12, v106, 43
	v_readlane_b32 s13, v109, 43
	v_pk_fma_f32 v[126:127], v[0:1], v[170:171], v[126:127] op_sel_hi:[1,0,1]
	v_mov_b32_e32 v1, s12
	v_mov_b32_e32 v0, s13
	v_pk_fma_f32 v[128:129], v[2:3], v[170:171], v[128:129] op_sel_hi:[1,0,1]
	v_pk_fma_f32 v[130:131], v[4:5], v[170:171], v[130:131] op_sel_hi:[1,0,1]
	v_pk_fma_f32 v[132:133], v[6:7], v[170:171], v[132:133] op_sel_hi:[1,0,1]
	v_pk_fma_f32 v[134:135], v[8:9], v[170:171], v[134:135] op_sel_hi:[1,0,1]
	v_pk_fma_f32 v[136:137], v[10:11], v[170:171], v[136:137] op_sel_hi:[1,0,1]
	v_pk_fma_f32 v[138:139], v[12:13], v[170:171], v[150:151] op_sel_hi:[1,0,1]
	v_pk_fma_f32 v[140:141], v[14:15], v[170:171], v[152:153] op_sel_hi:[1,0,1]
	v_pk_fma_f32 v[142:143], v[16:17], v[170:171], v[154:155] op_sel_hi:[1,0,1]
	v_pk_fma_f32 v[150:151], v[18:19], v[170:171], v[156:157] op_sel_hi:[1,0,1]
	v_pk_fma_f32 v[152:153], v[20:21], v[170:171], v[158:159] op_sel_hi:[1,0,1]
	v_pk_fma_f32 v[154:155], v[22:23], v[170:171], v[160:161] op_sel_hi:[1,0,1]
	v_pk_fma_f32 v[156:157], v[24:25], v[170:171], v[162:163] op_sel_hi:[1,0,1]
	v_pk_fma_f32 v[158:159], v[26:27], v[170:171], v[164:165] op_sel_hi:[1,0,1]
	v_pk_fma_f32 v[160:161], v[28:29], v[170:171], v[166:167] op_sel_hi:[1,0,1]
	v_pk_fma_f32 v[162:163], v[30:31], v[170:171], v[168:169] op_sel_hi:[1,0,1]
	v_cndmask_b32_e64 v164, v0, v1, s[0:1]
	s_waitcnt vmcnt(8)
	v_cvt_scalef32_pk32_f32_fp6 v[0:31], v[144:149], 1.0
	v_readlane_b32 s12, v106, 44
	v_readlane_b32 s13, v109, 44
	v_pk_fma_f32 v[126:127], v[0:1], v[164:165], v[126:127] op_sel_hi:[1,0,1]
	v_mov_b32_e32 v1, s12
	v_mov_b32_e32 v0, s13
	v_pk_fma_f32 v[128:129], v[2:3], v[164:165], v[128:129] op_sel_hi:[1,0,1]
	v_pk_fma_f32 v[130:131], v[4:5], v[164:165], v[130:131] op_sel_hi:[1,0,1]
	v_pk_fma_f32 v[132:133], v[6:7], v[164:165], v[132:133] op_sel_hi:[1,0,1]
	v_pk_fma_f32 v[134:135], v[8:9], v[164:165], v[134:135] op_sel_hi:[1,0,1]
	v_pk_fma_f32 v[136:137], v[10:11], v[164:165], v[136:137] op_sel_hi:[1,0,1]
	v_pk_fma_f32 v[138:139], v[12:13], v[164:165], v[138:139] op_sel_hi:[1,0,1]
	v_pk_fma_f32 v[140:141], v[14:15], v[164:165], v[140:141] op_sel_hi:[1,0,1]
	v_pk_fma_f32 v[142:143], v[16:17], v[164:165], v[142:143] op_sel_hi:[1,0,1]
	v_pk_fma_f32 v[144:145], v[18:19], v[164:165], v[150:151] op_sel_hi:[1,0,1]
	v_pk_fma_f32 v[146:147], v[20:21], v[164:165], v[152:153] op_sel_hi:[1,0,1]
	v_pk_fma_f32 v[148:149], v[22:23], v[164:165], v[154:155] op_sel_hi:[1,0,1]
	v_pk_fma_f32 v[150:151], v[24:25], v[164:165], v[156:157] op_sel_hi:[1,0,1]
	v_pk_fma_f32 v[152:153], v[26:27], v[164:165], v[158:159] op_sel_hi:[1,0,1]
	v_pk_fma_f32 v[154:155], v[28:29], v[164:165], v[160:161] op_sel_hi:[1,0,1]
	v_pk_fma_f32 v[156:157], v[30:31], v[164:165], v[162:163] op_sel_hi:[1,0,1]
	v_cndmask_b32_e64 v158, v0, v1, s[0:1]
	s_waitcnt vmcnt(6)
	v_cvt_scalef32_pk32_f32_fp6 v[0:31], v[50:55], 1.0
	v_readlane_b32 s12, v106, 45
	v_readlane_b32 s13, v109, 45
	v_pk_fma_f32 v[50:51], v[0:1], v[158:159], v[126:127] op_sel_hi:[1,0,1]
	v_mov_b32_e32 v1, s12
	v_mov_b32_e32 v0, s13
	v_pk_fma_f32 v[52:53], v[2:3], v[158:159], v[128:129] op_sel_hi:[1,0,1]
	v_pk_fma_f32 v[54:55], v[4:5], v[158:159], v[130:131] op_sel_hi:[1,0,1]
	v_pk_fma_f32 v[126:127], v[6:7], v[158:159], v[132:133] op_sel_hi:[1,0,1]
	v_pk_fma_f32 v[128:129], v[8:9], v[158:159], v[134:135] op_sel_hi:[1,0,1]
	v_pk_fma_f32 v[130:131], v[10:11], v[158:159], v[136:137] op_sel_hi:[1,0,1]
	v_pk_fma_f32 v[132:133], v[12:13], v[158:159], v[138:139] op_sel_hi:[1,0,1]
	v_pk_fma_f32 v[134:135], v[14:15], v[158:159], v[140:141] op_sel_hi:[1,0,1]
	v_pk_fma_f32 v[136:137], v[16:17], v[158:159], v[142:143] op_sel_hi:[1,0,1]
	v_pk_fma_f32 v[138:139], v[18:19], v[158:159], v[144:145] op_sel_hi:[1,0,1]
	v_pk_fma_f32 v[140:141], v[20:21], v[158:159], v[146:147] op_sel_hi:[1,0,1]
	v_pk_fma_f32 v[142:143], v[22:23], v[158:159], v[148:149] op_sel_hi:[1,0,1]
	v_pk_fma_f32 v[144:145], v[24:25], v[158:159], v[150:151] op_sel_hi:[1,0,1]
	v_pk_fma_f32 v[146:147], v[26:27], v[158:159], v[152:153] op_sel_hi:[1,0,1]
	v_pk_fma_f32 v[148:149], v[28:29], v[158:159], v[154:155] op_sel_hi:[1,0,1]
	v_pk_fma_f32 v[150:151], v[30:31], v[158:159], v[156:157] op_sel_hi:[1,0,1]
	v_cndmask_b32_e64 v152, v0, v1, s[0:1]
	s_waitcnt vmcnt(4)
; DI void phase_peer_out(const Params& p, char* lds) {
;     ...
;     for (int kb = 0; kb < 8; ++kb) {
;       v6u qb[8];
; #pragma unroll
;       for (int k = 0; k < 8; ++k) {
;         const int e0 = __builtin_amdgcn_readlane(el[0], kb * 8 + k), e1 = __builtin_amdgcn_readlane(el[1], kb * 8 + k);
;         qb[k] = load6(V6 + (size_t)(hb ? e1 : e0) * 768);
;       }
; #pragma unroll
;       for (int k = 0; k < 8; ++k) {
;         const float c0 = __uint_as_float(__builtin_amdgcn_readlane(__float_as_uint(coefv[0]), kb * 8 + k)), c1 = __uint_as_float(__builtin_amdgcn_readlane(__float_as_uint(coefv[1]), kb * 8 + k));
;         const float cf = hb ? c1 : c0;
;         const f32x2 c2 = {cf, cf};
;         const v32f f = __builtin_amdgcn_cvt_scalef32_pk32_f32_fp6(qb[k], 1.0f);
; #pragma unroll
;         for (int i = 0; i < 16; ++i) o2[i] = f32x2{f[2 * i], f[2 * i + 1]} * c2 + o2[i];
	v_cvt_scalef32_pk32_f32_fp6 v[0:31], v[44:49], 1.0
	v_readlane_b32 s12, v106, 46
	v_readlane_b32 s13, v109, 46
	v_pk_fma_f32 v[44:45], v[0:1], v[152:153], v[50:51] op_sel_hi:[1,0,1]
	v_mov_b32_e32 v1, s12
	v_mov_b32_e32 v0, s13
	v_pk_fma_f32 v[46:47], v[2:3], v[152:153], v[52:53] op_sel_hi:[1,0,1]
	v_pk_fma_f32 v[48:49], v[4:5], v[152:153], v[54:55] op_sel_hi:[1,0,1]
	v_pk_fma_f32 v[50:51], v[6:7], v[152:153], v[126:127] op_sel_hi:[1,0,1]
	v_pk_fma_f32 v[52:53], v[8:9], v[152:153], v[128:129] op_sel_hi:[1,0,1]
	v_pk_fma_f32 v[54:55], v[10:11], v[152:153], v[130:131] op_sel_hi:[1,0,1]
	v_pk_fma_f32 v[126:127], v[12:13], v[152:153], v[132:133] op_sel_hi:[1,0,1]
	v_pk_fma_f32 v[128:129], v[14:15], v[152:153], v[134:135] op_sel_hi:[1,0,1]
	v_pk_fma_f32 v[130:131], v[16:17], v[152:153], v[136:137] op_sel_hi:[1,0,1]
	v_pk_fma_f32 v[132:133], v[18:19], v[152:153], v[138:139] op_sel_hi:[1,0,1]
	v_pk_fma_f32 v[134:135], v[20:21], v[152:153], v[140:141] op_sel_hi:[1,0,1]
	v_pk_fma_f32 v[136:137], v[22:23], v[152:153], v[142:143] op_sel_hi:[1,0,1]
	v_pk_fma_f32 v[138:139], v[24:25], v[152:153], v[144:145] op_sel_hi:[1,0,1]
	v_pk_fma_f32 v[140:141], v[26:27], v[152:153], v[146:147] op_sel_hi:[1,0,1]
	v_pk_fma_f32 v[142:143], v[28:29], v[152:153], v[148:149] op_sel_hi:[1,0,1]
	v_pk_fma_f32 v[144:145], v[30:31], v[152:153], v[150:151] op_sel_hi:[1,0,1]
	v_cndmask_b32_e64 v146, v0, v1, s[0:1]
	s_waitcnt vmcnt(1)
	v_cvt_scalef32_pk32_f32_fp6 v[0:31], v[38:43], 1.0
	v_readlane_b32 s12, v106, 47
	v_readlane_b32 s13, v109, 47
	v_pk_fma_f32 v[38:39], v[0:1], v[146:147], v[44:45] op_sel_hi:[1,0,1]
	v_mov_b32_e32 v1, s12
	v_mov_b32_e32 v0, s13
	v_readlane_b32 s12, v108, 48
	v_readlane_b32 s13, v107, 48
	v_pk_fma_f32 v[40:41], v[2:3], v[146:147], v[46:47] op_sel_hi:[1,0,1]
	v_pk_fma_f32 v[42:43], v[4:5], v[146:147], v[48:49] op_sel_hi:[1,0,1]
	v_pk_fma_f32 v[44:45], v[6:7], v[146:147], v[50:51] op_sel_hi:[1,0,1]
	v_pk_fma_f32 v[46:47], v[8:9], v[146:147], v[52:53] op_sel_hi:[1,0,1]
	v_pk_fma_f32 v[48:49], v[10:11], v[146:147], v[54:55] op_sel_hi:[1,0,1]
	v_pk_fma_f32 v[50:51], v[12:13], v[146:147], v[126:127] op_sel_hi:[1,0,1]
	v_pk_fma_f32 v[52:53], v[14:15], v[146:147], v[128:129] op_sel_hi:[1,0,1]
	v_pk_fma_f32 v[54:55], v[16:17], v[146:147], v[130:131] op_sel_hi:[1,0,1]
	v_pk_fma_f32 v[132:133], v[18:19], v[146:147], v[132:133] op_sel_hi:[1,0,1]
	v_pk_fma_f32 v[134:135], v[20:21], v[146:147], v[134:135] op_sel_hi:[1,0,1]
	v_pk_fma_f32 v[136:137], v[22:23], v[146:147], v[136:137] op_sel_hi:[1,0,1]
	v_pk_fma_f32 v[138:139], v[24:25], v[146:147], v[138:139] op_sel_hi:[1,0,1]
	v_pk_fma_f32 v[140:141], v[26:27], v[146:147], v[140:141] op_sel_hi:[1,0,1]
	v_pk_fma_f32 v[142:143], v[28:29], v[146:147], v[142:143] op_sel_hi:[1,0,1]
	v_pk_fma_f32 v[144:145], v[30:31], v[146:147], v[144:145] op_sel_hi:[1,0,1]
	v_cndmask_b32_e64 v146, v0, v1, s[0:1]
	v_mov_b32_e32 v0, s13
	v_mov_b32_e32 v1, s12
	v_cndmask_b32_e64 v0, v0, v1, s[0:1]
	v_mad_i64_i32 v[130:131], s[12:13], v0, s23, v[64:65]
	s_waitcnt vmcnt(0)
	v_cvt_scalef32_pk32_f32_fp6 v[0:31], v[32:37], 1.0
	v_readlane_b32 s12, v108, 49
	v_readlane_b32 s13, v107, 49
	v_pk_fma_f32 v[150:151], v[0:1], v[146:147], v[38:39] op_sel_hi:[1,0,1]
	v_mov_b32_e32 v1, s12
	v_mov_b32_e32 v0, s13
	v_cndmask_b32_e64 v0, v0, v1, s[0:1]
	v_mad_i64_i32 v[0:1], s[12:13], v0, s23, v[64:65]
	v_readlane_b32 s12, v108, 50
	v_readlane_b32 s13, v107, 50
	global_load_dwordx4 v[126:129], v[130:131], off
	v_pk_fma_f32 v[168:169], v[18:19], v[146:147], v[132:133] op_sel_hi:[1,0,1]
	global_load_dwordx2 v[130:131], v[130:131], off offset:16
	v_pk_fma_f32 v[170:171], v[20:21], v[146:147], v[134:135] op_sel_hi:[1,0,1]
	v_pk_fma_f32 v[172:173], v[22:23], v[146:147], v[136:137] op_sel_hi:[1,0,1]
	global_load_dwordx2 v[136:137], v[0:1], off offset:16
	global_load_dwordx4 v[132:135], v[0:1], off
	v_mov_b32_e32 v0, s13
	v_mov_b32_e32 v1, s12
	v_cndmask_b32_e64 v0, v0, v1, s[0:1]
	v_mad_i64_i32 v[0:1], s[12:13], v0, s23, v[64:65]
	v_readlane_b32 s12, v108, 51
	v_readlane_b32 s13, v107, 51
	v_pk_fma_f32 v[152:153], v[2:3], v[146:147], v[40:41] op_sel_hi:[1,0,1]
	v_mov_b32_e32 v3, s12
	v_mov_b32_e32 v2, s13
	v_cndmask_b32_e64 v2, v2, v3, s[0:1]
	v_mad_i64_i32 v[2:3], s[12:13], v2, s23, v[64:65]
	v_readlane_b32 s12, v108, 52
	v_readlane_b32 s13, v107, 52
	v_pk_fma_f32 v[154:155], v[4:5], v[146:147], v[42:43] op_sel_hi:[1,0,1]
	v_pk_fma_f32 v[156:157], v[6:7], v[146:147], v[44:45] op_sel_hi:[1,0,1]
	v_pk_fma_f32 v[158:159], v[8:9], v[146:147], v[46:47] op_sel_hi:[1,0,1]
	v_pk_fma_f32 v[160:161], v[10:11], v[146:147], v[48:49] op_sel_hi:[1,0,1]
	v_pk_fma_f32 v[162:163], v[12:13], v[146:147], v[50:51] op_sel_hi:[1,0,1]
	v_pk_fma_f32 v[164:165], v[14:15], v[146:147], v[52:53] op_sel_hi:[1,0,1]
	v_pk_fma_f32 v[166:167], v[16:17], v[146:147], v[54:55] op_sel_hi:[1,0,1]
	v_pk_fma_f32 v[174:175], v[24:25], v[146:147], v[138:139] op_sel_hi:[1,0,1]
	v_pk_fma_f32 v[176:177], v[26:27], v[146:147], v[140:141] op_sel_hi:[1,0,1]
	v_pk_fma_f32 v[178:179], v[28:29], v[146:147], v[142:143] op_sel_hi:[1,0,1]
	v_pk_fma_f32 v[180:181], v[30:31], v[146:147], v[144:145] op_sel_hi:[1,0,1]
	global_load_dwordx4 v[138:141], v[0:1], off
	global_load_dwordx2 v[142:143], v[0:1], off offset:16
	global_load_dwordx4 v[144:147], v[2:3], off
	v_mov_b32_e32 v0, s13
	v_mov_b32_e32 v1, s12
	v_cndmask_b32_e64 v0, v0, v1, s[0:1]
	v_mad_i64_i32 v[0:1], s[12:13], v0, s23, v[64:65]
	v_readlane_b32 s12, v108, 53
	v_readlane_b32 s13, v107, 53
	global_load_dwordx2 v[148:149], v[2:3], off offset:16
	global_load_dwordx4 v[50:53], v[0:1], off
	v_mov_b32_e32 v2, s13
	v_mov_b32_e32 v3, s12
	v_cndmask_b32_e64 v2, v2, v3, s[0:1]
	v_mad_i64_i32 v[2:3], s[12:13], v2, s23, v[64:65]
	v_readlane_b32 s12, v108, 54
	v_readlane_b32 s13, v107, 54
	global_load_dwordx2 v[54:55], v[0:1], off offset:16
	global_load_dwordx4 v[44:47], v[2:3], off
	v_mov_b32_e32 v0, s13
	v_mov_b32_e32 v1, s12
	v_cndmask_b32_e64 v0, v0, v1, s[0:1]
	v_mad_i64_i32 v[0:1], s[12:13], v0, s23, v[64:65]
	v_readlane_b32 s12, v108, 55
	v_readlane_b32 s13, v107, 55
	global_load_dwordx2 v[48:49], v[2:3], off offset:16
	global_load_dwordx4 v[38:41], v[0:1], off
	v_mov_b32_e32 v2, s13
	v_mov_b32_e32 v3, s12
	v_cndmask_b32_e64 v2, v2, v3, s[0:1]
	v_mad_i64_i32 v[2:3], s[12:13], v2, s23, v[64:65]
	global_load_dwordx2 v[36:37], v[2:3], off offset:16
	global_load_dwordx2 v[42:43], v[0:1], off offset:16
	global_load_dwordx4 v[32:35], v[2:3], off
	v_readlane_b32 s12, v106, 48
	v_readlane_b32 s13, v109, 48
	s_nop 0
	v_mov_b32_e32 v1, s12
	v_mov_b32_e32 v0, s13
	v_cndmask_b32_e64 v182, v0, v1, s[0:1]
	v_readlane_b32 s12, v106, 49
	v_readlane_b32 s13, v109, 49
	s_waitcnt vmcnt(14)
; DI void phase_peer_out(const Params& p, char* lds) {
;     ...
;       for (int k = 0; k < 8; ++k) {
;         const int e0 = __builtin_amdgcn_readlane(el[0], kb * 8 + k), e1 = __builtin_amdgcn_readlane(el[1], kb * 8 + k);
;         qb[k] = load6(V6 + (size_t)(hb ? e1 : e0) * 768);
;       }
; #pragma unroll
;       for (int k = 0; k < 8; ++k) {
;         const float c0 = __uint_as_float(__builtin_amdgcn_readlane(__float_as_uint(coefv[0]), kb * 8 + k)), c1 = __uint_as_float(__builtin_amdgcn_readlane(__float_as_uint(coefv[1]), kb * 8 + k));
;         const float cf = hb ? c1 : c0;
;         const f32x2 c2 = {cf, cf};
;         const v32f f = __builtin_amdgcn_cvt_scalef32_pk32_f32_fp6(qb[k], 1.0f);
; #pragma unroll
;         for (int i = 0; i < 16; ++i) o2[i] = f32x2{f[2 * i], f[2 * i + 1]} * c2 + o2[i];
	v_cvt_scalef32_pk32_f32_fp6 v[0:31], v[126:131], 1.0
	v_pk_fma_f32 v[126:127], v[0:1], v[182:183], v[150:151] op_sel_hi:[1,0,1]
	v_mov_b32_e32 v0, s13
	v_mov_b32_e32 v1, s12
	v_pk_fma_f32 v[128:129], v[2:3], v[182:183], v[152:153] op_sel_hi:[1,0,1]
	v_pk_fma_f32 v[130:131], v[4:5], v[182:183], v[154:155] op_sel_hi:[1,0,1]
	v_pk_fma_f32 v[150:151], v[6:7], v[182:183], v[156:157] op_sel_hi:[1,0,1]
	v_pk_fma_f32 v[152:153], v[8:9], v[182:183], v[158:159] op_sel_hi:[1,0,1]
	v_pk_fma_f32 v[154:155], v[10:11], v[182:183], v[160:161] op_sel_hi:[1,0,1]
	v_pk_fma_f32 v[156:157], v[12:13], v[182:183], v[162:163] op_sel_hi:[1,0,1]
	v_pk_fma_f32 v[158:159], v[14:15], v[182:183], v[164:165] op_sel_hi:[1,0,1]
	v_pk_fma_f32 v[160:161], v[16:17], v[182:183], v[166:167] op_sel_hi:[1,0,1]
	v_pk_fma_f32 v[162:163], v[18:19], v[182:183], v[168:169] op_sel_hi:[1,0,1]
	v_pk_fma_f32 v[164:165], v[20:21], v[182:183], v[170:171] op_sel_hi:[1,0,1]
	v_pk_fma_f32 v[166:167], v[22:23], v[182:183], v[172:173] op_sel_hi:[1,0,1]
	v_pk_fma_f32 v[168:169], v[24:25], v[182:183], v[174:175] op_sel_hi:[1,0,1]
	v_pk_fma_f32 v[170:171], v[26:27], v[182:183], v[176:177] op_sel_hi:[1,0,1]
	v_pk_fma_f32 v[172:173], v[28:29], v[182:183], v[178:179] op_sel_hi:[1,0,1]
	v_pk_fma_f32 v[174:175], v[30:31], v[182:183], v[180:181] op_sel_hi:[1,0,1]
	v_cndmask_b32_e64 v176, v0, v1, s[0:1]
	s_waitcnt vmcnt(12)
	v_cvt_scalef32_pk32_f32_fp6 v[0:31], v[132:137], 1.0
	v_readlane_b32 s12, v106, 50
	v_readlane_b32 s13, v109, 50
	v_pk_fma_f32 v[126:127], v[0:1], v[176:177], v[126:127] op_sel_hi:[1,0,1]
	v_mov_b32_e32 v1, s12
	v_mov_b32_e32 v0, s13
	v_pk_fma_f32 v[128:129], v[2:3], v[176:177], v[128:129] op_sel_hi:[1,0,1]
	v_pk_fma_f32 v[130:131], v[4:5], v[176:177], v[130:131] op_sel_hi:[1,0,1]
	v_pk_fma_f32 v[132:133], v[6:7], v[176:177], v[150:151] op_sel_hi:[1,0,1]
	v_pk_fma_f32 v[134:135], v[8:9], v[176:177], v[152:153] op_sel_hi:[1,0,1]
	v_pk_fma_f32 v[136:137], v[10:11], v[176:177], v[154:155] op_sel_hi:[1,0,1]
	v_pk_fma_f32 v[150:151], v[12:13], v[176:177], v[156:157] op_sel_hi:[1,0,1]
	v_pk_fma_f32 v[152:153], v[14:15], v[176:177], v[158:159] op_sel_hi:[1,0,1]
	v_pk_fma_f32 v[154:155], v[16:17], v[176:177], v[160:161] op_sel_hi:[1,0,1]
	v_pk_fma_f32 v[156:157], v[18:19], v[176:177], v[162:163] op_sel_hi:[1,0,1]
	v_pk_fma_f32 v[158:159], v[20:21], v[176:177], v[164:165] op_sel_hi:[1,0,1]
	v_pk_fma_f32 v[160:161], v[22:23], v[176:177], v[166:167] op_sel_hi:[1,0,1]
	v_pk_fma_f32 v[162:163], v[24:25], v[176:177], v[168:169] op_sel_hi:[1,0,1]
	v_pk_fma_f32 v[164:165], v[26:27], v[176:177], v[170:171] op_sel_hi:[1,0,1]
	v_pk_fma_f32 v[166:167], v[28:29], v[176:177], v[172:173] op_sel_hi:[1,0,1]
	v_pk_fma_f32 v[168:169], v[30:31], v[176:177], v[174:175] op_sel_hi:[1,0,1]
	v_cndmask_b32_e64 v170, v0, v1, s[0:1]
	s_waitcnt vmcnt(10)
	v_cvt_scalef32_pk32_f32_fp6 v[0:31], v[138:143], 1.0
	v_readlane_b32 s12, v106, 51
	v_readlane_b32 s13, v109, 51
	v_pk_fma_f32 v[126:127], v[0:1], v[170:171], v[126:127] op_sel_hi:[1,0,1]
	v_mov_b32_e32 v1, s12
	v_mov_b32_e32 v0, s13
	v_pk_fma_f32 v[128:129], v[2:3], v[170:171], v[128:129] op_sel_hi:[1,0,1]
	v_pk_fma_f32 v[130:131], v[4:5], v[170:171], v[130:131] op_sel_hi:[1,0,1]
	v_pk_fma_f32 v[132:133], v[6:7], v[170:171], v[132:133] op_sel_hi:[1,0,1]
	v_pk_fma_f32 v[134:135], v[8:9], v[170:171], v[134:135] op_sel_hi:[1,0,1]
	v_pk_fma_f32 v[136:137], v[10:11], v[170:171], v[136:137] op_sel_hi:[1,0,1]
	v_pk_fma_f32 v[138:139], v[12:13], v[170:171], v[150:151] op_sel_hi:[1,0,1]
	v_pk_fma_f32 v[140:141], v[14:15], v[170:171], v[152:153] op_sel_hi:[1,0,1]
	v_pk_fma_f32 v[142:143], v[16:17], v[170:171], v[154:155] op_sel_hi:[1,0,1]
	v_pk_fma_f32 v[150:151], v[18:19], v[170:171], v[156:157] op_sel_hi:[1,0,1]
	v_pk_fma_f32 v[152:153], v[20:21], v[170:171], v[158:159] op_sel_hi:[1,0,1]
	v_pk_fma_f32 v[154:155], v[22:23], v[170:171], v[160:161] op_sel_hi:[1,0,1]
	v_pk_fma_f32 v[156:157], v[24:25], v[170:171], v[162:163] op_sel_hi:[1,0,1]
	v_pk_fma_f32 v[158:159], v[26:27], v[170:171], v[164:165] op_sel_hi:[1,0,1]
	v_pk_fma_f32 v[160:161], v[28:29], v[170:171], v[166:167] op_sel_hi:[1,0,1]
	v_pk_fma_f32 v[162:163], v[30:31], v[170:171], v[168:169] op_sel_hi:[1,0,1]
	v_cndmask_b32_e64 v164, v0, v1, s[0:1]
	s_waitcnt vmcnt(8)
	v_cvt_scalef32_pk32_f32_fp6 v[0:31], v[144:149], 1.0
	v_readlane_b32 s12, v106, 52
	v_readlane_b32 s13, v109, 52
	v_pk_fma_f32 v[126:127], v[0:1], v[164:165], v[126:127] op_sel_hi:[1,0,1]
	v_mov_b32_e32 v1, s12
	v_mov_b32_e32 v0, s13
	v_pk_fma_f32 v[128:129], v[2:3], v[164:165], v[128:129] op_sel_hi:[1,0,1]
	v_pk_fma_f32 v[130:131], v[4:5], v[164:165], v[130:131] op_sel_hi:[1,0,1]
	v_pk_fma_f32 v[132:133], v[6:7], v[164:165], v[132:133] op_sel_hi:[1,0,1]
	v_pk_fma_f32 v[134:135], v[8:9], v[164:165], v[134:135] op_sel_hi:[1,0,1]
	v_pk_fma_f32 v[136:137], v[10:11], v[164:165], v[136:137] op_sel_hi:[1,0,1]
	v_pk_fma_f32 v[138:139], v[12:13], v[164:165], v[138:139] op_sel_hi:[1,0,1]
	v_pk_fma_f32 v[140:141], v[14:15], v[164:165], v[140:141] op_sel_hi:[1,0,1]
	v_pk_fma_f32 v[142:143], v[16:17], v[164:165], v[142:143] op_sel_hi:[1,0,1]
	v_pk_fma_f32 v[144:145], v[18:19], v[164:165], v[150:151] op_sel_hi:[1,0,1]
	v_pk_fma_f32 v[146:147], v[20:21], v[164:165], v[152:153] op_sel_hi:[1,0,1]
	v_pk_fma_f32 v[148:149], v[22:23], v[164:165], v[154:155] op_sel_hi:[1,0,1]
	v_pk_fma_f32 v[150:151], v[24:25], v[164:165], v[156:157] op_sel_hi:[1,0,1]
	v_pk_fma_f32 v[152:153], v[26:27], v[164:165], v[158:159] op_sel_hi:[1,0,1]
	v_pk_fma_f32 v[154:155], v[28:29], v[164:165], v[160:161] op_sel_hi:[1,0,1]
	v_pk_fma_f32 v[156:157], v[30:31], v[164:165], v[162:163] op_sel_hi:[1,0,1]
	v_cndmask_b32_e64 v158, v0, v1, s[0:1]
	s_waitcnt vmcnt(6)
; DI void phase_peer_out(const Params& p, char* lds) {
;     ...
;       for (int k = 0; k < 8; ++k) {
;         const int e0 = __builtin_amdgcn_readlane(el[0], kb * 8 + k), e1 = __builtin_amdgcn_readlane(el[1], kb * 8 + k);
;         qb[k] = load6(V6 + (size_t)(hb ? e1 : e0) * 768);
;       }
; #pragma unroll
;       for (int k = 0; k < 8; ++k) {
;         const float c0 = __uint_as_float(__builtin_amdgcn_readlane(__float_as_uint(coefv[0]), kb * 8 + k)), c1 = __uint_as_float(__builtin_amdgcn_readlane(__float_as_uint(coefv[1]), kb * 8 + k));
;         const float cf = hb ? c1 : c0;
;         const f32x2 c2 = {cf, cf};
;         const v32f f = __builtin_amdgcn_cvt_scalef32_pk32_f32_fp6(qb[k], 1.0f);
; #pragma unroll
;         for (int i = 0; i < 16; ++i) o2[i] = f32x2{f[2 * i], f[2 * i + 1]} * c2 + o2[i];
	v_cvt_scalef32_pk32_f32_fp6 v[0:31], v[50:55], 1.0
	v_readlane_b32 s12, v106, 53
	v_readlane_b32 s13, v109, 53
	v_pk_fma_f32 v[50:51], v[0:1], v[158:159], v[126:127] op_sel_hi:[1,0,1]
	v_mov_b32_e32 v1, s12
	v_mov_b32_e32 v0, s13
	v_pk_fma_f32 v[52:53], v[2:3], v[158:159], v[128:129] op_sel_hi:[1,0,1]
	v_pk_fma_f32 v[54:55], v[4:5], v[158:159], v[130:131] op_sel_hi:[1,0,1]
	v_pk_fma_f32 v[126:127], v[6:7], v[158:159], v[132:133] op_sel_hi:[1,0,1]
	v_pk_fma_f32 v[128:129], v[8:9], v[158:159], v[134:135] op_sel_hi:[1,0,1]
	v_pk_fma_f32 v[130:131], v[10:11], v[158:159], v[136:137] op_sel_hi:[1,0,1]
	v_pk_fma_f32 v[132:133], v[12:13], v[158:159], v[138:139] op_sel_hi:[1,0,1]
	v_pk_fma_f32 v[134:135], v[14:15], v[158:159], v[140:141] op_sel_hi:[1,0,1]
	v_pk_fma_f32 v[136:137], v[16:17], v[158:159], v[142:143] op_sel_hi:[1,0,1]
	v_pk_fma_f32 v[138:139], v[18:19], v[158:159], v[144:145] op_sel_hi:[1,0,1]
	v_pk_fma_f32 v[140:141], v[20:21], v[158:159], v[146:147] op_sel_hi:[1,0,1]
	v_pk_fma_f32 v[142:143], v[22:23], v[158:159], v[148:149] op_sel_hi:[1,0,1]
	v_pk_fma_f32 v[144:145], v[24:25], v[158:159], v[150:151] op_sel_hi:[1,0,1]
	v_pk_fma_f32 v[146:147], v[26:27], v[158:159], v[152:153] op_sel_hi:[1,0,1]
	v_pk_fma_f32 v[148:149], v[28:29], v[158:159], v[154:155] op_sel_hi:[1,0,1]
	v_pk_fma_f32 v[150:151], v[30:31], v[158:159], v[156:157] op_sel_hi:[1,0,1]
	v_cndmask_b32_e64 v152, v0, v1, s[0:1]
	s_waitcnt vmcnt(4)
	v_cvt_scalef32_pk32_f32_fp6 v[0:31], v[44:49], 1.0
	v_readlane_b32 s12, v106, 54
	v_readlane_b32 s13, v109, 54
	v_pk_fma_f32 v[44:45], v[0:1], v[152:153], v[50:51] op_sel_hi:[1,0,1]
	v_mov_b32_e32 v1, s12
	v_mov_b32_e32 v0, s13
	v_pk_fma_f32 v[46:47], v[2:3], v[152:153], v[52:53] op_sel_hi:[1,0,1]
	v_pk_fma_f32 v[48:49], v[4:5], v[152:153], v[54:55] op_sel_hi:[1,0,1]
	v_pk_fma_f32 v[50:51], v[6:7], v[152:153], v[126:127] op_sel_hi:[1,0,1]
	v_pk_fma_f32 v[52:53], v[8:9], v[152:153], v[128:129] op_sel_hi:[1,0,1]
	v_pk_fma_f32 v[54:55], v[10:11], v[152:153], v[130:131] op_sel_hi:[1,0,1]
	v_pk_fma_f32 v[126:127], v[12:13], v[152:153], v[132:133] op_sel_hi:[1,0,1]
	v_pk_fma_f32 v[128:129], v[14:15], v[152:153], v[134:135] op_sel_hi:[1,0,1]
	v_pk_fma_f32 v[130:131], v[16:17], v[152:153], v[136:137] op_sel_hi:[1,0,1]
	v_pk_fma_f32 v[132:133], v[18:19], v[152:153], v[138:139] op_sel_hi:[1,0,1]
	v_pk_fma_f32 v[134:135], v[20:21], v[152:153], v[140:141] op_sel_hi:[1,0,1]
	v_pk_fma_f32 v[136:137], v[22:23], v[152:153], v[142:143] op_sel_hi:[1,0,1]
	v_pk_fma_f32 v[138:139], v[24:25], v[152:153], v[144:145] op_sel_hi:[1,0,1]
	v_pk_fma_f32 v[140:141], v[26:27], v[152:153], v[146:147] op_sel_hi:[1,0,1]
	v_pk_fma_f32 v[142:143], v[28:29], v[152:153], v[148:149] op_sel_hi:[1,0,1]
	v_pk_fma_f32 v[144:145], v[30:31], v[152:153], v[150:151] op_sel_hi:[1,0,1]
	v_cndmask_b32_e64 v146, v0, v1, s[0:1]
	s_waitcnt vmcnt(1)
	v_cvt_scalef32_pk32_f32_fp6 v[0:31], v[38:43], 1.0
	v_readlane_b32 s12, v106, 55
	v_readlane_b32 s13, v109, 55
	v_pk_fma_f32 v[38:39], v[0:1], v[146:147], v[44:45] op_sel_hi:[1,0,1]
	v_mov_b32_e32 v1, s12
	v_mov_b32_e32 v0, s13
	v_readlane_b32 s12, v108, 56
	v_readlane_b32 s13, v107, 56
	v_pk_fma_f32 v[40:41], v[2:3], v[146:147], v[46:47] op_sel_hi:[1,0,1]
	v_pk_fma_f32 v[42:43], v[4:5], v[146:147], v[48:49] op_sel_hi:[1,0,1]
	v_pk_fma_f32 v[44:45], v[6:7], v[146:147], v[50:51] op_sel_hi:[1,0,1]
	v_pk_fma_f32 v[46:47], v[8:9], v[146:147], v[52:53] op_sel_hi:[1,0,1]
	v_pk_fma_f32 v[48:49], v[10:11], v[146:147], v[54:55] op_sel_hi:[1,0,1]
	v_pk_fma_f32 v[50:51], v[12:13], v[146:147], v[126:127] op_sel_hi:[1,0,1]
	v_pk_fma_f32 v[52:53], v[14:15], v[146:147], v[128:129] op_sel_hi:[1,0,1]
	v_pk_fma_f32 v[54:55], v[16:17], v[146:147], v[130:131] op_sel_hi:[1,0,1]
	v_pk_fma_f32 v[132:133], v[18:19], v[146:147], v[132:133] op_sel_hi:[1,0,1]
	v_pk_fma_f32 v[134:135], v[20:21], v[146:147], v[134:135] op_sel_hi:[1,0,1]
	v_pk_fma_f32 v[136:137], v[22:23], v[146:147], v[136:137] op_sel_hi:[1,0,1]
	v_pk_fma_f32 v[138:139], v[24:25], v[146:147], v[138:139] op_sel_hi:[1,0,1]
	v_pk_fma_f32 v[140:141], v[26:27], v[146:147], v[140:141] op_sel_hi:[1,0,1]
	v_pk_fma_f32 v[142:143], v[28:29], v[146:147], v[142:143] op_sel_hi:[1,0,1]
	v_pk_fma_f32 v[144:145], v[30:31], v[146:147], v[144:145] op_sel_hi:[1,0,1]
	v_cndmask_b32_e64 v146, v0, v1, s[0:1]
	v_mov_b32_e32 v0, s13
	v_mov_b32_e32 v1, s12
	v_cndmask_b32_e64 v0, v0, v1, s[0:1]
	v_mad_i64_i32 v[130:131], s[12:13], v0, s23, v[64:65]
	s_waitcnt vmcnt(0)
; DI void phase_peer_out(const Params& p, char* lds) {
;     ...
;     for (int kb = 0; kb < 8; ++kb) {
;       v6u qb[8];
; #pragma unroll
;       for (int k = 0; k < 8; ++k) {
;         const int e0 = __builtin_amdgcn_readlane(el[0], kb * 8 + k), e1 = __builtin_amdgcn_readlane(el[1], kb * 8 + k);
;         qb[k] = load6(V6 + (size_t)(hb ? e1 : e0) * 768);
;       }
; #pragma unroll
;       for (int k = 0; k < 8; ++k) {
;         const float c0 = __uint_as_float(__builtin_amdgcn_readlane(__float_as_uint(coefv[0]), kb * 8 + k)), c1 = __uint_as_float(__builtin_amdgcn_readlane(__float_as_uint(coefv[1]), kb * 8 + k));
;         const float cf = hb ? c1 : c0;
;         const f32x2 c2 = {cf, cf};
;         const v32f f = __builtin_amdgcn_cvt_scalef32_pk32_f32_fp6(qb[k], 1.0f);
; #pragma unroll
;         for (int i = 0; i < 16; ++i) o2[i] = f32x2{f[2 * i], f[2 * i + 1]} * c2 + o2[i];
	v_cvt_scalef32_pk32_f32_fp6 v[0:31], v[32:37], 1.0
	v_readlane_b32 s12, v108, 57
	v_readlane_b32 s13, v107, 57
	v_pk_fma_f32 v[150:151], v[0:1], v[146:147], v[38:39] op_sel_hi:[1,0,1]
	v_mov_b32_e32 v1, s12
	v_mov_b32_e32 v0, s13
	v_cndmask_b32_e64 v0, v0, v1, s[0:1]
	v_mad_i64_i32 v[0:1], s[12:13], v0, s23, v[64:65]
	v_readlane_b32 s12, v108, 58
	v_readlane_b32 s13, v107, 58
	global_load_dwordx4 v[126:129], v[130:131], off
	v_pk_fma_f32 v[168:169], v[18:19], v[146:147], v[132:133] op_sel_hi:[1,0,1]
	global_load_dwordx2 v[130:131], v[130:131], off offset:16
	v_pk_fma_f32 v[170:171], v[20:21], v[146:147], v[134:135] op_sel_hi:[1,0,1]
	v_pk_fma_f32 v[172:173], v[22:23], v[146:147], v[136:137] op_sel_hi:[1,0,1]
	global_load_dwordx2 v[136:137], v[0:1], off offset:16
	global_load_dwordx4 v[132:135], v[0:1], off
	v_mov_b32_e32 v0, s13
	v_mov_b32_e32 v1, s12
	v_cndmask_b32_e64 v0, v0, v1, s[0:1]
	v_mad_i64_i32 v[0:1], s[12:13], v0, s23, v[64:65]
	v_readlane_b32 s12, v108, 59
	v_readlane_b32 s13, v107, 59
	v_pk_fma_f32 v[152:153], v[2:3], v[146:147], v[40:41] op_sel_hi:[1,0,1]
	v_mov_b32_e32 v3, s12
	v_mov_b32_e32 v2, s13
	v_cndmask_b32_e64 v2, v2, v3, s[0:1]
	v_mad_i64_i32 v[2:3], s[12:13], v2, s23, v[64:65]
	v_readlane_b32 s12, v108, 60
	v_readlane_b32 s13, v107, 60
	v_pk_fma_f32 v[154:155], v[4:5], v[146:147], v[42:43] op_sel_hi:[1,0,1]
	v_pk_fma_f32 v[156:157], v[6:7], v[146:147], v[44:45] op_sel_hi:[1,0,1]
	v_pk_fma_f32 v[158:159], v[8:9], v[146:147], v[46:47] op_sel_hi:[1,0,1]
	v_pk_fma_f32 v[160:161], v[10:11], v[146:147], v[48:49] op_sel_hi:[1,0,1]
	v_pk_fma_f32 v[162:163], v[12:13], v[146:147], v[50:51] op_sel_hi:[1,0,1]
	v_pk_fma_f32 v[164:165], v[14:15], v[146:147], v[52:53] op_sel_hi:[1,0,1]
	v_pk_fma_f32 v[166:167], v[16:17], v[146:147], v[54:55] op_sel_hi:[1,0,1]
	v_pk_fma_f32 v[174:175], v[24:25], v[146:147], v[138:139] op_sel_hi:[1,0,1]
	v_pk_fma_f32 v[176:177], v[26:27], v[146:147], v[140:141] op_sel_hi:[1,0,1]
	v_pk_fma_f32 v[178:179], v[28:29], v[146:147], v[142:143] op_sel_hi:[1,0,1]
	v_pk_fma_f32 v[180:181], v[30:31], v[146:147], v[144:145] op_sel_hi:[1,0,1]
	global_load_dwordx4 v[138:141], v[0:1], off
	global_load_dwordx2 v[142:143], v[0:1], off offset:16
	global_load_dwordx4 v[144:147], v[2:3], off
	v_mov_b32_e32 v0, s13
	v_mov_b32_e32 v1, s12
	v_cndmask_b32_e64 v0, v0, v1, s[0:1]
	v_mad_i64_i32 v[0:1], s[12:13], v0, s23, v[64:65]
	v_readlane_b32 s12, v108, 61
	v_readlane_b32 s13, v107, 61
	global_load_dwordx2 v[148:149], v[2:3], off offset:16
	global_load_dwordx4 v[50:53], v[0:1], off
	v_mov_b32_e32 v2, s13
	v_mov_b32_e32 v3, s12
	v_cndmask_b32_e64 v2, v2, v3, s[0:1]
	v_mad_i64_i32 v[2:3], s[12:13], v2, s23, v[64:65]
	v_readlane_b32 s12, v108, 62
	v_readlane_b32 s13, v107, 62
	global_load_dwordx2 v[54:55], v[0:1], off offset:16
	global_load_dwordx4 v[44:47], v[2:3], off
	v_mov_b32_e32 v0, s13
	v_mov_b32_e32 v1, s12
	v_cndmask_b32_e64 v0, v0, v1, s[0:1]
	v_mad_i64_i32 v[0:1], s[12:13], v0, s23, v[64:65]
	v_readlane_b32 s12, v108, 63
	v_readlane_b32 s13, v107, 63
	global_load_dwordx2 v[48:49], v[2:3], off offset:16
	global_load_dwordx4 v[38:41], v[0:1], off
	v_mov_b32_e32 v2, s13
	v_mov_b32_e32 v3, s12
	v_cndmask_b32_e64 v2, v2, v3, s[0:1]
	v_mad_i64_i32 v[2:3], s[12:13], v2, s23, v[64:65]
	global_load_dwordx2 v[36:37], v[2:3], off offset:16
	global_load_dwordx2 v[42:43], v[0:1], off offset:16
	global_load_dwordx4 v[32:35], v[2:3], off
	v_readlane_b32 s12, v106, 56
	v_readlane_b32 s13, v109, 56
	s_nop 0
	v_mov_b32_e32 v1, s12
	v_mov_b32_e32 v0, s13
	v_cndmask_b32_e64 v108, v0, v1, s[0:1]
	v_readlane_b32 s12, v106, 57
	v_readlane_b32 s13, v109, 57
	s_waitcnt vmcnt(14)
	v_cvt_scalef32_pk32_f32_fp6 v[0:31], v[126:131], 1.0
	v_pk_fma_f32 v[126:127], v[0:1], v[108:109], v[150:151] op_sel_hi:[1,0,1]
	v_mov_b32_e32 v0, s13
	v_mov_b32_e32 v1, s12
	v_pk_fma_f32 v[128:129], v[2:3], v[108:109], v[152:153] op_sel_hi:[1,0,1]
	v_pk_fma_f32 v[130:131], v[4:5], v[108:109], v[154:155] op_sel_hi:[1,0,1]
	v_pk_fma_f32 v[150:151], v[6:7], v[108:109], v[156:157] op_sel_hi:[1,0,1]
	v_pk_fma_f32 v[152:153], v[8:9], v[108:109], v[158:159] op_sel_hi:[1,0,1]
	v_pk_fma_f32 v[154:155], v[10:11], v[108:109], v[160:161] op_sel_hi:[1,0,1]
	v_pk_fma_f32 v[156:157], v[12:13], v[108:109], v[162:163] op_sel_hi:[1,0,1]
	v_pk_fma_f32 v[158:159], v[14:15], v[108:109], v[164:165] op_sel_hi:[1,0,1]
	v_pk_fma_f32 v[160:161], v[16:17], v[108:109], v[166:167] op_sel_hi:[1,0,1]
	v_pk_fma_f32 v[162:163], v[18:19], v[108:109], v[168:169] op_sel_hi:[1,0,1]
	v_pk_fma_f32 v[164:165], v[20:21], v[108:109], v[170:171] op_sel_hi:[1,0,1]
	v_pk_fma_f32 v[166:167], v[22:23], v[108:109], v[172:173] op_sel_hi:[1,0,1]
	v_pk_fma_f32 v[168:169], v[24:25], v[108:109], v[174:175] op_sel_hi:[1,0,1]
	v_pk_fma_f32 v[170:171], v[26:27], v[108:109], v[176:177] op_sel_hi:[1,0,1]
	v_pk_fma_f32 v[172:173], v[28:29], v[108:109], v[178:179] op_sel_hi:[1,0,1]
	v_pk_fma_f32 v[174:175], v[30:31], v[108:109], v[180:181] op_sel_hi:[1,0,1]
	v_cndmask_b32_e64 v108, v0, v1, s[0:1]
	s_waitcnt vmcnt(12)
; DI void phase_peer_out(const Params& p, char* lds) {
;     ...
;     for (int kb = 0; kb < 8; ++kb) {
;       v6u qb[8];
; #pragma unroll
;       for (int k = 0; k < 8; ++k) {
;         const int e0 = __builtin_amdgcn_readlane(el[0], kb * 8 + k), e1 = __builtin_amdgcn_readlane(el[1], kb * 8 + k);
;         qb[k] = load6(V6 + (size_t)(hb ? e1 : e0) * 768);
;       }
; #pragma unroll
;       for (int k = 0; k < 8; ++k) {
;         const float c0 = __uint_as_float(__builtin_amdgcn_readlane(__float_as_uint(coefv[0]), kb * 8 + k)), c1 = __uint_as_float(__builtin_amdgcn_readlane(__float_as_uint(coefv[1]), kb * 8 + k));
;         const float cf = hb ? c1 : c0;
;         const f32x2 c2 = {cf, cf};
;         const v32f f = __builtin_amdgcn_cvt_scalef32_pk32_f32_fp6(qb[k], 1.0f);
; #pragma unroll
;         for (int i = 0; i < 16; ++i) o2[i] = f32x2{f[2 * i], f[2 * i + 1]} * c2 + o2[i];
;       }
	v_cvt_scalef32_pk32_f32_fp6 v[0:31], v[132:137], 1.0
	v_readlane_b32 s12, v106, 58
	v_readlane_b32 s13, v109, 58
	v_pk_fma_f32 v[126:127], v[0:1], v[108:109], v[126:127] op_sel_hi:[1,0,1]
	v_mov_b32_e32 v1, s12
	v_mov_b32_e32 v0, s13
	v_pk_fma_f32 v[128:129], v[2:3], v[108:109], v[128:129] op_sel_hi:[1,0,1]
	v_pk_fma_f32 v[130:131], v[4:5], v[108:109], v[130:131] op_sel_hi:[1,0,1]
	v_pk_fma_f32 v[132:133], v[6:7], v[108:109], v[150:151] op_sel_hi:[1,0,1]
	v_pk_fma_f32 v[134:135], v[8:9], v[108:109], v[152:153] op_sel_hi:[1,0,1]
	v_pk_fma_f32 v[136:137], v[10:11], v[108:109], v[154:155] op_sel_hi:[1,0,1]
	v_pk_fma_f32 v[150:151], v[12:13], v[108:109], v[156:157] op_sel_hi:[1,0,1]
	v_pk_fma_f32 v[152:153], v[14:15], v[108:109], v[158:159] op_sel_hi:[1,0,1]
	v_pk_fma_f32 v[154:155], v[16:17], v[108:109], v[160:161] op_sel_hi:[1,0,1]
	v_pk_fma_f32 v[156:157], v[18:19], v[108:109], v[162:163] op_sel_hi:[1,0,1]
	v_pk_fma_f32 v[158:159], v[20:21], v[108:109], v[164:165] op_sel_hi:[1,0,1]
	v_pk_fma_f32 v[160:161], v[22:23], v[108:109], v[166:167] op_sel_hi:[1,0,1]
	v_pk_fma_f32 v[162:163], v[24:25], v[108:109], v[168:169] op_sel_hi:[1,0,1]
	v_pk_fma_f32 v[164:165], v[26:27], v[108:109], v[170:171] op_sel_hi:[1,0,1]
	v_pk_fma_f32 v[166:167], v[28:29], v[108:109], v[172:173] op_sel_hi:[1,0,1]
	v_pk_fma_f32 v[168:169], v[30:31], v[108:109], v[174:175] op_sel_hi:[1,0,1]
	v_cndmask_b32_e64 v108, v0, v1, s[0:1]
	s_waitcnt vmcnt(10)
	v_cvt_scalef32_pk32_f32_fp6 v[0:31], v[138:143], 1.0
	v_readlane_b32 s12, v106, 59
	v_readlane_b32 s13, v109, 59
	v_pk_fma_f32 v[126:127], v[0:1], v[108:109], v[126:127] op_sel_hi:[1,0,1]
	v_mov_b32_e32 v1, s12
	v_mov_b32_e32 v0, s13
	v_pk_fma_f32 v[128:129], v[2:3], v[108:109], v[128:129] op_sel_hi:[1,0,1]
	v_pk_fma_f32 v[130:131], v[4:5], v[108:109], v[130:131] op_sel_hi:[1,0,1]
	v_pk_fma_f32 v[132:133], v[6:7], v[108:109], v[132:133] op_sel_hi:[1,0,1]
	v_pk_fma_f32 v[134:135], v[8:9], v[108:109], v[134:135] op_sel_hi:[1,0,1]
	v_pk_fma_f32 v[136:137], v[10:11], v[108:109], v[136:137] op_sel_hi:[1,0,1]
	v_pk_fma_f32 v[138:139], v[12:13], v[108:109], v[150:151] op_sel_hi:[1,0,1]
	v_pk_fma_f32 v[140:141], v[14:15], v[108:109], v[152:153] op_sel_hi:[1,0,1]
	v_pk_fma_f32 v[142:143], v[16:17], v[108:109], v[154:155] op_sel_hi:[1,0,1]
	v_pk_fma_f32 v[150:151], v[18:19], v[108:109], v[156:157] op_sel_hi:[1,0,1]
	v_pk_fma_f32 v[152:153], v[20:21], v[108:109], v[158:159] op_sel_hi:[1,0,1]
	v_pk_fma_f32 v[154:155], v[22:23], v[108:109], v[160:161] op_sel_hi:[1,0,1]
	v_pk_fma_f32 v[156:157], v[24:25], v[108:109], v[162:163] op_sel_hi:[1,0,1]
	v_pk_fma_f32 v[158:159], v[26:27], v[108:109], v[164:165] op_sel_hi:[1,0,1]
	v_pk_fma_f32 v[160:161], v[28:29], v[108:109], v[166:167] op_sel_hi:[1,0,1]
	v_pk_fma_f32 v[162:163], v[30:31], v[108:109], v[168:169] op_sel_hi:[1,0,1]
	v_cndmask_b32_e64 v108, v0, v1, s[0:1]
	s_waitcnt vmcnt(8)
	v_cvt_scalef32_pk32_f32_fp6 v[0:31], v[144:149], 1.0
	v_readlane_b32 s12, v106, 60
	v_readlane_b32 s13, v109, 60
	v_pk_fma_f32 v[126:127], v[0:1], v[108:109], v[126:127] op_sel_hi:[1,0,1]
	v_mov_b32_e32 v1, s12
	v_mov_b32_e32 v0, s13
	v_pk_fma_f32 v[128:129], v[2:3], v[108:109], v[128:129] op_sel_hi:[1,0,1]
	v_pk_fma_f32 v[130:131], v[4:5], v[108:109], v[130:131] op_sel_hi:[1,0,1]
	v_pk_fma_f32 v[132:133], v[6:7], v[108:109], v[132:133] op_sel_hi:[1,0,1]
	v_pk_fma_f32 v[134:135], v[8:9], v[108:109], v[134:135] op_sel_hi:[1,0,1]
	v_pk_fma_f32 v[136:137], v[10:11], v[108:109], v[136:137] op_sel_hi:[1,0,1]
	v_pk_fma_f32 v[138:139], v[12:13], v[108:109], v[138:139] op_sel_hi:[1,0,1]
	v_pk_fma_f32 v[140:141], v[14:15], v[108:109], v[140:141] op_sel_hi:[1,0,1]
	v_pk_fma_f32 v[142:143], v[16:17], v[108:109], v[142:143] op_sel_hi:[1,0,1]
	v_pk_fma_f32 v[144:145], v[18:19], v[108:109], v[150:151] op_sel_hi:[1,0,1]
	v_pk_fma_f32 v[146:147], v[20:21], v[108:109], v[152:153] op_sel_hi:[1,0,1]
	v_pk_fma_f32 v[148:149], v[22:23], v[108:109], v[154:155] op_sel_hi:[1,0,1]
	v_pk_fma_f32 v[150:151], v[24:25], v[108:109], v[156:157] op_sel_hi:[1,0,1]
	v_pk_fma_f32 v[152:153], v[26:27], v[108:109], v[158:159] op_sel_hi:[1,0,1]
	v_pk_fma_f32 v[154:155], v[28:29], v[108:109], v[160:161] op_sel_hi:[1,0,1]
	v_pk_fma_f32 v[156:157], v[30:31], v[108:109], v[162:163] op_sel_hi:[1,0,1]
	v_cndmask_b32_e64 v108, v0, v1, s[0:1]
	s_waitcnt vmcnt(6)
	v_cvt_scalef32_pk32_f32_fp6 v[0:31], v[50:55], 1.0
	v_readlane_b32 s12, v106, 61
	v_readlane_b32 s13, v109, 61
	v_pk_fma_f32 v[50:51], v[0:1], v[108:109], v[126:127] op_sel_hi:[1,0,1]
	v_mov_b32_e32 v1, s12
	v_mov_b32_e32 v0, s13
	v_pk_fma_f32 v[52:53], v[2:3], v[108:109], v[128:129] op_sel_hi:[1,0,1]
	v_pk_fma_f32 v[54:55], v[4:5], v[108:109], v[130:131] op_sel_hi:[1,0,1]
	v_pk_fma_f32 v[126:127], v[6:7], v[108:109], v[132:133] op_sel_hi:[1,0,1]
	v_pk_fma_f32 v[128:129], v[8:9], v[108:109], v[134:135] op_sel_hi:[1,0,1]
	v_pk_fma_f32 v[130:131], v[10:11], v[108:109], v[136:137] op_sel_hi:[1,0,1]
	v_pk_fma_f32 v[132:133], v[12:13], v[108:109], v[138:139] op_sel_hi:[1,0,1]
	v_pk_fma_f32 v[134:135], v[14:15], v[108:109], v[140:141] op_sel_hi:[1,0,1]
	v_pk_fma_f32 v[136:137], v[16:17], v[108:109], v[142:143] op_sel_hi:[1,0,1]
	v_pk_fma_f32 v[138:139], v[18:19], v[108:109], v[144:145] op_sel_hi:[1,0,1]
	v_pk_fma_f32 v[140:141], v[20:21], v[108:109], v[146:147] op_sel_hi:[1,0,1]
	v_pk_fma_f32 v[142:143], v[22:23], v[108:109], v[148:149] op_sel_hi:[1,0,1]
	v_pk_fma_f32 v[144:145], v[24:25], v[108:109], v[150:151] op_sel_hi:[1,0,1]
	v_pk_fma_f32 v[146:147], v[26:27], v[108:109], v[152:153] op_sel_hi:[1,0,1]
	v_pk_fma_f32 v[148:149], v[28:29], v[108:109], v[154:155] op_sel_hi:[1,0,1]
	v_pk_fma_f32 v[150:151], v[30:31], v[108:109], v[156:157] op_sel_hi:[1,0,1]
	v_cndmask_b32_e64 v108, v0, v1, s[0:1]
	s_waitcnt vmcnt(4)
; DI void phase_peer_out(const Params& p, char* lds) {
;     ...
;       for (int k = 0; k < 8; ++k) {
;         const float c0 = __uint_as_float(__builtin_amdgcn_readlane(__float_as_uint(coefv[0]), kb * 8 + k)), c1 = __uint_as_float(__builtin_amdgcn_readlane(__float_as_uint(coefv[1]), kb * 8 + k));
;         const float cf = hb ? c1 : c0;
;         const f32x2 c2 = {cf, cf};
;         const v32f f = __builtin_amdgcn_cvt_scalef32_pk32_f32_fp6(qb[k], 1.0f);
; #pragma unroll
;         for (int i = 0; i < 16; ++i) o2[i] = f32x2{f[2 * i], f[2 * i + 1]} * c2 + o2[i];
;       }
;     }
;     float s = 0.f;
; #pragma unroll
;     for (int i = 0; i < 16; ++i) {
;       o2[i].x += __shfl_xor(o2[i].x, 32); o2[i].y += __shfl_xor(o2[i].y, 32);
;       o2[i] = x2[i] * f32x2{ALPHA, ALPHA} + o2[i]; s += o2[i].x + o2[i].y;
	v_cvt_scalef32_pk32_f32_fp6 v[0:31], v[44:49], 1.0
	v_readlane_b32 s12, v106, 62
	v_readlane_b32 s13, v109, 62
	v_pk_fma_f32 v[44:45], v[0:1], v[108:109], v[50:51] op_sel_hi:[1,0,1]
	v_mov_b32_e32 v1, s12
	v_mov_b32_e32 v0, s13
	v_pk_fma_f32 v[46:47], v[2:3], v[108:109], v[52:53] op_sel_hi:[1,0,1]
	v_pk_fma_f32 v[48:49], v[4:5], v[108:109], v[54:55] op_sel_hi:[1,0,1]
	v_pk_fma_f32 v[50:51], v[6:7], v[108:109], v[126:127] op_sel_hi:[1,0,1]
	v_pk_fma_f32 v[52:53], v[8:9], v[108:109], v[128:129] op_sel_hi:[1,0,1]
	v_pk_fma_f32 v[54:55], v[10:11], v[108:109], v[130:131] op_sel_hi:[1,0,1]
	v_pk_fma_f32 v[126:127], v[12:13], v[108:109], v[132:133] op_sel_hi:[1,0,1]
	v_pk_fma_f32 v[128:129], v[14:15], v[108:109], v[134:135] op_sel_hi:[1,0,1]
	v_pk_fma_f32 v[130:131], v[16:17], v[108:109], v[136:137] op_sel_hi:[1,0,1]
	v_pk_fma_f32 v[132:133], v[18:19], v[108:109], v[138:139] op_sel_hi:[1,0,1]
	v_pk_fma_f32 v[134:135], v[20:21], v[108:109], v[140:141] op_sel_hi:[1,0,1]
	v_pk_fma_f32 v[136:137], v[22:23], v[108:109], v[142:143] op_sel_hi:[1,0,1]
	v_pk_fma_f32 v[138:139], v[24:25], v[108:109], v[144:145] op_sel_hi:[1,0,1]
	v_pk_fma_f32 v[140:141], v[26:27], v[108:109], v[146:147] op_sel_hi:[1,0,1]
	v_pk_fma_f32 v[142:143], v[28:29], v[108:109], v[148:149] op_sel_hi:[1,0,1]
	v_pk_fma_f32 v[144:145], v[30:31], v[108:109], v[150:151] op_sel_hi:[1,0,1]
	v_cndmask_b32_e64 v108, v0, v1, s[0:1]
	s_waitcnt vmcnt(1)
	v_cvt_scalef32_pk32_f32_fp6 v[0:31], v[38:43], 1.0
	v_readlane_b32 s12, v106, 63
	v_readlane_b32 s13, v109, 63
	v_pk_fma_f32 v[38:39], v[0:1], v[108:109], v[44:45] op_sel_hi:[1,0,1]
	v_mov_b32_e32 v1, s12
	v_mov_b32_e32 v0, s13
	v_pk_fma_f32 v[40:41], v[2:3], v[108:109], v[46:47] op_sel_hi:[1,0,1]
	v_pk_fma_f32 v[42:43], v[4:5], v[108:109], v[48:49] op_sel_hi:[1,0,1]
	v_pk_fma_f32 v[44:45], v[6:7], v[108:109], v[50:51] op_sel_hi:[1,0,1]
	v_pk_fma_f32 v[46:47], v[8:9], v[108:109], v[52:53] op_sel_hi:[1,0,1]
	v_pk_fma_f32 v[48:49], v[10:11], v[108:109], v[54:55] op_sel_hi:[1,0,1]
	v_pk_fma_f32 v[50:51], v[12:13], v[108:109], v[126:127] op_sel_hi:[1,0,1]
	v_pk_fma_f32 v[52:53], v[14:15], v[108:109], v[128:129] op_sel_hi:[1,0,1]
	v_pk_fma_f32 v[54:55], v[16:17], v[108:109], v[130:131] op_sel_hi:[1,0,1]
	v_pk_fma_f32 v[126:127], v[18:19], v[108:109], v[132:133] op_sel_hi:[1,0,1]
	v_pk_fma_f32 v[128:129], v[20:21], v[108:109], v[134:135] op_sel_hi:[1,0,1]
	v_pk_fma_f32 v[130:131], v[22:23], v[108:109], v[136:137] op_sel_hi:[1,0,1]
	v_pk_fma_f32 v[132:133], v[24:25], v[108:109], v[138:139] op_sel_hi:[1,0,1]
	v_pk_fma_f32 v[134:135], v[26:27], v[108:109], v[140:141] op_sel_hi:[1,0,1]
	v_pk_fma_f32 v[136:137], v[28:29], v[108:109], v[142:143] op_sel_hi:[1,0,1]
	v_pk_fma_f32 v[138:139], v[30:31], v[108:109], v[144:145] op_sel_hi:[1,0,1]
	v_cndmask_b32_e64 v106, v0, v1, s[0:1]
	s_waitcnt vmcnt(0)
	v_cvt_scalef32_pk32_f32_fp6 v[0:31], v[32:37], 1.0
	v_pk_fma_f32 v[0:1], v[0:1], v[106:107], v[38:39] op_sel_hi:[1,0,1]
	v_pk_fma_f32 v[32:33], v[8:9], v[106:107], v[46:47] op_sel_hi:[1,0,1]
	ds_bpermute_b32 v8, v113, v0
	ds_bpermute_b32 v9, v113, v1
	v_pk_fma_f32 v[2:3], v[2:3], v[106:107], v[40:41] op_sel_hi:[1,0,1]
	v_pk_fma_f32 v[34:35], v[10:11], v[106:107], v[48:49] op_sel_hi:[1,0,1]
	ds_bpermute_b32 v10, v113, v2
	ds_bpermute_b32 v11, v113, v3
	s_waitcnt lgkmcnt(2)
	v_pk_add_f32 v[0:1], v[0:1], v[8:9]
	v_pk_fma_f32 v[36:37], v[12:13], v[106:107], v[50:51] op_sel_hi:[1,0,1]
	v_pk_fma_f32 v[12:13], v[94:95], s[20:21], v[0:1] op_sel_hi:[1,0,1]
	v_pk_fma_f32 v[4:5], v[4:5], v[106:107], v[42:43] op_sel_hi:[1,0,1]
	v_add_f32_e32 v0, v12, v13
	v_add_f32_e32 v8, 0, v0
	s_waitcnt lgkmcnt(0)
	v_pk_add_f32 v[0:1], v[2:3], v[10:11]
	v_pk_fma_f32 v[38:39], v[14:15], v[106:107], v[52:53] op_sel_hi:[1,0,1]
	v_pk_fma_f32 v[14:15], v[92:93], s[20:21], v[0:1] op_sel_hi:[1,0,1]
	ds_bpermute_b32 v0, v113, v4
	ds_bpermute_b32 v1, v113, v5
	v_pk_fma_f32 v[6:7], v[6:7], v[106:107], v[44:45] op_sel_hi:[1,0,1]
	v_add_f32_e32 v2, v14, v15
	v_add_f32_e32 v10, v2, v8
	ds_bpermute_b32 v2, v113, v6
	ds_bpermute_b32 v3, v113, v7
	s_waitcnt lgkmcnt(2)
	v_pk_add_f32 v[0:1], v[4:5], v[0:1]
	v_pk_fma_f32 v[40:41], v[22:23], v[106:107], v[130:131] op_sel_hi:[1,0,1]
	v_pk_fma_f32 v[8:9], v[86:87], s[20:21], v[0:1] op_sel_hi:[1,0,1]
	v_pk_fma_f32 v[16:17], v[16:17], v[106:107], v[54:55] op_sel_hi:[1,0,1]
	v_add_f32_e32 v0, v8, v9
	v_add_f32_e32 v4, v0, v10
	s_waitcnt lgkmcnt(0)
	v_pk_add_f32 v[0:1], v[6:7], v[2:3]
	ds_bpermute_b32 v3, v113, v35
	v_pk_fma_f32 v[10:11], v[100:101], s[20:21], v[0:1] op_sel_hi:[1,0,1]
	ds_bpermute_b32 v0, v113, v32
	ds_bpermute_b32 v1, v113, v33
	v_add_f32_e32 v2, v10, v11
	v_add_f32_e32 v6, v2, v4
	ds_bpermute_b32 v2, v113, v34
	v_pk_fma_f32 v[42:43], v[26:27], v[106:107], v[134:135] op_sel_hi:[1,0,1]
	s_waitcnt lgkmcnt(1)
	v_pk_add_f32 v[0:1], v[32:33], v[0:1]
	v_pk_fma_f32 v[18:19], v[18:19], v[106:107], v[126:127] op_sel_hi:[1,0,1]
	v_pk_fma_f32 v[4:5], v[104:105], s[20:21], v[0:1] op_sel_hi:[1,0,1]
	v_pk_fma_f32 v[46:47], v[30:31], v[106:107], v[138:139] op_sel_hi:[1,0,1]
	v_add_f32_e32 v0, v4, v5
	v_add_f32_e32 v22, v0, v6
	s_waitcnt lgkmcnt(0)
	v_pk_add_f32 v[0:1], v[34:35], v[2:3]
	ds_bpermute_b32 v3, v113, v39
	v_pk_fma_f32 v[6:7], v[102:103], s[20:21], v[0:1] op_sel_hi:[1,0,1]
	ds_bpermute_b32 v0, v113, v36
	ds_bpermute_b32 v1, v113, v37
	v_add_f32_e32 v2, v6, v7
	v_add_f32_e32 v22, v2, v22
	ds_bpermute_b32 v2, v113, v38
	v_pk_fma_f32 v[44:45], v[28:29], v[106:107], v[136:137] op_sel_hi:[1,0,1]
	s_waitcnt lgkmcnt(1)
	v_pk_add_f32 v[0:1], v[36:37], v[0:1]
	v_pk_fma_f32 v[20:21], v[20:21], v[106:107], v[128:129] op_sel_hi:[1,0,1]
	v_pk_fma_f32 v[0:1], v[98:99], s[20:21], v[0:1] op_sel_hi:[1,0,1]
	s_waitcnt lgkmcnt(0)
; DI void phase_peer_out(const Params& p, char* lds) {
;     ...
;     float s = 0.f;
; #pragma unroll
;     for (int i = 0; i < 16; ++i) {
;       o2[i].x += __shfl_xor(o2[i].x, 32); o2[i].y += __shfl_xor(o2[i].y, 32);
;       o2[i] = x2[i] * f32x2{ALPHA, ALPHA} + o2[i]; s += o2[i].x + o2[i].y;
;     }
;     for (int o = 16; o; o >>= 1) s += __shfl_xor(s, o);
	v_pk_add_f32 v[2:3], v[38:39], v[2:3]
	v_add_f32_e32 v23, v0, v1
	v_add_f32_e32 v26, v22, v23
	ds_bpermute_b32 v22, v113, v16
	ds_bpermute_b32 v23, v113, v17
	v_pk_fma_f32 v[2:3], v[96:97], s[20:21], v[2:3] op_sel_hi:[1,0,1]
	v_pk_fma_f32 v[24:25], v[24:25], v[106:107], v[132:133] op_sel_hi:[1,0,1]
	v_add_f32_e32 v27, v2, v3
	v_add_f32_e32 v30, v26, v27
	ds_bpermute_b32 v26, v113, v18
	ds_bpermute_b32 v27, v113, v19
	s_waitcnt lgkmcnt(2)
	v_pk_add_f32 v[16:17], v[16:17], v[22:23]
	ds_bpermute_b32 v33, v113, v47
	v_pk_fma_f32 v[28:29], v[90:91], s[20:21], v[16:17] op_sel_hi:[1,0,1]
	s_nop 0
	v_add_f32_e32 v16, v28, v29
	v_add_f32_e32 v22, v30, v16
	s_waitcnt lgkmcnt(1)
	v_pk_add_f32 v[16:17], v[18:19], v[26:27]
	ds_bpermute_b32 v18, v113, v40
	v_pk_fma_f32 v[30:31], v[88:89], s[20:21], v[16:17] op_sel_hi:[1,0,1]
	ds_bpermute_b32 v16, v113, v20
	ds_bpermute_b32 v17, v113, v21
	ds_bpermute_b32 v19, v113, v41
	v_add_f32_e32 v23, v30, v31
	v_add_f32_e32 v32, v22, v23
	s_waitcnt lgkmcnt(1)
	v_pk_add_f32 v[16:17], v[20:21], v[16:17]
	s_nop 0
	v_pk_fma_f32 v[22:23], v[84:85], s[20:21], v[16:17] op_sel_hi:[1,0,1]
	s_waitcnt lgkmcnt(0)
	v_pk_add_f32 v[16:17], v[40:41], v[18:19]
	v_mov_b32_e32 v18, v23
	v_pk_fma_f32 v[26:27], v[82:83], s[20:21], v[16:17] op_sel_hi:[1,0,1]
	v_mov_b32_e32 v16, v22
	v_mov_b32_e32 v17, v26
	v_mov_b32_e32 v19, v27
	v_pk_add_f32 v[16:17], v[16:17], v[18:19]
	ds_bpermute_b32 v18, v113, v24
	ds_bpermute_b32 v19, v113, v25
	ds_bpermute_b32 v20, v113, v42
	ds_bpermute_b32 v21, v113, v43
	v_add_f32_e32 v16, v32, v16
	v_add_f32_e32 v34, v16, v17
	s_waitcnt lgkmcnt(2)
	v_pk_add_f32 v[16:17], v[24:25], v[18:19]
	ds_bpermute_b32 v32, v113, v46
	v_pk_fma_f32 v[18:19], v[78:79], s[20:21], v[16:17] op_sel_hi:[1,0,1]
	s_waitcnt lgkmcnt(1)
	v_pk_add_f32 v[16:17], v[42:43], v[20:21]
	v_mov_b32_e32 v20, v19
	v_pk_fma_f32 v[24:25], v[76:77], s[20:21], v[16:17] op_sel_hi:[1,0,1]
	v_mov_b32_e32 v16, v18
	v_mov_b32_e32 v17, v24
	v_mov_b32_e32 v21, v25
	v_pk_add_f32 v[16:17], v[16:17], v[20:21]
	ds_bpermute_b32 v20, v113, v44
	ds_bpermute_b32 v21, v113, v45
	v_add_f32_e32 v16, v34, v16
	v_add_f32_e32 v36, v16, v17
	v_mov_b32_e32 v43, v22
	s_waitcnt lgkmcnt(0)
	v_pk_add_f32 v[16:17], v[44:45], v[20:21]
	v_pk_add_f32 v[20:21], v[46:47], v[32:33]
	v_pk_fma_f32 v[16:17], v[74:75], s[20:21], v[16:17] op_sel_hi:[1,0,1]
	v_pk_fma_f32 v[20:21], v[80:81], s[20:21], v[20:21] op_sel_hi:[1,0,1]
	v_mov_b32_e32 v32, v16
	v_mov_b32_e32 v33, v20
	v_mov_b32_e32 v34, v17
	v_mov_b32_e32 v35, v21
	v_pk_add_f32 v[32:33], v[32:33], v[34:35]
	v_mov_b32_e32 v44, v27
	v_add_f32_e32 v32, v36, v32
	v_add_f32_e32 v32, v32, v33
	ds_bpermute_b32 v33, v118, v32
	v_mov_b32_e32 v45, v23
	s_waitcnt lgkmcnt(0)
	v_add_f32_e32 v32, v32, v33
	ds_bpermute_b32 v33, v114, v32
	s_waitcnt lgkmcnt(0)
	v_add_f32_e32 v32, v32, v33
	ds_bpermute_b32 v33, v115, v32
	s_waitcnt lgkmcnt(0)
	v_add_f32_e32 v32, v32, v33
	ds_bpermute_b32 v33, v116, v32
	s_waitcnt lgkmcnt(0)
	v_add_f32_e32 v32, v32, v33
	ds_bpermute_b32 v33, v117, v32
	s_waitcnt lgkmcnt(0)
; DI void phase_peer_out(const Params& p, char* lds) {
;     ...
;     const float mu = s * (1.f / 1024.f);
;     float q = 0.f;
; #pragma unroll
;     for (int i = 0; i < 16; ++i) { const float a = o2[i].x - mu, bq = o2[i].y - mu; q += a * a + bq * bq; }
;     for (int o = 16; o; o >>= 1) q += __shfl_xor(q, o);
;     const float rstd = rsqrtf(q * (1.f / 1024.f) + LN_EPS);
;     float* orow = p.out + (size_t)t * 1024 + 32 * l5 + 16 * hb;
; #pragma unroll
;     for (int q4 = 0; q4 < 4; ++q4) {
;       const float4 gg = *(const float4*)(g3 + 32 * l5 + 16 * hb + 4 * q4), bb = *(const float4*)(b3 + 32 * l5 + 16 * hb + 4 * q4);
;       const f32x2 a0 = hb ? o2[8 + 2 * q4] : o2[2 * q4], a1 = hb ? o2[8 + 2 * q4 + 1] : o2[2 * q4 + 1];
;       float4 o;
;       o.x = (a0.x - mu) * rstd * gg.x + bb.x; o.y = (a0.y - mu) * rstd * gg.y + bb.y;
;       o.z = (a1.x - mu) * rstd * gg.z + bb.z; o.w = (a1.y - mu) * rstd * gg.w + bb.w;
;       *(float4*)(orow + 4 * q4) = o;
;     }
	v_add_f32_e32 v33, v32, v33
	v_fmamk_f32 v35, v33, 0xba800000, v13
	v_fmamk_f32 v34, v33, 0xba800000, v12
	v_mul_f32_e32 v35, v35, v35
	v_fmamk_f32 v36, v33, 0xba800000, v15
	v_fmac_f32_e32 v35, v34, v34
	v_fmamk_f32 v34, v33, 0xba800000, v14
	v_mul_f32_e32 v36, v36, v36
	v_fmac_f32_e32 v36, v34, v34
	v_add_f32_e32 v34, v35, v36
	v_fmamk_f32 v36, v33, 0xba800000, v9
	v_fmamk_f32 v35, v33, 0xba800000, v8
	v_mul_f32_e32 v36, v36, v36
	v_fmac_f32_e32 v36, v35, v35
	v_add_f32_e32 v34, v36, v34
	v_fmamk_f32 v36, v33, 0xba800000, v11
	v_fmamk_f32 v35, v33, 0xba800000, v10
	v_mul_f32_e32 v36, v36, v36
	v_fmac_f32_e32 v36, v35, v35
	v_add_f32_e32 v34, v36, v34
	v_fmamk_f32 v36, v33, 0xba800000, v5
	v_fmamk_f32 v35, v33, 0xba800000, v4
	v_mul_f32_e32 v36, v36, v36
	v_fmac_f32_e32 v36, v35, v35
	v_add_f32_e32 v34, v36, v34
	v_fmamk_f32 v36, v33, 0xba800000, v7
	v_fmamk_f32 v35, v33, 0xba800000, v6
	v_mul_f32_e32 v36, v36, v36
	v_fmac_f32_e32 v36, v35, v35
	v_add_f32_e32 v34, v36, v34
	v_fmamk_f32 v36, v33, 0xba800000, v1
	v_fmamk_f32 v35, v33, 0xba800000, v0
	v_mul_f32_e32 v36, v36, v36
	v_fmac_f32_e32 v36, v35, v35
	v_add_f32_e32 v34, v36, v34
	v_fmamk_f32 v36, v33, 0xba800000, v3
	v_fmamk_f32 v35, v33, 0xba800000, v2
	v_mul_f32_e32 v36, v36, v36
	v_fmac_f32_e32 v36, v35, v35
	v_add_f32_e32 v34, v36, v34
	v_fmamk_f32 v36, v33, 0xba800000, v29
	v_fmamk_f32 v35, v33, 0xba800000, v28
	v_mul_f32_e32 v36, v36, v36
	v_fmac_f32_e32 v36, v35, v35
	v_mul_f32_e32 v32, 0x3a800000, v33
	v_add_f32_e32 v42, v36, v34
	v_fmamk_f32 v34, v33, 0xba800000, v30
	v_fmamk_f32 v33, v33, 0xba800000, v31
	v_mul_f32_e32 v33, v33, v33
	v_fmac_f32_e32 v33, v34, v34
	v_add_f32_e32 v33, v33, v42
	v_mov_b32_e32 v42, v26
	v_pk_add_f32 v[44:45], v[44:45], v[32:33] op_sel_hi:[1,0] neg_lo:[0,1] neg_hi:[0,1]
	v_pk_add_f32 v[42:43], v[42:43], v[32:33] op_sel_hi:[1,0] neg_lo:[0,1] neg_hi:[0,1]
	v_pk_mul_f32 v[44:45], v[44:45], v[44:45]
	v_cndmask_b32_e64 v13, v29, v13, s[0:1]
	v_pk_fma_f32 v[42:43], v[42:43], v[42:43], v[44:45]
	v_mov_b32_e32 v44, v25
	v_add_f32_e32 v33, v43, v33
	v_add_f32_e32 v33, v42, v33
	v_mov_b32_e32 v45, v19
	v_mov_b32_e32 v42, v24
	v_mov_b32_e32 v43, v18
	v_pk_add_f32 v[44:45], v[44:45], v[32:33] op_sel_hi:[1,0] neg_lo:[0,1] neg_hi:[0,1]
	v_pk_add_f32 v[42:43], v[42:43], v[32:33] op_sel_hi:[1,0] neg_lo:[0,1] neg_hi:[0,1]
	v_pk_mul_f32 v[44:45], v[44:45], v[44:45]
	v_cndmask_b32_e64 v12, v28, v12, s[0:1]
	v_pk_fma_f32 v[42:43], v[42:43], v[42:43], v[44:45]
	v_mov_b32_e32 v44, v21
	v_add_f32_e32 v33, v43, v33
	v_add_f32_e32 v33, v42, v33
	v_mov_b32_e32 v45, v17
	v_mov_b32_e32 v42, v20
	v_mov_b32_e32 v43, v16
	v_pk_add_f32 v[44:45], v[44:45], v[32:33] op_sel_hi:[1,0] neg_lo:[0,1] neg_hi:[0,1]
	v_pk_add_f32 v[42:43], v[42:43], v[32:33] op_sel_hi:[1,0] neg_lo:[0,1] neg_hi:[0,1]
	v_pk_mul_f32 v[44:45], v[44:45], v[44:45]
	v_cndmask_b32_e64 v15, v31, v15, s[0:1]
	v_pk_fma_f32 v[42:43], v[42:43], v[42:43], v[44:45]
	v_cndmask_b32_e64 v14, v30, v14, s[0:1]
	v_add_f32_e32 v33, v43, v33
	v_add_f32_e32 v33, v42, v33
	ds_bpermute_b32 v42, v118, v33
	v_lshlrev_b64 v[44:45], 12, v[60:61]
	v_lshl_add_u64 v[44:45], v[72:73], 0, v[44:45]
	v_cndmask_b32_e64 v9, v23, v9, s[0:1]
	v_cndmask_b32_e64 v8, v22, v8, s[0:1]
	s_waitcnt lgkmcnt(0)
	v_add_f32_e32 v33, v33, v42
	ds_bpermute_b32 v42, v114, v33
	v_cndmask_b32_e64 v11, v27, v11, s[0:1]
	v_cndmask_b32_e64 v10, v26, v10, s[0:1]
	v_cndmask_b32_e64 v5, v19, v5, s[0:1]
	v_cndmask_b32_e64 v4, v18, v4, s[0:1]
	s_waitcnt lgkmcnt(0)
	v_add_f32_e32 v33, v33, v42
	ds_bpermute_b32 v42, v115, v33
	v_cndmask_b32_e64 v7, v25, v7, s[0:1]
	v_cndmask_b32_e64 v6, v24, v6, s[0:1]
	v_cndmask_b32_e64 v1, v17, v1, s[0:1]
	v_cndmask_b32_e64 v0, v16, v0, s[0:1]
	s_waitcnt lgkmcnt(0)
	v_add_f32_e32 v33, v33, v42
	ds_bpermute_b32 v42, v116, v33
	v_cndmask_b32_e64 v3, v21, v3, s[0:1]
	v_cndmask_b32_e64 v2, v20, v2, s[0:1]
	v_add_u32_e32 v60, s53, v60
	s_waitcnt lgkmcnt(0)
	v_add_f32_e32 v33, v33, v42
	ds_bpermute_b32 v42, v117, v33
	s_waitcnt lgkmcnt(0)
	v_add_f32_e32 v33, v33, v42
	v_fmamk_f32 v33, v33, 0x3a800000, v123
	v_mul_f32_e32 v42, 0x4b800000, v33
	v_cmp_gt_f32_e64 s[12:13], s35, v33
	s_nop 1
	v_cndmask_b32_e64 v33, v33, v42, s[12:13]
	v_rsq_f32_e32 v33, v33
	s_nop 0
	v_mul_f32_e32 v42, 0x45800000, v33
	v_cndmask_b32_e64 v42, v33, v42, s[12:13]
	v_pk_add_f32 v[12:13], v[12:13], v[32:33] op_sel_hi:[1,0] neg_lo:[0,1] neg_hi:[0,1]
	v_pk_add_f32 v[14:15], v[14:15], v[32:33] op_sel_hi:[1,0] neg_lo:[0,1] neg_hi:[0,1]
	v_pk_mul_f32 v[12:13], v[12:13], v[42:43] op_sel_hi:[1,0]
	v_pk_mul_f32 v[14:15], v[14:15], v[42:43] op_sel_hi:[1,0]
	v_pk_add_f32 v[8:9], v[8:9], v[32:33] op_sel_hi:[1,0] neg_lo:[0,1] neg_hi:[0,1]
	v_pk_fma_f32 v[12:13], v[184:185], v[12:13], v[200:201]
	v_pk_fma_f32 v[14:15], v[186:187], v[14:15], v[202:203]
	global_store_dwordx4 v[44:45], v[12:15], off
	v_pk_add_f32 v[10:11], v[10:11], v[32:33] op_sel_hi:[1,0] neg_lo:[0,1] neg_hi:[0,1]
	v_pk_mul_f32 v[8:9], v[8:9], v[42:43] op_sel_hi:[1,0]
	v_pk_mul_f32 v[10:11], v[10:11], v[42:43] op_sel_hi:[1,0]
	v_pk_add_f32 v[4:5], v[4:5], v[32:33] op_sel_hi:[1,0] neg_lo:[0,1] neg_hi:[0,1]
	v_pk_add_f32 v[6:7], v[6:7], v[32:33] op_sel_hi:[1,0] neg_lo:[0,1] neg_hi:[0,1]
	v_pk_mul_f32 v[4:5], v[4:5], v[42:43] op_sel_hi:[1,0]
	v_pk_mul_f32 v[6:7], v[6:7], v[42:43] op_sel_hi:[1,0]
	v_pk_add_f32 v[0:1], v[0:1], v[32:33] op_sel_hi:[1,0] neg_lo:[0,1] neg_hi:[0,1]
	v_pk_add_f32 v[2:3], v[2:3], v[32:33] op_sel_hi:[1,0] neg_lo:[0,1] neg_hi:[0,1]
	v_pk_mul_f32 v[0:1], v[0:1], v[42:43] op_sel_hi:[1,0]
	v_pk_mul_f32 v[2:3], v[2:3], v[42:43] op_sel_hi:[1,0]
	v_cmp_lt_i32_e64 s[12:13], s36, v60
	s_or_b64 s[18:19], s[12:13], s[18:19]
	v_pk_fma_f32 v[8:9], v[188:189], v[8:9], v[204:205]
	v_pk_fma_f32 v[10:11], v[190:191], v[10:11], v[206:207]
	global_store_dwordx4 v[44:45], v[8:11], off offset:16
	v_pk_fma_f32 v[4:5], v[192:193], v[4:5], v[208:209]
	v_pk_fma_f32 v[6:7], v[194:195], v[6:7], v[210:211]
	global_store_dwordx4 v[44:45], v[4:7], off offset:32
	v_pk_fma_f32 v[0:1], v[0:1], v[196:197], v[212:213]
	v_pk_fma_f32 v[2:3], v[2:3], v[198:199], v[214:215]
	global_store_dwordx4 v[44:45], v[0:3], off offset:48
	s_andn2_b64 exec, exec, s[18:19]
	s_cbranch_execz .LBB0_1211
